# GEMM main loops without the per-MFMA-cluster s_setprio 1/0 flips
# baseline (speedup 1.0000x reference)
; #define PG8_STAGE(bufoff, gbase, voff) do { _Pragma("unroll") for (int _i = 0; _i < 2; ++_i) \
;         __builtin_amdgcn_global_load_lds((const unsigned*)((const char*)(gbase) + (voff)[_i]), (PG8_LAS unsigned*)(lds + (bufoff) + ldsw + _i * 8192), 16, 0, 0); } while (0)
; #define PG8_LDA(dst, b, h) do { _Pragma("unroll") for (int m = 0; m < 4; ++m) _Pragma("unroll") for (int k = 0; k < 2; ++k) dst[m][k] = *(const PG8_LAS bf16x8*)(lds + PG8_SA(b, h) + aoff + m * 2048 + k * 1024); } while (0)
; #define PG8_LDB(dst, b, h) do { _Pragma("unroll") for (int n = 0; n < 2; ++n) _Pragma("unroll") for (int k = 0; k < 2; ++k) dst[n][k] = *(const PG8_LAS bf16x8*)(lds + PG8_SB(b, h) + boff + n * 2048 + k * 1024); } while (0)
; #define PG8_MMA(ai, bj, At, Bt) do { __builtin_amdgcn_s_setprio(1); _Pragma("unroll") for (int m = 0; m < 4; ++m) _Pragma("unroll") for (int n = 0; n < 2; ++n) _Pragma("unroll") for (int k = 0; k < 2; ++k) \
;         acc[ai][bj][m][n] = __builtin_amdgcn_mfma_f32_16x16x32_bf16(Bt[n][k], At[m][k], acc[ai][bj][m][n], 0, 0, 0); __builtin_amdgcn_s_setprio(0); } while (0)
; #define PG8_WAIT_V(n) asm volatile("s_waitcnt vmcnt(" #n ")" ::: "memory")
; #define PG8_WAIT_L(n) asm volatile("s_waitcnt lgkmcnt(" #n ")" ::: "memory")
; #define PG8_BAR __builtin_amdgcn_s_barrier()
; #define PG8_SCHED __builtin_amdgcn_sched_barrier(0)
; template <class Epi, class Sched, bool ALIGN_EPI = false, bool SP2 = false>
; __device__ __forceinline__ void gemm_phase(PG8_LAS unsigned char* lds, const Gemm g, const Sched& S, const Epi& E) {
;     ...
;             PG8_LDB(B0, 0, 0); PG8_LDB(B1, 0, 1); PG8_SCHED; PG8_LDA(At, 0, 0); PG8_STAGE(PG8_SA(1, 1), a1 + hstep, voffA);
;             PG8_WAIT_V(8); PG8_WAIT_L(0); PG8_BAR; PG8_MMA(0, 0, At, B0); PG8_MMA(0, 1, At, B1); PG8_BAR; PG8_SCHED;
;             PG8_LDA(At, 0, 1); PG8_STAGE(PG8_SB(0, 0), b2, voffB); PG8_STAGE(PG8_SB(0, 1), b2 + hstep, voffB); PG8_STAGE(PG8_SA(0, 0), a2, voffA);
;             PG8_WAIT_V(8); PG8_WAIT_L(0); PG8_BAR; PG8_MMA(1, 0, At, B0); PG8_MMA(1, 1, At, B1); PG8_BAR; PG8_SCHED;
.LBB0_149:
	ds_read_b128 v[156:159], v153
	ds_read_b128 v[160:163], v153 offset:1024
	ds_read_b128 v[164:167], v153 offset:2048
	ds_read_b128 v[168:171], v153 offset:3072
	ds_read_b128 v[172:175], v154
	ds_read_b128 v[176:179], v154 offset:1024
	ds_read_b128 v[182:185], v154 offset:2048
	ds_read_b128 v[186:189], v154 offset:3072
	s_add_u32 s40, s26, 0xfffc0080
	s_addc_u32 s41, s27, -1
	s_cmp_eq_u32 s62, 12
	s_cselect_b32 s43, s17, s41
	s_cselect_b32 s42, s23, s40
	s_cselect_b32 s41, s15, s61
	s_cselect_b32 s40, s59, s60
	v_lshl_add_u64 v[144:145], s[26:27], 0, v[136:137]
	s_add_i32 m0, s25, 0xc000
	ds_read_b128 v[190:193], v155
	ds_read_b128 v[194:197], v155 offset:1024
	ds_read_b128 v[198:201], v155 offset:2048
	ds_read_b128 v[202:205], v155 offset:3072
	ds_read_b128 v[206:209], v155 offset:4096
	ds_read_b128 v[210:213], v155 offset:5120
	ds_read_b128 v[214:217], v155 offset:6144
	ds_read_b128 v[218:221], v155 offset:7168
	global_load_lds_dwordx4 v[144:145], off
	v_lshl_add_u64 v[144:145], s[26:27], 0, v[138:139]
	s_add_i32 m0, s25, 0xe000
	s_nop 0
	global_load_lds_dwordx4 v[144:145], off
	s_waitcnt vmcnt(8)
	s_waitcnt lgkmcnt(0)
	s_barrier
	s_waitcnt lgkmcnt(0)
	v_mfma_f32_16x16x32_bf16 v[124:127], v[156:159], v[190:193], v[124:127]
	v_mfma_f32_16x16x32_bf16 v[120:123], v[164:167], v[190:193], v[120:123]
	v_mfma_f32_16x16x32_bf16 v[108:111], v[156:159], v[198:201], v[108:111]
	v_mfma_f32_16x16x32_bf16 v[104:107], v[164:167], v[198:201], v[104:107]
	v_mfma_f32_16x16x32_bf16 v[92:95], v[156:159], v[206:209], v[92:95]
	v_mfma_f32_16x16x32_bf16 v[88:91], v[164:167], v[206:209], v[88:91]
	v_mfma_f32_16x16x32_bf16 v[76:79], v[156:159], v[214:217], v[76:79]
	v_mfma_f32_16x16x32_bf16 v[72:75], v[164:167], v[214:217], v[72:75]
	v_mfma_f32_16x16x32_bf16 v[124:127], v[160:163], v[194:197], v[124:127]
	v_mfma_f32_16x16x32_bf16 v[120:123], v[168:171], v[194:197], v[120:123]
	v_mfma_f32_16x16x32_bf16 v[108:111], v[160:163], v[202:205], v[108:111]
	v_mfma_f32_16x16x32_bf16 v[104:107], v[168:171], v[202:205], v[104:107]
	v_mfma_f32_16x16x32_bf16 v[92:95], v[160:163], v[210:213], v[92:95]
	v_mfma_f32_16x16x32_bf16 v[88:91], v[168:171], v[210:213], v[88:91]
	v_mfma_f32_16x16x32_bf16 v[76:79], v[160:163], v[218:221], v[76:79]
	v_mfma_f32_16x16x32_bf16 v[72:75], v[168:171], v[218:221], v[72:75]
	v_mfma_f32_16x16x32_bf16 v[116:119], v[172:175], v[190:193], v[116:119]
	v_mfma_f32_16x16x32_bf16 v[112:115], v[182:185], v[190:193], v[112:115]
	v_mfma_f32_16x16x32_bf16 v[100:103], v[172:175], v[198:201], v[100:103]
	v_mfma_f32_16x16x32_bf16 v[96:99], v[182:185], v[198:201], v[96:99]
	v_mfma_f32_16x16x32_bf16 v[84:87], v[172:175], v[206:209], v[84:87]
	v_mfma_f32_16x16x32_bf16 v[80:83], v[182:185], v[206:209], v[80:83]
	v_mfma_f32_16x16x32_bf16 v[68:71], v[172:175], v[214:217], v[68:71]
	v_mfma_f32_16x16x32_bf16 v[64:67], v[182:185], v[214:217], v[64:67]
	v_mfma_f32_16x16x32_bf16 v[116:119], v[176:179], v[194:197], v[116:119]
	v_mfma_f32_16x16x32_bf16 v[112:115], v[186:189], v[194:197], v[112:115]
	v_mfma_f32_16x16x32_bf16 v[100:103], v[176:179], v[202:205], v[100:103]
	v_mfma_f32_16x16x32_bf16 v[96:99], v[186:189], v[202:205], v[96:99]
	v_mfma_f32_16x16x32_bf16 v[84:87], v[176:179], v[210:213], v[84:87]
	v_mfma_f32_16x16x32_bf16 v[80:83], v[186:189], v[210:213], v[80:83]
	v_mfma_f32_16x16x32_bf16 v[68:71], v[176:179], v[218:221], v[68:71]
	v_mfma_f32_16x16x32_bf16 v[64:67], v[186:189], v[218:221], v[64:67]
	s_barrier
	s_add_i32 s63, s55, s45
	v_lshl_add_u64 v[144:145], s[40:41], 0, v[130:131]
	s_mov_b32 m0, s63
	ds_read_b128 v[190:193], v155 offset:16384
	ds_read_b128 v[194:197], v155 offset:17408
	ds_read_b128 v[198:201], v155 offset:18432
	ds_read_b128 v[202:205], v155 offset:19456
	ds_read_b128 v[206:209], v155 offset:20480
	ds_read_b128 v[210:213], v155 offset:21504
	ds_read_b128 v[214:217], v155 offset:22528
	ds_read_b128 v[218:221], v155 offset:23552
	global_load_lds_dwordx4 v[144:145], off
	s_add_i32 m0, s63, 0x2000
	s_add_u32 s64, s40, 0x40000
	v_lshl_add_u64 v[222:223], s[40:41], 0, v[134:135]
	s_addc_u32 s65, s41, 0
	s_add_i32 s63, s56, s45
	global_load_lds_dwordx4 v[222:223], off
	v_lshl_add_u64 v[224:225], s[64:65], 0, v[130:131]
	s_mov_b32 m0, s63
	v_lshl_add_u64 v[226:227], s[42:43], 0, v[132:133]
	global_load_lds_dwordx4 v[224:225], off
	v_lshl_add_u64 v[224:225], s[64:65], 0, v[134:135]
	s_add_i32 m0, s63, 0x2000
	s_nop 0
	global_load_lds_dwordx4 v[224:225], off
	v_lshl_add_u64 v[224:225], s[42:43], 0, v[128:129]
	s_mov_b32 m0, s25
	s_nop 0
	global_load_lds_dwordx4 v[224:225], off
	s_mov_b32 m0, s46
	s_nop 0
	global_load_lds_dwordx4 v[226:227], off
	s_waitcnt vmcnt(8)
	s_waitcnt lgkmcnt(0)
	s_barrier
; #define PG8_STAGE(bufoff, gbase, voff) do { _Pragma("unroll") for (int _i = 0; _i < 2; ++_i) \
;         __builtin_amdgcn_global_load_lds((const unsigned*)((const char*)(gbase) + (voff)[_i]), (PG8_LAS unsigned*)(lds + (bufoff) + ldsw + _i * 8192), 16, 0, 0); } while (0)
; #define PG8_LDA(dst, b, h) do { _Pragma("unroll") for (int m = 0; m < 4; ++m) _Pragma("unroll") for (int k = 0; k < 2; ++k) dst[m][k] = *(const PG8_LAS bf16x8*)(lds + PG8_SA(b, h) + aoff + m * 2048 + k * 1024); } while (0)
; #define PG8_LDB(dst, b, h) do { _Pragma("unroll") for (int n = 0; n < 2; ++n) _Pragma("unroll") for (int k = 0; k < 2; ++k) dst[n][k] = *(const PG8_LAS bf16x8*)(lds + PG8_SB(b, h) + boff + n * 2048 + k * 1024); } while (0)
; #define PG8_MMA(ai, bj, At, Bt) do { __builtin_amdgcn_s_setprio(1); _Pragma("unroll") for (int m = 0; m < 4; ++m) _Pragma("unroll") for (int n = 0; n < 2; ++n) _Pragma("unroll") for (int k = 0; k < 2; ++k) \
;         acc[ai][bj][m][n] = __builtin_amdgcn_mfma_f32_16x16x32_bf16(Bt[n][k], At[m][k], acc[ai][bj][m][n], 0, 0, 0); __builtin_amdgcn_s_setprio(0); } while (0)
; #define PG8_WAIT_V(n) asm volatile("s_waitcnt vmcnt(" #n ")" ::: "memory")
; #define PG8_WAIT_L(n) asm volatile("s_waitcnt lgkmcnt(" #n ")" ::: "memory")
; #define PG8_BAR __builtin_amdgcn_s_barrier()
; #define PG8_SCHED __builtin_amdgcn_sched_barrier(0)
; template <class Epi, class Sched, bool ALIGN_EPI = false, bool SP2 = false>
; __device__ __forceinline__ void gemm_phase(PG8_LAS unsigned char* lds, const Gemm g, const Sched& S, const Epi& E) {
;     ...
;             PG8_WAIT_V(8); PG8_WAIT_L(0); PG8_BAR; PG8_MMA(1, 0, At, B0); PG8_MMA(1, 1, At, B1); PG8_BAR; PG8_SCHED;
;             PG8_LDB(B0, 1, 0); PG8_LDB(B1, 1, 1); PG8_SCHED; PG8_LDA(At, 1, 0); PG8_STAGE(PG8_SA(0, 1), a2 + hstep, voffA);
;             PG8_WAIT_V(8); PG8_WAIT_L(0); PG8_BAR; PG8_MMA(0, 0, At, B0); PG8_MMA(0, 1, At, B1); PG8_BAR; PG8_SCHED;
	s_waitcnt lgkmcnt(0)
	v_mfma_f32_16x16x32_bf16 v[60:63], v[156:159], v[190:193], v[60:63]
	v_mfma_f32_16x16x32_bf16 v[56:59], v[164:167], v[190:193], v[56:59]
	v_mfma_f32_16x16x32_bf16 v[44:47], v[156:159], v[198:201], v[44:47]
	v_mfma_f32_16x16x32_bf16 v[40:43], v[164:167], v[198:201], v[40:43]
	v_mfma_f32_16x16x32_bf16 v[28:31], v[156:159], v[206:209], v[28:31]
	v_mfma_f32_16x16x32_bf16 v[24:27], v[164:167], v[206:209], v[24:27]
	v_mfma_f32_16x16x32_bf16 v[12:15], v[156:159], v[214:217], v[12:15]
	v_mfma_f32_16x16x32_bf16 v[8:11], v[164:167], v[214:217], v[8:11]
	v_mfma_f32_16x16x32_bf16 v[60:63], v[160:163], v[194:197], v[60:63]
	v_mfma_f32_16x16x32_bf16 v[56:59], v[168:171], v[194:197], v[56:59]
	v_mfma_f32_16x16x32_bf16 v[44:47], v[160:163], v[202:205], v[44:47]
	v_mfma_f32_16x16x32_bf16 v[40:43], v[168:171], v[202:205], v[40:43]
	v_mfma_f32_16x16x32_bf16 v[28:31], v[160:163], v[210:213], v[28:31]
	v_mfma_f32_16x16x32_bf16 v[24:27], v[168:171], v[210:213], v[24:27]
	v_mfma_f32_16x16x32_bf16 v[12:15], v[160:163], v[218:221], v[12:15]
	v_mfma_f32_16x16x32_bf16 v[8:11], v[168:171], v[218:221], v[8:11]
	v_mfma_f32_16x16x32_bf16 v[52:55], v[172:175], v[190:193], v[52:55]
	v_mfma_f32_16x16x32_bf16 v[48:51], v[182:185], v[190:193], v[48:51]
	v_mfma_f32_16x16x32_bf16 v[36:39], v[172:175], v[198:201], v[36:39]
	v_mfma_f32_16x16x32_bf16 v[32:35], v[182:185], v[198:201], v[32:35]
	v_mfma_f32_16x16x32_bf16 v[20:23], v[172:175], v[206:209], v[20:23]
	v_mfma_f32_16x16x32_bf16 v[16:19], v[182:185], v[206:209], v[16:19]
	v_mfma_f32_16x16x32_bf16 v[4:7], v[172:175], v[214:217], v[4:7]
	v_mfma_f32_16x16x32_bf16 v[0:3], v[182:185], v[214:217], v[0:3]
	v_mfma_f32_16x16x32_bf16 v[52:55], v[176:179], v[194:197], v[52:55]
	v_mfma_f32_16x16x32_bf16 v[48:51], v[186:189], v[194:197], v[48:51]
	v_mfma_f32_16x16x32_bf16 v[36:39], v[176:179], v[202:205], v[36:39]
	v_mfma_f32_16x16x32_bf16 v[32:35], v[186:189], v[202:205], v[32:35]
	v_mfma_f32_16x16x32_bf16 v[20:23], v[176:179], v[210:213], v[20:23]
	v_mfma_f32_16x16x32_bf16 v[16:19], v[186:189], v[210:213], v[16:19]
	v_mfma_f32_16x16x32_bf16 v[4:7], v[176:179], v[218:221], v[4:7]
	v_mfma_f32_16x16x32_bf16 v[0:3], v[186:189], v[218:221], v[0:3]
	s_barrier
	s_add_i32 s63, 0, 0x18000
	s_add_i32 s64, 0, 0x1c000
	v_add_u32_e32 v168, s63, v148
	v_add_u32_e32 v181, s64, v148
	ds_read_b128 v[156:159], v168
	ds_read_b128 v[160:163], v168 offset:1024
	ds_read_b128 v[164:167], v168 offset:2048
	ds_read_b128 v[168:171], v168 offset:3072
	ds_read_b128 v[172:175], v181
	ds_read_b128 v[176:179], v181 offset:1024
	ds_read_b128 v[182:185], v181 offset:2048
	ds_read_b128 v[186:189], v181 offset:3072
	s_add_u32 s42, s42, 0x40000
	s_addc_u32 s43, s43, 0
	s_mov_b32 m0, s47
	v_lshl_add_u64 v[228:229], s[42:43], 0, v[128:129]
	ds_read_b128 v[190:193], v155 offset:32768
	ds_read_b128 v[194:197], v155 offset:33792
	ds_read_b128 v[198:201], v155 offset:34816
	ds_read_b128 v[202:205], v155 offset:35840
	ds_read_b128 v[206:209], v155 offset:36864
	ds_read_b128 v[210:213], v155 offset:37888
	ds_read_b128 v[214:217], v155 offset:38912
	ds_read_b128 v[218:221], v155 offset:39936
	global_load_lds_dwordx4 v[228:229], off
	v_lshl_add_u64 v[228:229], s[42:43], 0, v[132:133]
	s_mov_b32 m0, s48
	s_nop 0
	global_load_lds_dwordx4 v[228:229], off
	s_waitcnt vmcnt(8)
	s_waitcnt lgkmcnt(0)
	s_barrier
	s_waitcnt lgkmcnt(0)
	v_mfma_f32_16x16x32_bf16 v[124:127], v[156:159], v[190:193], v[124:127]
	v_mfma_f32_16x16x32_bf16 v[120:123], v[164:167], v[190:193], v[120:123]
	v_mfma_f32_16x16x32_bf16 v[108:111], v[156:159], v[198:201], v[108:111]
	v_mfma_f32_16x16x32_bf16 v[104:107], v[164:167], v[198:201], v[104:107]
	v_mfma_f32_16x16x32_bf16 v[92:95], v[156:159], v[206:209], v[92:95]
	v_mfma_f32_16x16x32_bf16 v[88:91], v[164:167], v[206:209], v[88:91]
	v_mfma_f32_16x16x32_bf16 v[76:79], v[156:159], v[214:217], v[76:79]
	v_mfma_f32_16x16x32_bf16 v[72:75], v[164:167], v[214:217], v[72:75]
	v_mfma_f32_16x16x32_bf16 v[124:127], v[160:163], v[194:197], v[124:127]
	v_mfma_f32_16x16x32_bf16 v[120:123], v[168:171], v[194:197], v[120:123]
	v_mfma_f32_16x16x32_bf16 v[108:111], v[160:163], v[202:205], v[108:111]
	v_mfma_f32_16x16x32_bf16 v[104:107], v[168:171], v[202:205], v[104:107]
	v_mfma_f32_16x16x32_bf16 v[92:95], v[160:163], v[210:213], v[92:95]
	v_mfma_f32_16x16x32_bf16 v[88:91], v[168:171], v[210:213], v[88:91]
	v_mfma_f32_16x16x32_bf16 v[76:79], v[160:163], v[218:221], v[76:79]
	v_mfma_f32_16x16x32_bf16 v[72:75], v[168:171], v[218:221], v[72:75]
	v_mfma_f32_16x16x32_bf16 v[116:119], v[172:175], v[190:193], v[116:119]
	v_mfma_f32_16x16x32_bf16 v[112:115], v[182:185], v[190:193], v[112:115]
	v_mfma_f32_16x16x32_bf16 v[100:103], v[172:175], v[198:201], v[100:103]
	v_mfma_f32_16x16x32_bf16 v[96:99], v[182:185], v[198:201], v[96:99]
	v_mfma_f32_16x16x32_bf16 v[84:87], v[172:175], v[206:209], v[84:87]
	v_mfma_f32_16x16x32_bf16 v[80:83], v[182:185], v[206:209], v[80:83]
	v_mfma_f32_16x16x32_bf16 v[68:71], v[172:175], v[214:217], v[68:71]
	v_mfma_f32_16x16x32_bf16 v[64:67], v[182:185], v[214:217], v[64:67]
	v_mfma_f32_16x16x32_bf16 v[116:119], v[176:179], v[194:197], v[116:119]
	v_mfma_f32_16x16x32_bf16 v[112:115], v[186:189], v[194:197], v[112:115]
	v_mfma_f32_16x16x32_bf16 v[100:103], v[176:179], v[202:205], v[100:103]
	v_mfma_f32_16x16x32_bf16 v[96:99], v[186:189], v[202:205], v[96:99]
	v_mfma_f32_16x16x32_bf16 v[84:87], v[176:179], v[210:213], v[84:87]
	v_mfma_f32_16x16x32_bf16 v[80:83], v[186:189], v[210:213], v[80:83]
	v_mfma_f32_16x16x32_bf16 v[68:71], v[176:179], v[218:221], v[68:71]
	v_mfma_f32_16x16x32_bf16 v[64:67], v[186:189], v[218:221], v[64:67]
	s_barrier
; #define PG8_STAGE(bufoff, gbase, voff) do { _Pragma("unroll") for (int _i = 0; _i < 2; ++_i) \
;         __builtin_amdgcn_global_load_lds((const unsigned*)((const char*)(gbase) + (voff)[_i]), (PG8_LAS unsigned*)(lds + (bufoff) + ldsw + _i * 8192), 16, 0, 0); } while (0)
; #define PG8_LDA(dst, b, h) do { _Pragma("unroll") for (int m = 0; m < 4; ++m) _Pragma("unroll") for (int k = 0; k < 2; ++k) dst[m][k] = *(const PG8_LAS bf16x8*)(lds + PG8_SA(b, h) + aoff + m * 2048 + k * 1024); } while (0)
; #define PG8_MMA(ai, bj, At, Bt) do { __builtin_amdgcn_s_setprio(1); _Pragma("unroll") for (int m = 0; m < 4; ++m) _Pragma("unroll") for (int n = 0; n < 2; ++n) _Pragma("unroll") for (int k = 0; k < 2; ++k) \
;         acc[ai][bj][m][n] = __builtin_amdgcn_mfma_f32_16x16x32_bf16(Bt[n][k], At[m][k], acc[ai][bj][m][n], 0, 0, 0); __builtin_amdgcn_s_setprio(0); } while (0)
; #define PG8_WAIT_V(n) asm volatile("s_waitcnt vmcnt(" #n ")" ::: "memory")
; #define PG8_WAIT_L(n) asm volatile("s_waitcnt lgkmcnt(" #n ")" ::: "memory")
; #define PG8_BAR __builtin_amdgcn_s_barrier()
; #define PG8_SCHED __builtin_amdgcn_sched_barrier(0)
; template <class Epi, class Sched, bool ALIGN_EPI = false, bool SP2 = false>
; __device__ __forceinline__ void gemm_phase(PG8_LAS unsigned char* lds, const Gemm g, const Sched& S, const Epi& E) {
;     ...
;             PG8_LDA(At, 1, 1); PG8_STAGE(PG8_SB(1, 0), b3, voffB); PG8_STAGE(PG8_SB(1, 1), b3 + hstep, voffB); PG8_STAGE(PG8_SA(1, 0), a3, voffA);
;             PG8_WAIT_V(8); PG8_WAIT_L(0); PG8_BAR; PG8_MMA(1, 0, At, B0); PG8_MMA(1, 1, At, B1); PG8_BAR; PG8_SCHED;
	s_add_i32 s42, s63, s45
	v_lshl_add_u64 v[144:145], v[144:145], 0, s[10:11]
	s_mov_b32 m0, s42
	ds_read_b128 v[190:193], v155 offset:49152
	ds_read_b128 v[194:197], v155 offset:50176
	ds_read_b128 v[198:201], v155 offset:51200
	ds_read_b128 v[202:205], v155 offset:52224
	ds_read_b128 v[206:209], v155 offset:53248
	ds_read_b128 v[210:213], v155 offset:54272
	ds_read_b128 v[214:217], v155 offset:55296
	ds_read_b128 v[218:221], v155 offset:56320
	global_load_lds_dwordx4 v[144:145], off
	s_add_i32 m0, s42, 0x2000
	s_add_u32 s40, s40, 0x40080
	v_lshl_add_u64 v[144:145], v[222:223], 0, s[10:11]
	s_addc_u32 s41, s41, 0
	s_add_i32 s42, s64, s45
	global_load_lds_dwordx4 v[144:145], off
	v_lshl_add_u64 v[144:145], s[40:41], 0, v[130:131]
	s_mov_b32 m0, s42
	s_nop 0
	global_load_lds_dwordx4 v[144:145], off
	v_lshl_add_u64 v[144:145], s[40:41], 0, v[134:135]
	s_add_i32 m0, s42, 0x2000
	s_nop 0
	global_load_lds_dwordx4 v[144:145], off
	v_lshl_add_u64 v[144:145], v[224:225], 0, s[10:11]
	s_mov_b32 m0, s50
	s_nop 0
	global_load_lds_dwordx4 v[144:145], off
	v_lshl_add_u64 v[144:145], v[226:227], 0, s[10:11]
	s_mov_b32 m0, s51
	s_nop 0
	global_load_lds_dwordx4 v[144:145], off
	s_waitcnt vmcnt(8)
	s_waitcnt lgkmcnt(0)
	s_barrier
	s_waitcnt lgkmcnt(0)
	v_mfma_f32_16x16x32_bf16 v[60:63], v[156:159], v[190:193], v[60:63]
	v_mfma_f32_16x16x32_bf16 v[56:59], v[164:167], v[190:193], v[56:59]
	v_mfma_f32_16x16x32_bf16 v[44:47], v[156:159], v[198:201], v[44:47]
	v_mfma_f32_16x16x32_bf16 v[40:43], v[164:167], v[198:201], v[40:43]
	v_mfma_f32_16x16x32_bf16 v[28:31], v[156:159], v[206:209], v[28:31]
	v_mfma_f32_16x16x32_bf16 v[24:27], v[164:167], v[206:209], v[24:27]
	v_mfma_f32_16x16x32_bf16 v[12:15], v[156:159], v[214:217], v[12:15]
	v_mfma_f32_16x16x32_bf16 v[8:11], v[164:167], v[214:217], v[8:11]
	v_mfma_f32_16x16x32_bf16 v[60:63], v[160:163], v[194:197], v[60:63]
	v_mfma_f32_16x16x32_bf16 v[56:59], v[168:171], v[194:197], v[56:59]
	v_mfma_f32_16x16x32_bf16 v[44:47], v[160:163], v[202:205], v[44:47]
	v_mfma_f32_16x16x32_bf16 v[40:43], v[168:171], v[202:205], v[40:43]
	v_mfma_f32_16x16x32_bf16 v[28:31], v[160:163], v[210:213], v[28:31]
	v_mfma_f32_16x16x32_bf16 v[24:27], v[168:171], v[210:213], v[24:27]
	v_mfma_f32_16x16x32_bf16 v[12:15], v[160:163], v[218:221], v[12:15]
	v_mfma_f32_16x16x32_bf16 v[8:11], v[168:171], v[218:221], v[8:11]
	v_mfma_f32_16x16x32_bf16 v[52:55], v[172:175], v[190:193], v[52:55]
	v_mfma_f32_16x16x32_bf16 v[48:51], v[182:185], v[190:193], v[48:51]
	v_mfma_f32_16x16x32_bf16 v[36:39], v[172:175], v[198:201], v[36:39]
	v_mfma_f32_16x16x32_bf16 v[32:35], v[182:185], v[198:201], v[32:35]
	v_mfma_f32_16x16x32_bf16 v[20:23], v[172:175], v[206:209], v[20:23]
	v_mfma_f32_16x16x32_bf16 v[16:19], v[182:185], v[206:209], v[16:19]
	v_mfma_f32_16x16x32_bf16 v[4:7], v[172:175], v[214:217], v[4:7]
	v_mfma_f32_16x16x32_bf16 v[0:3], v[182:185], v[214:217], v[0:3]
	v_mfma_f32_16x16x32_bf16 v[52:55], v[176:179], v[194:197], v[52:55]
	v_mfma_f32_16x16x32_bf16 v[48:51], v[186:189], v[194:197], v[48:51]
	v_mfma_f32_16x16x32_bf16 v[36:39], v[176:179], v[202:205], v[36:39]
	v_mfma_f32_16x16x32_bf16 v[32:35], v[186:189], v[202:205], v[32:35]
	v_mfma_f32_16x16x32_bf16 v[20:23], v[176:179], v[210:213], v[20:23]
	v_mfma_f32_16x16x32_bf16 v[16:19], v[186:189], v[210:213], v[16:19]
	v_mfma_f32_16x16x32_bf16 v[4:7], v[176:179], v[218:221], v[4:7]
	v_mfma_f32_16x16x32_bf16 v[0:3], v[186:189], v[218:221], v[0:3]
	s_barrier
	s_add_i32 s62, s62, 2
	s_add_u32 s26, s26, 0x100
	s_addc_u32 s27, s27, 0
	s_add_u32 s60, s60, 0x100
	s_addc_u32 s61, s61, 0
	s_cmp_gt_u32 s62, 13
	s_cbranch_scc0 .LBB0_149
	s_and_b64 vcc, exec, s[12:13]
	s_cbranch_vccz .LBB0_152
	s_barrier

; #define PG8_STAGE(bufoff, gbase, voff) do { _Pragma("unroll") for (int _i = 0; _i < 2; ++_i) \
;         __builtin_amdgcn_global_load_lds((const unsigned*)((const char*)(gbase) + (voff)[_i]), (PG8_LAS unsigned*)(lds + (bufoff) + ldsw + _i * 8192), 16, 0, 0); } while (0)
; #define PG8_LDA(dst, b, h) do { _Pragma("unroll") for (int m = 0; m < 4; ++m) _Pragma("unroll") for (int k = 0; k < 2; ++k) dst[m][k] = *(const PG8_LAS bf16x8*)(lds + PG8_SA(b, h) + aoff + m * 2048 + k * 1024); } while (0)
; #define PG8_LDB(dst, b, h) do { _Pragma("unroll") for (int n = 0; n < 2; ++n) _Pragma("unroll") for (int k = 0; k < 2; ++k) dst[n][k] = *(const PG8_LAS bf16x8*)(lds + PG8_SB(b, h) + boff + n * 2048 + k * 1024); } while (0)
; #define PG8_MMA(ai, bj, At, Bt) do { __builtin_amdgcn_s_setprio(1); _Pragma("unroll") for (int m = 0; m < 4; ++m) _Pragma("unroll") for (int n = 0; n < 2; ++n) _Pragma("unroll") for (int k = 0; k < 2; ++k) \
;         acc[ai][bj][m][n] = __builtin_amdgcn_mfma_f32_16x16x32_bf16(Bt[n][k], At[m][k], acc[ai][bj][m][n], 0, 0, 0); __builtin_amdgcn_s_setprio(0); } while (0)
; #define PG8_WAIT_V(n) asm volatile("s_waitcnt vmcnt(" #n ")" ::: "memory")
; #define PG8_WAIT_L(n) asm volatile("s_waitcnt lgkmcnt(" #n ")" ::: "memory")
; #define PG8_BAR __builtin_amdgcn_s_barrier()
; #define PG8_SCHED __builtin_amdgcn_sched_barrier(0)
; template <class Epi, class Sched, bool ALIGN_EPI = false, bool SP2 = false>
; __device__ __forceinline__ void gemm_phase(PG8_LAS unsigned char* lds, const Gemm g, const Sched& S, const Epi& E) {
;     ...
;             PG8_LDB(B0, 0, 0); PG8_LDB(B1, 0, 1); PG8_SCHED; PG8_LDA(At, 0, 0); PG8_STAGE(PG8_SA(1, 1), a1 + hstep, voffA);
;             PG8_WAIT_V(8); PG8_WAIT_L(0); PG8_BAR; PG8_MMA(0, 0, At, B0); PG8_MMA(0, 1, At, B1); PG8_BAR; PG8_SCHED;
;             PG8_LDA(At, 0, 1); PG8_STAGE(PG8_SB(0, 0), b2, voffB); PG8_STAGE(PG8_SB(0, 1), b2 + hstep, voffB); PG8_STAGE(PG8_SA(0, 0), a2, voffA);
;             PG8_WAIT_V(8); PG8_WAIT_L(0); PG8_BAR; PG8_MMA(1, 0, At, B0); PG8_MMA(1, 1, At, B1); PG8_BAR; PG8_SCHED;
.LBB0_306:
	ds_read_b128 v[140:143], v151
	ds_read_b128 v[154:157], v151 offset:1024
	ds_read_b128 v[158:161], v151 offset:2048
	ds_read_b128 v[162:165], v151 offset:3072
	ds_read_b128 v[166:169], v152
	ds_read_b128 v[170:173], v152 offset:1024
	ds_read_b128 v[174:177], v152 offset:2048
	ds_read_b128 v[182:185], v152 offset:3072
	s_add_u32 s20, s18, 0xfff50080
	s_addc_u32 s21, s19, -1
	s_cmp_eq_u32 s57, 40
	s_cselect_b32 s23, s5, s21
	s_cselect_b32 s22, s4, s20
	s_cselect_b32 s21, s17, s56
	s_cselect_b32 s20, s16, s55
	v_lshl_add_u64 v[178:179], s[18:19], 0, v[132:133]
	s_add_i32 m0, s34, 0xc000
	ds_read_b128 v[186:189], v153
	ds_read_b128 v[190:193], v153 offset:1024
	ds_read_b128 v[194:197], v153 offset:2048
	ds_read_b128 v[198:201], v153 offset:3072
	ds_read_b128 v[202:205], v153 offset:4096
	ds_read_b128 v[206:209], v153 offset:5120
	ds_read_b128 v[210:213], v153 offset:6144
	ds_read_b128 v[214:217], v153 offset:7168
	global_load_lds_dwordx4 v[178:179], off
	v_lshl_add_u64 v[178:179], s[18:19], 0, v[134:135]
	s_add_i32 m0, s34, 0xe000
	s_nop 0
	global_load_lds_dwordx4 v[178:179], off
	s_waitcnt vmcnt(8)
	s_waitcnt lgkmcnt(0)
	s_barrier
	s_waitcnt lgkmcnt(0)
	v_mfma_f32_16x16x32_bf16 v[124:127], v[140:143], v[186:189], v[124:127]
	v_mfma_f32_16x16x32_bf16 v[120:123], v[158:161], v[186:189], v[120:123]
	v_mfma_f32_16x16x32_bf16 v[116:119], v[140:143], v[194:197], v[116:119]
	v_mfma_f32_16x16x32_bf16 v[112:115], v[158:161], v[194:197], v[112:115]
	v_mfma_f32_16x16x32_bf16 v[100:103], v[140:143], v[202:205], v[100:103]
	v_mfma_f32_16x16x32_bf16 v[96:99], v[158:161], v[202:205], v[96:99]
	v_mfma_f32_16x16x32_bf16 v[84:87], v[140:143], v[210:213], v[84:87]
	v_mfma_f32_16x16x32_bf16 v[80:83], v[158:161], v[210:213], v[80:83]
	v_mfma_f32_16x16x32_bf16 v[124:127], v[154:157], v[190:193], v[124:127]
	v_mfma_f32_16x16x32_bf16 v[120:123], v[162:165], v[190:193], v[120:123]
	v_mfma_f32_16x16x32_bf16 v[116:119], v[154:157], v[198:201], v[116:119]
	v_mfma_f32_16x16x32_bf16 v[112:115], v[162:165], v[198:201], v[112:115]
	v_mfma_f32_16x16x32_bf16 v[100:103], v[154:157], v[206:209], v[100:103]
	v_mfma_f32_16x16x32_bf16 v[96:99], v[162:165], v[206:209], v[96:99]
	v_mfma_f32_16x16x32_bf16 v[84:87], v[154:157], v[214:217], v[84:87]
	v_mfma_f32_16x16x32_bf16 v[80:83], v[162:165], v[214:217], v[80:83]
	v_mfma_f32_16x16x32_bf16 v[108:111], v[166:169], v[186:189], v[108:111]
	v_mfma_f32_16x16x32_bf16 v[104:107], v[174:177], v[186:189], v[104:107]
	v_mfma_f32_16x16x32_bf16 v[92:95], v[166:169], v[194:197], v[92:95]
	v_mfma_f32_16x16x32_bf16 v[88:91], v[174:177], v[194:197], v[88:91]
	v_mfma_f32_16x16x32_bf16 v[76:79], v[166:169], v[202:205], v[76:79]
	v_mfma_f32_16x16x32_bf16 v[72:75], v[174:177], v[202:205], v[72:75]
	v_mfma_f32_16x16x32_bf16 v[68:71], v[166:169], v[210:213], v[68:71]
	v_mfma_f32_16x16x32_bf16 v[64:67], v[174:177], v[210:213], v[64:67]
	v_mfma_f32_16x16x32_bf16 v[108:111], v[170:173], v[190:193], v[108:111]
	v_mfma_f32_16x16x32_bf16 v[104:107], v[182:185], v[190:193], v[104:107]
	v_mfma_f32_16x16x32_bf16 v[92:95], v[170:173], v[198:201], v[92:95]
	v_mfma_f32_16x16x32_bf16 v[88:91], v[182:185], v[198:201], v[88:91]
	v_mfma_f32_16x16x32_bf16 v[76:79], v[170:173], v[206:209], v[76:79]
	v_mfma_f32_16x16x32_bf16 v[72:75], v[182:185], v[206:209], v[72:75]
	v_mfma_f32_16x16x32_bf16 v[68:71], v[170:173], v[214:217], v[68:71]
	v_mfma_f32_16x16x32_bf16 v[64:67], v[182:185], v[214:217], v[64:67]
	s_barrier
	s_add_i32 s58, s48, s33
	v_lshl_add_u64 v[178:179], s[20:21], 0, v[128:129]
	s_mov_b32 m0, s58
	ds_read_b128 v[186:189], v153 offset:16384
	ds_read_b128 v[190:193], v153 offset:17408
	ds_read_b128 v[194:197], v153 offset:18432
	ds_read_b128 v[198:201], v153 offset:19456
	ds_read_b128 v[202:205], v153 offset:20480
	ds_read_b128 v[206:209], v153 offset:21504
	ds_read_b128 v[210:213], v153 offset:22528
	ds_read_b128 v[214:217], v153 offset:23552
	global_load_lds_dwordx4 v[178:179], off
	s_add_i32 m0, s58, 0x2000
	s_add_u32 s58, s20, 0xb0000
	v_lshl_add_u64 v[218:219], s[20:21], 0, v[130:131]
	s_addc_u32 s59, s21, 0
	s_add_i32 s60, s50, s33
	global_load_lds_dwordx4 v[218:219], off
	v_lshl_add_u64 v[220:221], s[58:59], 0, v[128:129]
	s_mov_b32 m0, s60
	v_lshl_add_u64 v[222:223], s[22:23], 0, v[130:131]
	global_load_lds_dwordx4 v[220:221], off
	v_lshl_add_u64 v[220:221], s[58:59], 0, v[130:131]
	s_add_i32 m0, s60, 0x2000
	s_nop 0
	global_load_lds_dwordx4 v[220:221], off
	v_lshl_add_u64 v[220:221], s[22:23], 0, v[128:129]
	s_mov_b32 m0, s34
	s_nop 0
	global_load_lds_dwordx4 v[220:221], off
	s_mov_b32 m0, s35
	s_nop 0
	global_load_lds_dwordx4 v[222:223], off
	s_waitcnt vmcnt(8)
	s_waitcnt lgkmcnt(0)
	s_barrier
; #define PG8_STAGE(bufoff, gbase, voff) do { _Pragma("unroll") for (int _i = 0; _i < 2; ++_i) \
;         __builtin_amdgcn_global_load_lds((const unsigned*)((const char*)(gbase) + (voff)[_i]), (PG8_LAS unsigned*)(lds + (bufoff) + ldsw + _i * 8192), 16, 0, 0); } while (0)
; #define PG8_LDA(dst, b, h) do { _Pragma("unroll") for (int m = 0; m < 4; ++m) _Pragma("unroll") for (int k = 0; k < 2; ++k) dst[m][k] = *(const PG8_LAS bf16x8*)(lds + PG8_SA(b, h) + aoff + m * 2048 + k * 1024); } while (0)
; #define PG8_LDB(dst, b, h) do { _Pragma("unroll") for (int n = 0; n < 2; ++n) _Pragma("unroll") for (int k = 0; k < 2; ++k) dst[n][k] = *(const PG8_LAS bf16x8*)(lds + PG8_SB(b, h) + boff + n * 2048 + k * 1024); } while (0)
; #define PG8_MMA(ai, bj, At, Bt) do { __builtin_amdgcn_s_setprio(1); _Pragma("unroll") for (int m = 0; m < 4; ++m) _Pragma("unroll") for (int n = 0; n < 2; ++n) _Pragma("unroll") for (int k = 0; k < 2; ++k) \
;         acc[ai][bj][m][n] = __builtin_amdgcn_mfma_f32_16x16x32_bf16(Bt[n][k], At[m][k], acc[ai][bj][m][n], 0, 0, 0); __builtin_amdgcn_s_setprio(0); } while (0)
; #define PG8_WAIT_V(n) asm volatile("s_waitcnt vmcnt(" #n ")" ::: "memory")
; #define PG8_WAIT_L(n) asm volatile("s_waitcnt lgkmcnt(" #n ")" ::: "memory")
; #define PG8_BAR __builtin_amdgcn_s_barrier()
; #define PG8_SCHED __builtin_amdgcn_sched_barrier(0)
; template <class Epi, class Sched, bool ALIGN_EPI = false, bool SP2 = false>
; __device__ __forceinline__ void gemm_phase(PG8_LAS unsigned char* lds, const Gemm g, const Sched& S, const Epi& E) {
;     ...
;             PG8_WAIT_V(8); PG8_WAIT_L(0); PG8_BAR; PG8_MMA(1, 0, At, B0); PG8_MMA(1, 1, At, B1); PG8_BAR; PG8_SCHED;
;             PG8_LDB(B0, 1, 0); PG8_LDB(B1, 1, 1); PG8_SCHED; PG8_LDA(At, 1, 0); PG8_STAGE(PG8_SA(0, 1), a2 + hstep, voffA);
;             PG8_WAIT_V(8); PG8_WAIT_L(0); PG8_BAR; PG8_MMA(0, 0, At, B0); PG8_MMA(0, 1, At, B1); PG8_BAR; PG8_SCHED;
	s_waitcnt lgkmcnt(0)
	v_mfma_f32_16x16x32_bf16 v[60:63], v[140:143], v[186:189], v[60:63]
	v_mfma_f32_16x16x32_bf16 v[56:59], v[158:161], v[186:189], v[56:59]
	v_mfma_f32_16x16x32_bf16 v[52:55], v[140:143], v[194:197], v[52:55]
	v_mfma_f32_16x16x32_bf16 v[48:51], v[158:161], v[194:197], v[48:51]
	v_mfma_f32_16x16x32_bf16 v[36:39], v[140:143], v[202:205], v[36:39]
	v_mfma_f32_16x16x32_bf16 v[32:35], v[158:161], v[202:205], v[32:35]
	v_mfma_f32_16x16x32_bf16 v[20:23], v[140:143], v[210:213], v[20:23]
	v_mfma_f32_16x16x32_bf16 v[16:19], v[158:161], v[210:213], v[16:19]
	v_mfma_f32_16x16x32_bf16 v[60:63], v[154:157], v[190:193], v[60:63]
	v_mfma_f32_16x16x32_bf16 v[56:59], v[162:165], v[190:193], v[56:59]
	v_mfma_f32_16x16x32_bf16 v[52:55], v[154:157], v[198:201], v[52:55]
	v_mfma_f32_16x16x32_bf16 v[48:51], v[162:165], v[198:201], v[48:51]
	v_mfma_f32_16x16x32_bf16 v[36:39], v[154:157], v[206:209], v[36:39]
	v_mfma_f32_16x16x32_bf16 v[32:35], v[162:165], v[206:209], v[32:35]
	v_mfma_f32_16x16x32_bf16 v[20:23], v[154:157], v[214:217], v[20:23]
	v_mfma_f32_16x16x32_bf16 v[16:19], v[162:165], v[214:217], v[16:19]
	v_mfma_f32_16x16x32_bf16 v[44:47], v[166:169], v[186:189], v[44:47]
	v_mfma_f32_16x16x32_bf16 v[40:43], v[174:177], v[186:189], v[40:43]
	v_mfma_f32_16x16x32_bf16 v[28:31], v[166:169], v[194:197], v[28:31]
	v_mfma_f32_16x16x32_bf16 v[24:27], v[174:177], v[194:197], v[24:27]
	v_mfma_f32_16x16x32_bf16 v[12:15], v[166:169], v[202:205], v[12:15]
	v_mfma_f32_16x16x32_bf16 v[8:11], v[174:177], v[202:205], v[8:11]
	v_mfma_f32_16x16x32_bf16 v[4:7], v[166:169], v[210:213], v[4:7]
	v_mfma_f32_16x16x32_bf16 v[0:3], v[174:177], v[210:213], v[0:3]
	v_mfma_f32_16x16x32_bf16 v[44:47], v[170:173], v[190:193], v[44:47]
	v_mfma_f32_16x16x32_bf16 v[40:43], v[182:185], v[190:193], v[40:43]
	v_mfma_f32_16x16x32_bf16 v[28:31], v[170:173], v[198:201], v[28:31]
	v_mfma_f32_16x16x32_bf16 v[24:27], v[182:185], v[198:201], v[24:27]
	v_mfma_f32_16x16x32_bf16 v[12:15], v[170:173], v[206:209], v[12:15]
	v_mfma_f32_16x16x32_bf16 v[8:11], v[182:185], v[206:209], v[8:11]
	v_mfma_f32_16x16x32_bf16 v[4:7], v[170:173], v[214:217], v[4:7]
	v_mfma_f32_16x16x32_bf16 v[0:3], v[182:185], v[214:217], v[0:3]
	s_barrier
	s_add_i32 s58, 0, 0x18000
	s_add_i32 s59, 0, 0x1c000
	v_add_u32_e32 v162, s58, v149
	v_add_u32_e32 v181, s59, v149
	ds_read_b128 v[140:143], v162
	ds_read_b128 v[154:157], v162 offset:1024
	ds_read_b128 v[158:161], v162 offset:2048
	ds_read_b128 v[162:165], v162 offset:3072
	ds_read_b128 v[166:169], v181
	ds_read_b128 v[170:173], v181 offset:1024
	ds_read_b128 v[174:177], v181 offset:2048
	ds_read_b128 v[182:185], v181 offset:3072
	s_add_u32 s22, s22, 0xb0000
	s_addc_u32 s23, s23, 0
	s_mov_b32 m0, s40
	v_lshl_add_u64 v[224:225], s[22:23], 0, v[128:129]
	ds_read_b128 v[186:189], v153 offset:32768
	ds_read_b128 v[190:193], v153 offset:33792
	ds_read_b128 v[194:197], v153 offset:34816
	ds_read_b128 v[198:201], v153 offset:35840
	ds_read_b128 v[202:205], v153 offset:36864
	ds_read_b128 v[206:209], v153 offset:37888
	ds_read_b128 v[210:213], v153 offset:38912
	ds_read_b128 v[214:217], v153 offset:39936
	global_load_lds_dwordx4 v[224:225], off
	v_lshl_add_u64 v[224:225], s[22:23], 0, v[130:131]
	s_mov_b32 m0, s41
	s_nop 0
	global_load_lds_dwordx4 v[224:225], off
	s_waitcnt vmcnt(8)
	s_waitcnt lgkmcnt(0)
	s_barrier
	s_waitcnt lgkmcnt(0)
	v_mfma_f32_16x16x32_bf16 v[124:127], v[140:143], v[186:189], v[124:127]
	v_mfma_f32_16x16x32_bf16 v[120:123], v[158:161], v[186:189], v[120:123]
	v_mfma_f32_16x16x32_bf16 v[116:119], v[140:143], v[194:197], v[116:119]
	v_mfma_f32_16x16x32_bf16 v[112:115], v[158:161], v[194:197], v[112:115]
	v_mfma_f32_16x16x32_bf16 v[100:103], v[140:143], v[202:205], v[100:103]
	v_mfma_f32_16x16x32_bf16 v[96:99], v[158:161], v[202:205], v[96:99]
	v_mfma_f32_16x16x32_bf16 v[84:87], v[140:143], v[210:213], v[84:87]
	v_mfma_f32_16x16x32_bf16 v[80:83], v[158:161], v[210:213], v[80:83]
	v_mfma_f32_16x16x32_bf16 v[124:127], v[154:157], v[190:193], v[124:127]
	v_mfma_f32_16x16x32_bf16 v[120:123], v[162:165], v[190:193], v[120:123]
	v_mfma_f32_16x16x32_bf16 v[116:119], v[154:157], v[198:201], v[116:119]
	v_mfma_f32_16x16x32_bf16 v[112:115], v[162:165], v[198:201], v[112:115]
	v_mfma_f32_16x16x32_bf16 v[100:103], v[154:157], v[206:209], v[100:103]
	v_mfma_f32_16x16x32_bf16 v[96:99], v[162:165], v[206:209], v[96:99]
	v_mfma_f32_16x16x32_bf16 v[84:87], v[154:157], v[214:217], v[84:87]
	v_mfma_f32_16x16x32_bf16 v[80:83], v[162:165], v[214:217], v[80:83]
	v_mfma_f32_16x16x32_bf16 v[108:111], v[166:169], v[186:189], v[108:111]
	v_mfma_f32_16x16x32_bf16 v[104:107], v[174:177], v[186:189], v[104:107]
	v_mfma_f32_16x16x32_bf16 v[92:95], v[166:169], v[194:197], v[92:95]
	v_mfma_f32_16x16x32_bf16 v[88:91], v[174:177], v[194:197], v[88:91]
	v_mfma_f32_16x16x32_bf16 v[76:79], v[166:169], v[202:205], v[76:79]
	v_mfma_f32_16x16x32_bf16 v[72:75], v[174:177], v[202:205], v[72:75]
	v_mfma_f32_16x16x32_bf16 v[68:71], v[166:169], v[210:213], v[68:71]
	v_mfma_f32_16x16x32_bf16 v[64:67], v[174:177], v[210:213], v[64:67]
	v_mfma_f32_16x16x32_bf16 v[108:111], v[170:173], v[190:193], v[108:111]
	v_mfma_f32_16x16x32_bf16 v[104:107], v[182:185], v[190:193], v[104:107]
	v_mfma_f32_16x16x32_bf16 v[92:95], v[170:173], v[198:201], v[92:95]
	v_mfma_f32_16x16x32_bf16 v[88:91], v[182:185], v[198:201], v[88:91]
	v_mfma_f32_16x16x32_bf16 v[76:79], v[170:173], v[206:209], v[76:79]
	v_mfma_f32_16x16x32_bf16 v[72:75], v[182:185], v[206:209], v[72:75]
	v_mfma_f32_16x16x32_bf16 v[68:71], v[170:173], v[214:217], v[68:71]
	v_mfma_f32_16x16x32_bf16 v[64:67], v[182:185], v[214:217], v[64:67]
	s_barrier
; #define PG8_STAGE(bufoff, gbase, voff) do { _Pragma("unroll") for (int _i = 0; _i < 2; ++_i) \
;         __builtin_amdgcn_global_load_lds((const unsigned*)((const char*)(gbase) + (voff)[_i]), (PG8_LAS unsigned*)(lds + (bufoff) + ldsw + _i * 8192), 16, 0, 0); } while (0)
; #define PG8_LDA(dst, b, h) do { _Pragma("unroll") for (int m = 0; m < 4; ++m) _Pragma("unroll") for (int k = 0; k < 2; ++k) dst[m][k] = *(const PG8_LAS bf16x8*)(lds + PG8_SA(b, h) + aoff + m * 2048 + k * 1024); } while (0)
; #define PG8_MMA(ai, bj, At, Bt) do { __builtin_amdgcn_s_setprio(1); _Pragma("unroll") for (int m = 0; m < 4; ++m) _Pragma("unroll") for (int n = 0; n < 2; ++n) _Pragma("unroll") for (int k = 0; k < 2; ++k) \
;         acc[ai][bj][m][n] = __builtin_amdgcn_mfma_f32_16x16x32_bf16(Bt[n][k], At[m][k], acc[ai][bj][m][n], 0, 0, 0); __builtin_amdgcn_s_setprio(0); } while (0)
; #define PG8_WAIT_V(n) asm volatile("s_waitcnt vmcnt(" #n ")" ::: "memory")
; #define PG8_WAIT_L(n) asm volatile("s_waitcnt lgkmcnt(" #n ")" ::: "memory")
; #define PG8_BAR __builtin_amdgcn_s_barrier()
; #define PG8_SCHED __builtin_amdgcn_sched_barrier(0)
; template <class Epi, class Sched, bool ALIGN_EPI = false, bool SP2 = false>
; __device__ __forceinline__ void gemm_phase(PG8_LAS unsigned char* lds, const Gemm g, const Sched& S, const Epi& E) {
;     ...
;             PG8_LDA(At, 1, 1); PG8_STAGE(PG8_SB(1, 0), b3, voffB); PG8_STAGE(PG8_SB(1, 1), b3 + hstep, voffB); PG8_STAGE(PG8_SA(1, 0), a3, voffA);
;             PG8_WAIT_V(8); PG8_WAIT_L(0); PG8_BAR; PG8_MMA(1, 0, At, B0); PG8_MMA(1, 1, At, B1); PG8_BAR; PG8_SCHED;
	s_add_i32 s22, s58, s33
	v_lshl_add_u64 v[178:179], v[178:179], 0, s[12:13]
	s_mov_b32 m0, s22
	ds_read_b128 v[186:189], v153 offset:49152
	ds_read_b128 v[190:193], v153 offset:50176
	ds_read_b128 v[194:197], v153 offset:51200
	ds_read_b128 v[198:201], v153 offset:52224
	ds_read_b128 v[202:205], v153 offset:53248
	ds_read_b128 v[206:209], v153 offset:54272
	ds_read_b128 v[210:213], v153 offset:55296
	ds_read_b128 v[214:217], v153 offset:56320
	global_load_lds_dwordx4 v[178:179], off
	s_add_i32 m0, s22, 0x2000
	s_add_u32 s20, s20, 0xb0080
	v_lshl_add_u64 v[178:179], v[218:219], 0, s[12:13]
	s_addc_u32 s21, s21, 0
	s_add_i32 s22, s59, s33
	global_load_lds_dwordx4 v[178:179], off
	v_lshl_add_u64 v[178:179], s[20:21], 0, v[128:129]
	s_mov_b32 m0, s22
	s_nop 0
	global_load_lds_dwordx4 v[178:179], off
	v_lshl_add_u64 v[178:179], s[20:21], 0, v[130:131]
	s_add_i32 m0, s22, 0x2000
	s_nop 0
	global_load_lds_dwordx4 v[178:179], off
	v_lshl_add_u64 v[178:179], v[220:221], 0, s[12:13]
	s_mov_b32 m0, s43
	s_nop 0
	global_load_lds_dwordx4 v[178:179], off
	v_lshl_add_u64 v[178:179], v[222:223], 0, s[12:13]
	s_mov_b32 m0, s44
	s_nop 0
	global_load_lds_dwordx4 v[178:179], off
	s_waitcnt vmcnt(8)
	s_waitcnt lgkmcnt(0)
	s_barrier
	s_waitcnt lgkmcnt(0)
	v_mfma_f32_16x16x32_bf16 v[60:63], v[140:143], v[186:189], v[60:63]
	v_mfma_f32_16x16x32_bf16 v[56:59], v[158:161], v[186:189], v[56:59]
	v_mfma_f32_16x16x32_bf16 v[52:55], v[140:143], v[194:197], v[52:55]
	v_mfma_f32_16x16x32_bf16 v[48:51], v[158:161], v[194:197], v[48:51]
	v_mfma_f32_16x16x32_bf16 v[36:39], v[140:143], v[202:205], v[36:39]
	v_mfma_f32_16x16x32_bf16 v[32:35], v[158:161], v[202:205], v[32:35]
	v_mfma_f32_16x16x32_bf16 v[20:23], v[140:143], v[210:213], v[20:23]
	v_mfma_f32_16x16x32_bf16 v[16:19], v[158:161], v[210:213], v[16:19]
	v_mfma_f32_16x16x32_bf16 v[60:63], v[154:157], v[190:193], v[60:63]
	v_mfma_f32_16x16x32_bf16 v[56:59], v[162:165], v[190:193], v[56:59]
	v_mfma_f32_16x16x32_bf16 v[52:55], v[154:157], v[198:201], v[52:55]
	v_mfma_f32_16x16x32_bf16 v[48:51], v[162:165], v[198:201], v[48:51]
	v_mfma_f32_16x16x32_bf16 v[36:39], v[154:157], v[206:209], v[36:39]
	v_mfma_f32_16x16x32_bf16 v[32:35], v[162:165], v[206:209], v[32:35]
	v_mfma_f32_16x16x32_bf16 v[20:23], v[154:157], v[214:217], v[20:23]
	v_mfma_f32_16x16x32_bf16 v[16:19], v[162:165], v[214:217], v[16:19]
	v_mfma_f32_16x16x32_bf16 v[44:47], v[166:169], v[186:189], v[44:47]
	v_mfma_f32_16x16x32_bf16 v[40:43], v[174:177], v[186:189], v[40:43]
	v_mfma_f32_16x16x32_bf16 v[28:31], v[166:169], v[194:197], v[28:31]
	v_mfma_f32_16x16x32_bf16 v[24:27], v[174:177], v[194:197], v[24:27]
	v_mfma_f32_16x16x32_bf16 v[12:15], v[166:169], v[202:205], v[12:15]
	v_mfma_f32_16x16x32_bf16 v[8:11], v[174:177], v[202:205], v[8:11]
	v_mfma_f32_16x16x32_bf16 v[4:7], v[166:169], v[210:213], v[4:7]
	v_mfma_f32_16x16x32_bf16 v[0:3], v[174:177], v[210:213], v[0:3]
	v_mfma_f32_16x16x32_bf16 v[44:47], v[170:173], v[190:193], v[44:47]
	v_mfma_f32_16x16x32_bf16 v[40:43], v[182:185], v[190:193], v[40:43]
	v_mfma_f32_16x16x32_bf16 v[28:31], v[170:173], v[198:201], v[28:31]
	v_mfma_f32_16x16x32_bf16 v[24:27], v[182:185], v[198:201], v[24:27]
	v_mfma_f32_16x16x32_bf16 v[12:15], v[170:173], v[206:209], v[12:15]
	v_mfma_f32_16x16x32_bf16 v[8:11], v[182:185], v[206:209], v[8:11]
	v_mfma_f32_16x16x32_bf16 v[4:7], v[170:173], v[214:217], v[4:7]
	v_mfma_f32_16x16x32_bf16 v[0:3], v[182:185], v[214:217], v[0:3]
	s_barrier
	s_add_i32 s57, s57, 2
	s_add_u32 s18, s18, 0x100
	s_addc_u32 s19, s19, 0
	s_add_u32 s55, s55, 0x100
	s_addc_u32 s56, s56, 0
	s_cmp_gt_u32 s57, 41
	s_cbranch_scc0 .LBB0_306
	s_and_b64 vcc, exec, s[14:15]
	s_cbranch_vccz .LBB0_309
	s_barrier

; #define PG8_STAGE(bufoff, gbase, voff) do { _Pragma("unroll") for (int _i = 0; _i < 2; ++_i) \
;         __builtin_amdgcn_global_load_lds((const unsigned*)((const char*)(gbase) + (voff)[_i]), (PG8_LAS unsigned*)(lds + (bufoff) + ldsw + _i * 8192), 16, 0, 0); } while (0)
; #define PG8_WAIT_V(n) asm volatile("s_waitcnt vmcnt(" #n ")" ::: "memory")
; template <class Epi, class Sched, bool ALIGN_EPI = false, bool SP2 = false>
; __device__ __forceinline__ void gemm_phase(PG8_LAS unsigned char* lds, const Gemm g, const Sched& S, const Epi& E) {
;     ...
;         PG8_STAGE(PG8_SB(1, 0), cB + kstep, voffB); PG8_STAGE(PG8_SA(1, 0), cA + kstep, voffA); PG8_STAGE(PG8_SB(1, 1), cB + hstep + kstep, voffB);
;         PG8_WAIT_V(6); PG8_BAR;
;     } else {
;         PG8_STAGE(PG8_SB(0, 0), cB, voffB); PG8_STAGE(PG8_SA(0, 0), cA, voffA); PG8_STAGE(PG8_SB(0, 1), cB + hstep, voffB); PG8_STAGE(PG8_SA(0, 1), cA + hstep, voffA);
;         if (wr == 1) PG8_BAR;
;         PG8_WAIT_V(4); PG8_BAR;
;         PG8_STAGE(PG8_SB(1, 0), cB + kstep, voffB); PG8_STAGE(PG8_SA(1, 0), cA + kstep, voffA); PG8_STAGE(PG8_SB(1, 1), cB + hstep + kstep, voffB);
;         PG8_WAIT_V(6); PG8_BAR;
;     }
;     for (;;) {
;         const bool has_next = S.next(ui + 1, nxt);
;         const char* nA = has_next ? (const char*)g.A + (size_t)nxt.pm * tstep : cA; const char* nB = has_next ? (const char*)g.Bt + (size_t)nxt.pn * tstep : cB;
;         for (int t = 0; t < nt; t += 2) {
;             const bool last = (t == nt - 2);
;             const char* a1 = cA + (size_t)(t + 1) * kstep;
;             const char* a2 = last ? nA : cA + (size_t)(t + 2) * kstep; const char* b2 = last ? nB : cB + (size_t)(t + 2) * kstep;
;             const char* a3 = a2 + kstep; const char* b3 = b2 + kstep;
;             if (last && has_next) S.a_ready(nxt);
;             if constexpr (SP2) {
;             PG8_LDB(B0, 0, 0); PG8_LDB(B1, 0, 1); PG8_SCHED; PG8_LDA(At, 0, 0); PG8_STAGE(PG8_SA(1, 1), a1 + hstep, voffA);
;             PG8_WAIT_V(8); PG8_WAIT_L(0); PG8_BAR; PG8_MMA(0, 0, At, B0); PG8_MMA(0, 1, At, B1); PG8_BAR; PG8_SCHED;
;             PG8_LDA(At, 0, 1); PG8_STAGE(PG8_SB(0, 0), b2, voffB); PG8_STAGE(PG8_SB(0, 1), b2 + hstep, voffB); PG8_STAGE(PG8_SA(0, 0), a2, voffA);
;             PG8_WAIT_V(8); PG8_WAIT_L(0); PG8_BAR; PG8_MMA(1, 0, At, B0); PG8_MMA(1, 1, At, B1); PG8_BAR; PG8_SCHED;
.LBB0_332:
	s_lshl_b64 s[8:9], s[8:9], 19
	s_add_u32 s8, s14, s8
	s_addc_u32 s9, s16, s9
	s_add_u32 s24, s8, 0xf000000
	s_addc_u32 s25, s9, 0
	s_add_i32 s33, 0, 0x18000
	s_lshl_b32 s8, s17, 5
	s_add_i32 s9, s33, s21
	s_mov_b64 s[18:19], 0x80
	s_lshl_b32 s23, s22, 13
	s_and_b32 s8, s8, 0x60
	v_lshl_add_u64 v[4:5], v[32:33], 0, s[18:19]
	s_mov_b32 m0, s9
	s_add_i32 s16, s9, 0x2000
	s_add_i32 s14, s12, 0x8000
	s_add_i32 s17, s12, 0xa000
	s_waitcnt vmcnt(2)
	s_barrier
	global_load_lds_dwordx4 v[4:5], off
	v_lshl_add_u64 v[6:7], v[34:35], 0, s[18:19]
	s_mov_b32 m0, s16
	s_add_u32 s26, s4, 0xb0080
	global_load_lds_dwordx4 v[6:7], off
	v_lshl_add_u64 v[2:3], v[24:25], 0, s[18:19]
	s_mov_b32 m0, s14
	s_addc_u32 s27, s5, 0
	s_add_i32 s34, 0, 0x1c000
	global_load_lds_dwordx4 v[2:3], off
	v_lshl_add_u64 v[8:9], v[22:23], 0, s[18:19]
	s_mov_b32 m0, s17
	s_add_i32 s18, s34, s21
	global_load_lds_dwordx4 v[8:9], off
	v_lshl_add_u64 v[16:17], s[26:27], 0, v[128:129]
	s_mov_b32 m0, s18
	s_add_i32 s19, s18, 0x2000
	global_load_lds_dwordx4 v[16:17], off
	v_lshl_add_u64 v[18:19], s[26:27], 0, v[130:131]
	s_mov_b32 m0, s19
	v_lshl_or_b32 v69, s8, 7, v147
	global_load_lds_dwordx4 v[18:19], off
	s_add_i32 s35, 0, 0x10000
	s_add_i32 s40, 0, 0x14000
	v_add_u32_e32 v172, s35, v69
	v_lshl_or_b32 v28, s22, 6, v145
	v_lshl_or_b32 v0, v145, 6, v146
	v_lshlrev_b32_e32 v1, 2, v145
	s_waitcnt vmcnt(6)
	s_barrier
	v_add_u32_e32 v145, s40, v69
	ds_read_b128 v[36:39], v172
	ds_read_b128 v[40:43], v172 offset:1024
	ds_read_b128 v[44:47], v172 offset:2048
	ds_read_b128 v[48:51], v172 offset:3072
	ds_read_b128 v[52:55], v145
	ds_read_b128 v[56:59], v145 offset:1024
	ds_read_b128 v[60:63], v145 offset:2048
	ds_read_b128 v[64:67], v145 offset:3072
	v_and_b32_e32 v1, 32, v1
	v_bitop3_b32 v68, v0, s23, v1 bitop3:0xde
	v_or_b32_e32 v0, 48, v28
	v_mov_b32_e32 v1, v129
	v_or_b32_e32 v10, 32, v28
	v_mov_b32_e32 v11, v129
	v_or_b32_e32 v20, 16, v28
	v_mov_b32_e32 v21, v129
	v_mov_b32_e32 v29, v129
	v_lshlrev_b64 v[0:1], 12, v[0:1]
	v_lshlrev_b64 v[10:11], 12, v[10:11]
	v_lshlrev_b64 v[20:21], 12, v[20:21]
	v_lshlrev_b64 v[28:29], 12, v[28:29]
	v_lshl_add_u64 v[0:1], s[24:25], 0, v[0:1]
	v_lshl_add_u64 v[10:11], s[24:25], 0, v[10:11]
	v_lshl_add_u64 v[20:21], s[24:25], 0, v[20:21]
	v_lshl_add_u64 v[28:29], s[24:25], 0, v[28:29]
	v_add_u32_e32 v173, 0, v68
	v_add_u32_e32 v174, s34, v69
	v_add_u32_e32 v175, s33, v69
	s_add_u32 s22, s2, 0xb0080
	s_addc_u32 s23, s3, 0
	s_add_i32 s25, s12, 0xc000
	v_lshl_add_u64 v[100:101], s[22:23], 0, v[128:129]
	s_mov_b32 m0, s25
	ds_read_b128 v[68:71], v173
	ds_read_b128 v[72:75], v173 offset:1024
	ds_read_b128 v[76:79], v173 offset:2048
	ds_read_b128 v[80:83], v173 offset:3072
	ds_read_b128 v[84:87], v173 offset:4096
	ds_read_b128 v[88:91], v173 offset:5120
	ds_read_b128 v[92:95], v173 offset:6144
	ds_read_b128 v[96:99], v173 offset:7168
	global_load_lds_dwordx4 v[100:101], off
	v_lshl_add_u64 v[100:101], s[22:23], 0, v[130:131]
	s_add_i32 s22, s12, 0xe000
	s_mov_b32 m0, s22
	s_nop 0
	global_load_lds_dwordx4 v[100:101], off
	s_waitcnt vmcnt(8)
	s_waitcnt lgkmcnt(0)
	s_barrier
	s_waitcnt lgkmcnt(0)
	v_mfma_f32_16x16x32_bf16 v[100:103], v[36:39], v[68:71], 0
	v_mfma_f32_16x16x32_bf16 v[108:111], v[36:39], v[76:79], 0
	v_mfma_f32_16x16x32_bf16 v[116:119], v[36:39], v[84:87], 0
	v_mfma_f32_16x16x32_bf16 v[36:39], v[36:39], v[92:95], 0
	v_mfma_f32_16x16x32_bf16 v[100:103], v[40:43], v[72:75], v[100:103]
	v_mfma_f32_16x16x32_bf16 v[104:107], v[44:47], v[68:71], 0
	v_mfma_f32_16x16x32_bf16 v[108:111], v[40:43], v[80:83], v[108:111]
	v_mfma_f32_16x16x32_bf16 v[112:115], v[44:47], v[76:79], 0
	v_mfma_f32_16x16x32_bf16 v[116:119], v[40:43], v[88:91], v[116:119]
	v_mfma_f32_16x16x32_bf16 v[120:123], v[44:47], v[84:87], 0
	v_mfma_f32_16x16x32_bf16 v[36:39], v[40:43], v[96:99], v[36:39]
	v_mfma_f32_16x16x32_bf16 v[40:43], v[44:47], v[92:95], 0
	v_mfma_f32_16x16x32_bf16 v[104:107], v[48:51], v[72:75], v[104:107]
	v_mfma_f32_16x16x32_bf16 v[112:115], v[48:51], v[80:83], v[112:115]
	v_mfma_f32_16x16x32_bf16 v[120:123], v[48:51], v[88:91], v[120:123]
	v_mfma_f32_16x16x32_bf16 v[40:43], v[48:51], v[96:99], v[40:43]
	v_mfma_f32_16x16x32_bf16 v[44:47], v[52:55], v[68:71], 0
	v_mfma_f32_16x16x32_bf16 v[48:51], v[60:63], v[68:71], 0
	v_mfma_f32_16x16x32_bf16 v[44:47], v[56:59], v[72:75], v[44:47]
	v_mfma_f32_16x16x32_bf16 v[48:51], v[64:67], v[72:75], v[48:51]
	v_mfma_f32_16x16x32_bf16 v[68:71], v[52:55], v[76:79], 0
	v_mfma_f32_16x16x32_bf16 v[72:75], v[60:63], v[76:79], 0
	v_mfma_f32_16x16x32_bf16 v[76:79], v[52:55], v[84:87], 0
	v_mfma_f32_16x16x32_bf16 v[52:55], v[52:55], v[92:95], 0
	v_mfma_f32_16x16x32_bf16 v[68:71], v[56:59], v[80:83], v[68:71]
	v_mfma_f32_16x16x32_bf16 v[72:75], v[64:67], v[80:83], v[72:75]
	v_mfma_f32_16x16x32_bf16 v[76:79], v[56:59], v[88:91], v[76:79]
	v_mfma_f32_16x16x32_bf16 v[80:83], v[60:63], v[84:87], 0
	v_mfma_f32_16x16x32_bf16 v[52:55], v[56:59], v[96:99], v[52:55]
	v_mfma_f32_16x16x32_bf16 v[56:59], v[60:63], v[92:95], 0
	v_mfma_f32_16x16x32_bf16 v[80:83], v[64:67], v[88:91], v[80:83]
	v_mfma_f32_16x16x32_bf16 v[56:59], v[64:67], v[96:99], v[56:59]
	s_barrier
	s_add_i32 s23, s35, s21
	s_mov_b64 s[26:27], 0x100
	s_add_i32 s24, s23, 0x2000
	v_lshl_add_u64 v[60:61], v[32:33], 0, s[26:27]
	s_mov_b32 m0, s23
	s_add_u32 s34, s4, 0xb0100
	global_load_lds_dwordx4 v[60:61], off
	v_lshl_add_u64 v[60:61], v[34:35], 0, s[26:27]
	s_mov_b32 m0, s24
	s_addc_u32 s35, s5, 0
	s_add_i32 s21, s40, s21
	global_load_lds_dwordx4 v[60:61], off
	v_lshl_add_u64 v[60:61], s[34:35], 0, v[128:129]
	s_mov_b32 m0, s21
	s_add_i32 s33, s21, 0x2000
	global_load_lds_dwordx4 v[60:61], off
	v_lshl_add_u64 v[60:61], s[34:35], 0, v[130:131]
	s_mov_b32 m0, s33
	s_nop 0
	global_load_lds_dwordx4 v[60:61], off
	v_lshl_add_u64 v[60:61], v[24:25], 0, s[26:27]
	s_mov_b32 m0, s12
	s_nop 0
	global_load_lds_dwordx4 v[60:61], off
	v_lshl_add_u64 v[60:61], v[22:23], 0, s[26:27]
	s_mov_b32 m0, s20
	s_nop 0
	global_load_lds_dwordx4 v[60:61], off
	s_waitcnt vmcnt(8)
	s_waitcnt lgkmcnt(0)
	s_barrier
; #define PG8_STAGE(bufoff, gbase, voff) do { _Pragma("unroll") for (int _i = 0; _i < 2; ++_i) \
;         __builtin_amdgcn_global_load_lds((const unsigned*)((const char*)(gbase) + (voff)[_i]), (PG8_LAS unsigned*)(lds + (bufoff) + ldsw + _i * 8192), 16, 0, 0); } while (0)
; #define PG8_LDA(dst, b, h) do { _Pragma("unroll") for (int m = 0; m < 4; ++m) _Pragma("unroll") for (int k = 0; k < 2; ++k) dst[m][k] = *(const PG8_LAS bf16x8*)(lds + PG8_SA(b, h) + aoff + m * 2048 + k * 1024); } while (0)
; #define PG8_LDB(dst, b, h) do { _Pragma("unroll") for (int n = 0; n < 2; ++n) _Pragma("unroll") for (int k = 0; k < 2; ++k) dst[n][k] = *(const PG8_LAS bf16x8*)(lds + PG8_SB(b, h) + boff + n * 2048 + k * 1024); } while (0)
; #define PG8_MMA(ai, bj, At, Bt) do { __builtin_amdgcn_s_setprio(1); _Pragma("unroll") for (int m = 0; m < 4; ++m) _Pragma("unroll") for (int n = 0; n < 2; ++n) _Pragma("unroll") for (int k = 0; k < 2; ++k) \
;         acc[ai][bj][m][n] = __builtin_amdgcn_mfma_f32_16x16x32_bf16(Bt[n][k], At[m][k], acc[ai][bj][m][n], 0, 0, 0); __builtin_amdgcn_s_setprio(0); } while (0)
; #define PG8_WAIT_V(n) asm volatile("s_waitcnt vmcnt(" #n ")" ::: "memory")
; template <class Epi, class Sched, bool ALIGN_EPI = false, bool SP2 = false>
; __device__ __forceinline__ void gemm_phase(PG8_LAS unsigned char* lds, const Gemm g, const Sched& S, const Epi& E) {
;     ...
;             PG8_LDB(B0, 0, 0); PG8_LDB(B1, 0, 1); PG8_SCHED; PG8_LDA(At, 0, 0); PG8_STAGE(PG8_SA(1, 1), a1 + hstep, voffA);
;             PG8_WAIT_V(8); PG8_WAIT_L(0); PG8_BAR; PG8_MMA(0, 0, At, B0); PG8_MMA(0, 1, At, B1); PG8_BAR; PG8_SCHED;
;             PG8_LDA(At, 0, 1); PG8_STAGE(PG8_SB(0, 0), b2, voffB); PG8_STAGE(PG8_SB(0, 1), b2 + hstep, voffB); PG8_STAGE(PG8_SA(0, 0), a2, voffA);
;             PG8_WAIT_V(8); PG8_WAIT_L(0); PG8_BAR; PG8_MMA(1, 0, At, B0); PG8_MMA(1, 1, At, B1); PG8_BAR; PG8_SCHED;
;             PG8_LDB(B0, 1, 0); PG8_LDB(B1, 1, 1); PG8_SCHED; PG8_LDA(At, 1, 0); PG8_STAGE(PG8_SA(0, 1), a2 + hstep, voffA);
;             PG8_WAIT_V(8); PG8_WAIT_L(0); PG8_BAR; PG8_MMA(0, 0, At, B0); PG8_MMA(0, 1, At, B1); PG8_BAR; PG8_SCHED;
;             PG8_LDA(At, 1, 1); PG8_STAGE(PG8_SB(1, 0), b3, voffB); PG8_STAGE(PG8_SB(1, 1), b3 + hstep, voffB); PG8_STAGE(PG8_SA(1, 0), a3, voffA);
;             PG8_WAIT_V(8); PG8_WAIT_L(0); PG8_BAR; PG8_MMA(1, 0, At, B0); PG8_MMA(1, 1, At, B1); PG8_BAR; PG8_SCHED;
	s_setprio 0
	s_barrier
	ds_read_b128 v[60:63], v175
	ds_read_b128 v[64:67], v175 offset:1024
	ds_read_b128 v[84:87], v175 offset:2048
	ds_read_b128 v[88:91], v175 offset:3072
	ds_read_b128 v[92:95], v174
	ds_read_b128 v[96:99], v174 offset:1024
	ds_read_b128 v[124:127], v174 offset:2048
	ds_read_b128 v[132:135], v174 offset:3072
	s_add_u32 s26, s2, 0xb0100
	s_addc_u32 s27, s3, 0
	s_mov_b32 m0, s13
	v_lshl_add_u64 v[170:171], s[26:27], 0, v[128:129]
	ds_read_b128 v[136:139], v173 offset:32768
	ds_read_b128 v[140:143], v173 offset:33792
	ds_read_b128 v[146:149], v173 offset:34816
	ds_read_b128 v[150:153], v173 offset:35840
	ds_read_b128 v[154:157], v173 offset:36864
	ds_read_b128 v[158:161], v173 offset:37888
	ds_read_b128 v[162:165], v173 offset:38912
	ds_read_b128 v[166:169], v173 offset:39936
	global_load_lds_dwordx4 v[170:171], off
	v_lshl_add_u64 v[170:171], s[26:27], 0, v[130:131]
	s_mov_b32 m0, s15
	s_nop 0
	global_load_lds_dwordx4 v[170:171], off
	s_waitcnt vmcnt(8)
	s_waitcnt lgkmcnt(0)
	s_barrier
	s_waitcnt lgkmcnt(0)
	v_mfma_f32_16x16x32_bf16 v[100:103], v[60:63], v[136:139], v[100:103]
	v_mfma_f32_16x16x32_bf16 v[104:107], v[84:87], v[136:139], v[104:107]
	v_mfma_f32_16x16x32_bf16 v[108:111], v[60:63], v[146:149], v[108:111]
	v_mfma_f32_16x16x32_bf16 v[112:115], v[84:87], v[146:149], v[112:115]
	v_mfma_f32_16x16x32_bf16 v[116:119], v[60:63], v[154:157], v[116:119]
	v_mfma_f32_16x16x32_bf16 v[120:123], v[84:87], v[154:157], v[120:123]
	v_mfma_f32_16x16x32_bf16 v[36:39], v[60:63], v[162:165], v[36:39]
	v_mfma_f32_16x16x32_bf16 v[40:43], v[84:87], v[162:165], v[40:43]
	v_mfma_f32_16x16x32_bf16 v[100:103], v[64:67], v[140:143], v[100:103]
	v_mfma_f32_16x16x32_bf16 v[104:107], v[88:91], v[140:143], v[104:107]
	v_mfma_f32_16x16x32_bf16 v[108:111], v[64:67], v[150:153], v[108:111]
	v_mfma_f32_16x16x32_bf16 v[112:115], v[88:91], v[150:153], v[112:115]
	v_mfma_f32_16x16x32_bf16 v[116:119], v[64:67], v[158:161], v[116:119]
	v_mfma_f32_16x16x32_bf16 v[120:123], v[88:91], v[158:161], v[120:123]
	v_mfma_f32_16x16x32_bf16 v[36:39], v[64:67], v[166:169], v[36:39]
	v_mfma_f32_16x16x32_bf16 v[40:43], v[88:91], v[166:169], v[40:43]
	v_mfma_f32_16x16x32_bf16 v[44:47], v[92:95], v[136:139], v[44:47]
	v_mfma_f32_16x16x32_bf16 v[48:51], v[124:127], v[136:139], v[48:51]
	v_mfma_f32_16x16x32_bf16 v[60:63], v[92:95], v[146:149], v[68:71]
	v_mfma_f32_16x16x32_bf16 v[64:67], v[124:127], v[146:149], v[72:75]
	v_mfma_f32_16x16x32_bf16 v[68:71], v[92:95], v[154:157], v[76:79]
	v_mfma_f32_16x16x32_bf16 v[72:75], v[124:127], v[154:157], v[80:83]
	v_mfma_f32_16x16x32_bf16 v[52:55], v[92:95], v[162:165], v[52:55]
	v_mfma_f32_16x16x32_bf16 v[56:59], v[124:127], v[162:165], v[56:59]
	v_mfma_f32_16x16x32_bf16 v[44:47], v[96:99], v[140:143], v[44:47]
	v_mfma_f32_16x16x32_bf16 v[48:51], v[132:135], v[140:143], v[48:51]
	v_mfma_f32_16x16x32_bf16 v[60:63], v[96:99], v[150:153], v[60:63]
	v_mfma_f32_16x16x32_bf16 v[64:67], v[132:135], v[150:153], v[64:67]
	v_mfma_f32_16x16x32_bf16 v[68:71], v[96:99], v[158:161], v[68:71]
	v_mfma_f32_16x16x32_bf16 v[72:75], v[132:135], v[158:161], v[72:75]
	v_mfma_f32_16x16x32_bf16 v[52:55], v[96:99], v[166:169], v[52:55]
	v_mfma_f32_16x16x32_bf16 v[56:59], v[132:135], v[166:169], v[56:59]
	s_barrier
	s_mov_b64 s[26:27], 0x180
	s_mov_b32 m0, s9
	v_lshl_add_u64 v[76:77], v[32:33], 0, s[26:27]
	s_add_u32 s4, s4, 0xb0180
	global_load_lds_dwordx4 v[76:77], off
	v_lshl_add_u64 v[76:77], v[34:35], 0, s[26:27]
	s_mov_b32 m0, s16
	s_addc_u32 s5, s5, 0
	global_load_lds_dwordx4 v[76:77], off
	v_lshl_add_u64 v[76:77], s[4:5], 0, v[128:129]
	s_mov_b32 m0, s18
	s_nop 0
	global_load_lds_dwordx4 v[76:77], off
	v_lshl_add_u64 v[76:77], s[4:5], 0, v[130:131]
	s_mov_b32 m0, s19
	s_nop 0
	global_load_lds_dwordx4 v[76:77], off
	v_lshl_add_u64 v[76:77], v[24:25], 0, s[26:27]
	s_mov_b32 m0, s14
	s_nop 0
	global_load_lds_dwordx4 v[76:77], off
	v_lshl_add_u64 v[76:77], v[22:23], 0, s[26:27]
	s_mov_b32 m0, s17
	s_nop 0
	global_load_lds_dwordx4 v[76:77], off
	s_waitcnt vmcnt(8)
	s_waitcnt lgkmcnt(0)
	s_barrier
	s_setprio 0
	s_barrier
	ds_read_b128 v[76:79], v172
	ds_read_b128 v[80:83], v172 offset:1024
	ds_read_b128 v[84:87], v172 offset:2048
	ds_read_b128 v[88:91], v172 offset:3072
	ds_read_b128 v[92:95], v145
	ds_read_b128 v[96:99], v145 offset:1024
	ds_read_b128 v[124:127], v145 offset:2048
	ds_read_b128 v[132:135], v145 offset:3072
	s_add_u32 s2, s2, 0xb0180
	s_addc_u32 s3, s3, 0
	s_mov_b32 m0, s25
	v_lshl_add_u64 v[170:171], s[2:3], 0, v[128:129]
	ds_read_b128 v[136:139], v173
	ds_read_b128 v[140:143], v173 offset:1024
	ds_read_b128 v[146:149], v173 offset:2048
	ds_read_b128 v[150:153], v173 offset:3072
	ds_read_b128 v[154:157], v173 offset:4096
	ds_read_b128 v[158:161], v173 offset:5120
	ds_read_b128 v[162:165], v173 offset:6144
	ds_read_b128 v[166:169], v173 offset:7168
	global_load_lds_dwordx4 v[170:171], off
	v_lshl_add_u64 v[130:131], s[2:3], 0, v[130:131]
	s_mov_b32 m0, s22
	s_nop 0
	global_load_lds_dwordx4 v[130:131], off
	s_waitcnt vmcnt(8)
	s_waitcnt lgkmcnt(0)
	s_barrier
; #define PG8_STAGE(bufoff, gbase, voff) do { _Pragma("unroll") for (int _i = 0; _i < 2; ++_i) \
;         __builtin_amdgcn_global_load_lds((const unsigned*)((const char*)(gbase) + (voff)[_i]), (PG8_LAS unsigned*)(lds + (bufoff) + ldsw + _i * 8192), 16, 0, 0); } while (0)
; #define PG8_LDA(dst, b, h) do { _Pragma("unroll") for (int m = 0; m < 4; ++m) _Pragma("unroll") for (int k = 0; k < 2; ++k) dst[m][k] = *(const PG8_LAS bf16x8*)(lds + PG8_SA(b, h) + aoff + m * 2048 + k * 1024); } while (0)
; #define PG8_LDB(dst, b, h) do { _Pragma("unroll") for (int n = 0; n < 2; ++n) _Pragma("unroll") for (int k = 0; k < 2; ++k) dst[n][k] = *(const PG8_LAS bf16x8*)(lds + PG8_SB(b, h) + boff + n * 2048 + k * 1024); } while (0)
; #define PG8_MMA(ai, bj, At, Bt) do { __builtin_amdgcn_s_setprio(1); _Pragma("unroll") for (int m = 0; m < 4; ++m) _Pragma("unroll") for (int n = 0; n < 2; ++n) _Pragma("unroll") for (int k = 0; k < 2; ++k) \
;         acc[ai][bj][m][n] = __builtin_amdgcn_mfma_f32_16x16x32_bf16(Bt[n][k], At[m][k], acc[ai][bj][m][n], 0, 0, 0); __builtin_amdgcn_s_setprio(0); } while (0)
; #define PG8_WAIT_V(n) asm volatile("s_waitcnt vmcnt(" #n ")" ::: "memory")
; #define PG8_WAIT_L(n) asm volatile("s_waitcnt lgkmcnt(" #n ")" ::: "memory")
; #define PG8_BAR __builtin_amdgcn_s_barrier()
; #define PG8_SCHED __builtin_amdgcn_sched_barrier(0)
; template <class Epi, class Sched, bool ALIGN_EPI = false, bool SP2 = false>
; __device__ __forceinline__ void gemm_phase(PG8_LAS unsigned char* lds, const Gemm g, const Sched& S, const Epi& E) {
;     ...
;             PG8_LDB(B0, 0, 0); PG8_LDB(B1, 0, 1); PG8_SCHED; PG8_LDA(At, 0, 0); PG8_STAGE(PG8_SA(1, 1), a1 + hstep, voffA);
;             PG8_WAIT_V(8); PG8_WAIT_L(0); PG8_BAR; PG8_MMA(0, 0, At, B0); PG8_MMA(0, 1, At, B1); PG8_BAR; PG8_SCHED;
;             PG8_LDA(At, 0, 1); PG8_STAGE(PG8_SB(0, 0), b2, voffB); PG8_STAGE(PG8_SB(0, 1), b2 + hstep, voffB); PG8_STAGE(PG8_SA(0, 0), a2, voffA);
;             PG8_WAIT_V(8); PG8_WAIT_L(0); PG8_BAR; PG8_MMA(1, 0, At, B0); PG8_MMA(1, 1, At, B1); PG8_BAR; PG8_SCHED;
;             PG8_LDB(B0, 1, 0); PG8_LDB(B1, 1, 1); PG8_SCHED; PG8_LDA(At, 1, 0); PG8_STAGE(PG8_SA(0, 1), a2 + hstep, voffA);
;             PG8_WAIT_V(8); PG8_WAIT_L(0); PG8_BAR; PG8_MMA(0, 0, At, B0); PG8_MMA(0, 1, At, B1); PG8_BAR; PG8_SCHED;
	s_waitcnt lgkmcnt(0)
	v_mfma_f32_16x16x32_bf16 v[100:103], v[76:79], v[136:139], v[100:103]
	v_mfma_f32_16x16x32_bf16 v[104:107], v[84:87], v[136:139], v[104:107]
	v_mfma_f32_16x16x32_bf16 v[108:111], v[76:79], v[146:149], v[108:111]
	v_mfma_f32_16x16x32_bf16 v[112:115], v[84:87], v[146:149], v[112:115]
	v_mfma_f32_16x16x32_bf16 v[116:119], v[76:79], v[154:157], v[116:119]
	v_mfma_f32_16x16x32_bf16 v[120:123], v[84:87], v[154:157], v[120:123]
	v_mfma_f32_16x16x32_bf16 v[36:39], v[76:79], v[162:165], v[36:39]
	v_mfma_f32_16x16x32_bf16 v[40:43], v[84:87], v[162:165], v[40:43]
	v_mfma_f32_16x16x32_bf16 v[100:103], v[80:83], v[140:143], v[100:103]
	v_mfma_f32_16x16x32_bf16 v[104:107], v[88:91], v[140:143], v[104:107]
	v_mfma_f32_16x16x32_bf16 v[108:111], v[80:83], v[150:153], v[108:111]
	v_mfma_f32_16x16x32_bf16 v[112:115], v[88:91], v[150:153], v[112:115]
	v_mfma_f32_16x16x32_bf16 v[116:119], v[80:83], v[158:161], v[116:119]
	v_mfma_f32_16x16x32_bf16 v[120:123], v[88:91], v[158:161], v[120:123]
	v_mfma_f32_16x16x32_bf16 v[36:39], v[80:83], v[166:169], v[36:39]
	v_mfma_f32_16x16x32_bf16 v[40:43], v[88:91], v[166:169], v[40:43]
	v_mfma_f32_16x16x32_bf16 v[44:47], v[92:95], v[136:139], v[44:47]
	v_mfma_f32_16x16x32_bf16 v[48:51], v[124:127], v[136:139], v[48:51]
	v_mfma_f32_16x16x32_bf16 v[60:63], v[92:95], v[146:149], v[60:63]
	v_mfma_f32_16x16x32_bf16 v[64:67], v[124:127], v[146:149], v[64:67]
	v_mfma_f32_16x16x32_bf16 v[68:71], v[92:95], v[154:157], v[68:71]
	v_mfma_f32_16x16x32_bf16 v[72:75], v[124:127], v[154:157], v[72:75]
	v_mfma_f32_16x16x32_bf16 v[52:55], v[92:95], v[162:165], v[52:55]
	v_mfma_f32_16x16x32_bf16 v[56:59], v[124:127], v[162:165], v[56:59]
	v_mfma_f32_16x16x32_bf16 v[44:47], v[96:99], v[140:143], v[44:47]
	v_mfma_f32_16x16x32_bf16 v[48:51], v[132:135], v[140:143], v[48:51]
	v_mfma_f32_16x16x32_bf16 v[60:63], v[96:99], v[150:153], v[60:63]
	v_mfma_f32_16x16x32_bf16 v[64:67], v[132:135], v[150:153], v[64:67]
	v_mfma_f32_16x16x32_bf16 v[68:71], v[96:99], v[158:161], v[68:71]
	v_mfma_f32_16x16x32_bf16 v[72:75], v[132:135], v[158:161], v[72:75]
	v_mfma_f32_16x16x32_bf16 v[52:55], v[96:99], v[166:169], v[52:55]
	v_mfma_f32_16x16x32_bf16 v[56:59], v[132:135], v[166:169], v[56:59]
	s_barrier
	s_mov_b32 m0, s23
	s_nop 0
	global_load_lds_dwordx4 v[32:33], off
	s_mov_b32 m0, s24
	s_nop 0
	global_load_lds_dwordx4 v[34:35], off
	s_mov_b32 m0, s21
	s_nop 0
	global_load_lds_dwordx4 v[30:31], off
	s_mov_b32 m0, s33
	s_nop 0
	global_load_lds_dwordx4 v[26:27], off
	s_mov_b32 m0, s12
	s_nop 0
	global_load_lds_dwordx4 v[24:25], off
	s_mov_b32 m0, s20
	s_nop 0
	global_load_lds_dwordx4 v[22:23], off
	s_waitcnt vmcnt(8)
	s_waitcnt lgkmcnt(0)
	s_barrier
	s_setprio 0
	s_barrier
	ds_read_b128 v[22:25], v175
	ds_read_b128 v[30:33], v175 offset:1024
	ds_read_b128 v[76:79], v175 offset:2048
	ds_read_b128 v[80:83], v175 offset:3072
	ds_read_b128 v[84:87], v174
	ds_read_b128 v[88:91], v174 offset:1024
	ds_read_b128 v[92:95], v174 offset:2048
	ds_read_b128 v[96:99], v174 offset:3072
	s_mov_b32 m0, s13
	ds_read_b128 v[124:127], v173 offset:32768
	ds_read_b128 v[130:133], v173 offset:33792
	ds_read_b128 v[134:137], v173 offset:34816
	ds_read_b128 v[138:141], v173 offset:35840
	ds_read_b128 v[146:149], v173 offset:36864
	ds_read_b128 v[150:153], v173 offset:37888
	ds_read_b128 v[154:157], v173 offset:38912
	ds_read_b128 v[158:161], v173 offset:39936
	global_load_lds_dwordx4 v[12:13], off
	s_mov_b32 m0, s15
	s_nop 0
	global_load_lds_dwordx4 v[14:15], off
	s_waitcnt vmcnt(8)
	s_waitcnt lgkmcnt(0)
	s_barrier
; #define PG8_STAGE(bufoff, gbase, voff) do { _Pragma("unroll") for (int _i = 0; _i < 2; ++_i) \
;         __builtin_amdgcn_global_load_lds((const unsigned*)((const char*)(gbase) + (voff)[_i]), (PG8_LAS unsigned*)(lds + (bufoff) + ldsw + _i * 8192), 16, 0, 0); } while (0)
; #define PG8_LDA(dst, b, h) do { _Pragma("unroll") for (int m = 0; m < 4; ++m) _Pragma("unroll") for (int k = 0; k < 2; ++k) dst[m][k] = *(const PG8_LAS bf16x8*)(lds + PG8_SA(b, h) + aoff + m * 2048 + k * 1024); } while (0)
; #define PG8_MMA(ai, bj, At, Bt) do { __builtin_amdgcn_s_setprio(1); _Pragma("unroll") for (int m = 0; m < 4; ++m) _Pragma("unroll") for (int n = 0; n < 2; ++n) _Pragma("unroll") for (int k = 0; k < 2; ++k) \
;         acc[ai][bj][m][n] = __builtin_amdgcn_mfma_f32_16x16x32_bf16(Bt[n][k], At[m][k], acc[ai][bj][m][n], 0, 0, 0); __builtin_amdgcn_s_setprio(0); } while (0)
; #define PG8_WAIT_V(n) asm volatile("s_waitcnt vmcnt(" #n ")" ::: "memory")
; #define PG8_WAIT_L(n) asm volatile("s_waitcnt lgkmcnt(" #n ")" ::: "memory")
; #define PG8_BAR __builtin_amdgcn_s_barrier()
; #define PG8_SCHED __builtin_amdgcn_sched_barrier(0)
; template <class Epi, class Sched, bool ALIGN_EPI = false, bool SP2 = false>
; __device__ __forceinline__ void gemm_phase(PG8_LAS unsigned char* lds, const Gemm g, const Sched& S, const Epi& E) {
;     ...
;             PG8_LDA(At, 1, 1); PG8_STAGE(PG8_SB(1, 0), b3, voffB); PG8_STAGE(PG8_SB(1, 1), b3 + hstep, voffB); PG8_STAGE(PG8_SA(1, 0), a3, voffA);
;             PG8_WAIT_V(8); PG8_WAIT_L(0); PG8_BAR; PG8_MMA(1, 0, At, B0); PG8_MMA(1, 1, At, B1); PG8_BAR; PG8_SCHED;
;     __device__ __forceinline__ void operator()(const f32x4 (&acc)[2][2][4][2], const Unit& u, int wr, int wc, int fr, int fq) const {
;         const int col0 = u.pn * 256 + wc * 32 + 4 * fq;
; #pragma unroll
;         for (int m = 0; m < 4; ++m) {
;             const int row = wr * 64 + m * 16 + fr;
; #pragma unroll
;             for (int bj = 0; bj < 2; ++bj)
; #pragma unroll
;                 for (int n = 0; n < 2; ++n) *(f32x4*)(O + (size_t)row * DM + col0 + bj * 128 + n * 16) = acc[0][bj][m][n];
;             asm volatile("" ::: "memory");
;         }
	s_waitcnt lgkmcnt(0)
	v_mfma_f32_16x16x32_bf16 v[12:15], v[22:25], v[124:127], v[100:103]
	v_mfma_f32_16x16x32_bf16 v[100:103], v[76:79], v[124:127], v[104:107]
	v_mfma_f32_16x16x32_bf16 v[104:107], v[22:25], v[134:137], v[108:111]
	v_mfma_f32_16x16x32_bf16 v[108:111], v[76:79], v[134:137], v[112:115]
	v_mfma_f32_16x16x32_bf16 v[112:115], v[22:25], v[146:149], v[116:119]
	v_mfma_f32_16x16x32_bf16 v[22:25], v[22:25], v[154:157], v[36:39]
	v_mfma_f32_16x16x32_bf16 v[12:15], v[30:33], v[130:133], v[12:15]
	v_mfma_f32_16x16x32_bf16 v[104:107], v[30:33], v[138:141], v[104:107]
	v_mfma_f32_16x16x32_bf16 v[112:115], v[30:33], v[150:153], v[112:115]
	v_mfma_f32_16x16x32_bf16 v[116:119], v[76:79], v[146:149], v[120:123]
	v_mfma_f32_16x16x32_bf16 v[22:25], v[30:33], v[158:161], v[22:25]
	v_mfma_f32_16x16x32_bf16 v[30:33], v[76:79], v[154:157], v[40:43]
	v_mfma_f32_16x16x32_bf16 v[100:103], v[80:83], v[130:133], v[100:103]
	v_mfma_f32_16x16x32_bf16 v[108:111], v[80:83], v[138:141], v[108:111]
	v_mfma_f32_16x16x32_bf16 v[116:119], v[80:83], v[150:153], v[116:119]
	v_mfma_f32_16x16x32_bf16 v[30:33], v[80:83], v[158:161], v[30:33]
	v_mfma_f32_16x16x32_bf16 v[34:37], v[84:87], v[124:127], v[44:47]
	v_mfma_f32_16x16x32_bf16 v[38:41], v[92:95], v[124:127], v[48:51]
	v_mfma_f32_16x16x32_bf16 v[42:45], v[84:87], v[134:137], v[60:63]
	v_mfma_f32_16x16x32_bf16 v[46:49], v[92:95], v[134:137], v[64:67]
	v_mfma_f32_16x16x32_bf16 v[60:63], v[84:87], v[146:149], v[68:71]
	v_mfma_f32_16x16x32_bf16 v[64:67], v[92:95], v[146:149], v[72:75]
	v_mfma_f32_16x16x32_bf16 v[50:53], v[84:87], v[154:157], v[52:55]
	v_mfma_f32_16x16x32_bf16 v[54:57], v[92:95], v[154:157], v[56:59]
	v_mfma_f32_16x16x32_bf16 v[34:37], v[88:91], v[130:133], v[34:37]
	v_mfma_f32_16x16x32_bf16 v[38:41], v[96:99], v[130:133], v[38:41]
	v_mfma_f32_16x16x32_bf16 v[42:45], v[88:91], v[138:141], v[42:45]
	v_mfma_f32_16x16x32_bf16 v[46:49], v[96:99], v[138:141], v[46:49]
	v_mfma_f32_16x16x32_bf16 v[60:63], v[88:91], v[150:153], v[60:63]
	v_mfma_f32_16x16x32_bf16 v[64:67], v[96:99], v[150:153], v[64:67]
	v_mfma_f32_16x16x32_bf16 v[50:53], v[88:91], v[158:161], v[50:53]
	v_mfma_f32_16x16x32_bf16 v[54:57], v[96:99], v[158:161], v[54:57]
	s_barrier
	s_mov_b32 m0, s9
	s_nop 0
	global_load_lds_dwordx4 v[4:5], off
	s_mov_b32 m0, s16
	s_nop 0
	global_load_lds_dwordx4 v[6:7], off
	s_mov_b32 m0, s18
	s_nop 0
	global_load_lds_dwordx4 v[16:17], off
	s_mov_b32 m0, s19
	s_nop 0
	global_load_lds_dwordx4 v[18:19], off
	s_mov_b32 m0, s14
	s_nop 0
	global_load_lds_dwordx4 v[2:3], off
	s_mov_b32 m0, s17
	s_nop 0
	global_load_lds_dwordx4 v[8:9], off
	s_waitcnt vmcnt(8)
	s_waitcnt lgkmcnt(0)
	s_barrier
	s_setprio 0
	s_barrier
	s_lshl_b32 s2, s11, 8
	v_lshl_or_b32 v2, v144, 2, s2
	v_or_b32_e32 v2, s8, v2
	v_lshlrev_b32_e32 v128, 2, v2
	v_lshl_add_u64 v[2:3], v[28:29], 0, v[128:129]
	global_store_dwordx4 v[2:3], v[12:15], off
	global_store_dwordx4 v[2:3], v[100:103], off offset:64
	global_store_dwordx4 v[2:3], v[34:37], off offset:512
	global_store_dwordx4 v[2:3], v[38:41], off offset:576
	v_lshl_add_u64 v[2:3], v[20:21], 0, v[128:129]
	global_store_dwordx4 v[2:3], v[104:107], off
	global_store_dwordx4 v[2:3], v[108:111], off offset:64
	global_store_dwordx4 v[2:3], v[42:45], off offset:512
	global_store_dwordx4 v[2:3], v[46:49], off offset:576
	v_lshl_add_u64 v[2:3], v[10:11], 0, v[128:129]
	global_store_dwordx4 v[2:3], v[112:115], off
	global_store_dwordx4 v[2:3], v[116:119], off offset:64
	global_store_dwordx4 v[2:3], v[60:63], off offset:512
	global_store_dwordx4 v[2:3], v[64:67], off offset:576
	v_lshl_add_u64 v[0:1], v[0:1], 0, v[128:129]
	global_store_dwordx4 v[0:1], v[22:25], off
	global_store_dwordx4 v[0:1], v[30:33], off offset:64
	global_store_dwordx4 v[0:1], v[50:53], off offset:512
	global_store_dwordx4 v[0:1], v[54:57], off offset:576
	s_waitcnt vmcnt(0)
	s_cmpk_gt_u32 s10, 0xff
	s_cbranch_scc1 .LBB0_334
	s_barrier

; #define PG8_STAGE(bufoff, gbase, voff) do { _Pragma("unroll") for (int _i = 0; _i < 2; ++_i) \
;         __builtin_amdgcn_global_load_lds((const unsigned*)((const char*)(gbase) + (voff)[_i]), (PG8_LAS unsigned*)(lds + (bufoff) + ldsw + _i * 8192), 16, 0, 0); } while (0)
; #define PG8_LDA(dst, b, h) do { _Pragma("unroll") for (int m = 0; m < 4; ++m) _Pragma("unroll") for (int k = 0; k < 2; ++k) dst[m][k] = *(const PG8_LAS bf16x8*)(lds + PG8_SA(b, h) + aoff + m * 2048 + k * 1024); } while (0)
; #define PG8_LDB(dst, b, h) do { _Pragma("unroll") for (int n = 0; n < 2; ++n) _Pragma("unroll") for (int k = 0; k < 2; ++k) dst[n][k] = *(const PG8_LAS bf16x8*)(lds + PG8_SB(b, h) + boff + n * 2048 + k * 1024); } while (0)
; #define PG8_MMA(ai, bj, At, Bt) do { __builtin_amdgcn_s_setprio(1); _Pragma("unroll") for (int m = 0; m < 4; ++m) _Pragma("unroll") for (int n = 0; n < 2; ++n) _Pragma("unroll") for (int k = 0; k < 2; ++k) \
;         acc[ai][bj][m][n] = __builtin_amdgcn_mfma_f32_16x16x32_bf16(Bt[n][k], At[m][k], acc[ai][bj][m][n], 0, 0, 0); __builtin_amdgcn_s_setprio(0); } while (0)
; #define PG8_WAIT_V(n) asm volatile("s_waitcnt vmcnt(" #n ")" ::: "memory")
; #define PG8_WAIT_L(n) asm volatile("s_waitcnt lgkmcnt(" #n ")" ::: "memory")
; #define PG8_BAR __builtin_amdgcn_s_barrier()
; #define PG8_SCHED __builtin_amdgcn_sched_barrier(0)
; template <class Epi, class Sched, bool ALIGN_EPI = false, bool SP2 = false>
; __device__ __forceinline__ void gemm_phase(PG8_LAS unsigned char* lds, const Gemm g, const Sched& S, const Epi& E) {
;     ...
;             PG8_LDB(B0, 0, 0); PG8_LDB(B1, 0, 1); PG8_SCHED; PG8_LDA(At, 0, 0); PG8_STAGE(PG8_SA(1, 1), a1 + hstep, voffA);
;             PG8_WAIT_V(8); PG8_WAIT_L(0); PG8_BAR; PG8_MMA(0, 0, At, B0); PG8_MMA(0, 1, At, B1); PG8_BAR; PG8_SCHED;
;             PG8_LDA(At, 0, 1); PG8_STAGE(PG8_SB(0, 0), b2, voffB); PG8_STAGE(PG8_SB(0, 1), b2 + hstep, voffB); PG8_STAGE(PG8_SA(0, 0), a2, voffA);
;             PG8_WAIT_V(8); PG8_WAIT_L(0); PG8_BAR; PG8_MMA(1, 0, At, B0); PG8_MMA(1, 1, At, B1); PG8_BAR; PG8_SCHED;
.LBB0_521:
	ds_read_b128 v[128:131], v169
	ds_read_b128 v[152:155], v169 offset:1024
	ds_read_b128 v[156:159], v169 offset:2048
	ds_read_b128 v[174:177], v169 offset:3072
	ds_read_b128 v[182:185], v170
	ds_read_b128 v[186:189], v170 offset:1024
	ds_read_b128 v[190:193], v170 offset:2048
	ds_read_b128 v[194:197], v170 offset:3072
	s_add_u32 s12, s10, 0xfffc0080
	s_addc_u32 s13, s11, -1
	s_cmp_eq_u32 s67, 12
	s_cselect_b32 s15, s7, s13
	s_cselect_b32 s14, s9, s12
	s_cselect_b32 s13, s55, s66
	s_cselect_b32 s12, s59, s61
	v_lshl_add_u64 v[178:179], s[10:11], 0, v[144:145]
	s_add_i32 m0, s82, 0xc000
	ds_read_b128 v[198:201], v171
	ds_read_b128 v[202:205], v171 offset:1024
	ds_read_b128 v[206:209], v171 offset:2048
	ds_read_b128 v[210:213], v171 offset:3072
	ds_read_b128 v[214:217], v171 offset:4096
	ds_read_b128 v[218:221], v171 offset:5120
	ds_read_b128 v[222:225], v171 offset:6144
	ds_read_b128 v[226:229], v171 offset:7168
	global_load_lds_dwordx4 v[178:179], off
	v_lshl_add_u64 v[178:179], s[10:11], 0, v[146:147]
	s_add_i32 m0, s82, 0xe000
	s_nop 0
	global_load_lds_dwordx4 v[178:179], off
	s_waitcnt vmcnt(8)
	s_waitcnt lgkmcnt(0)
	s_barrier
	s_waitcnt lgkmcnt(0)
	v_mfma_f32_16x16x32_bf16 v[124:127], v[128:131], v[198:201], v[124:127]
	v_mfma_f32_16x16x32_bf16 v[120:123], v[156:159], v[198:201], v[120:123]
	v_mfma_f32_16x16x32_bf16 v[108:111], v[128:131], v[206:209], v[108:111]
	v_mfma_f32_16x16x32_bf16 v[104:107], v[156:159], v[206:209], v[104:107]
	v_mfma_f32_16x16x32_bf16 v[92:95], v[128:131], v[214:217], v[92:95]
	v_mfma_f32_16x16x32_bf16 v[88:91], v[156:159], v[214:217], v[88:91]
	v_mfma_f32_16x16x32_bf16 v[76:79], v[128:131], v[222:225], v[76:79]
	v_mfma_f32_16x16x32_bf16 v[72:75], v[156:159], v[222:225], v[72:75]
	v_mfma_f32_16x16x32_bf16 v[124:127], v[152:155], v[202:205], v[124:127]
	v_mfma_f32_16x16x32_bf16 v[120:123], v[174:177], v[202:205], v[120:123]
	v_mfma_f32_16x16x32_bf16 v[108:111], v[152:155], v[210:213], v[108:111]
	v_mfma_f32_16x16x32_bf16 v[104:107], v[174:177], v[210:213], v[104:107]
	v_mfma_f32_16x16x32_bf16 v[92:95], v[152:155], v[218:221], v[92:95]
	v_mfma_f32_16x16x32_bf16 v[88:91], v[174:177], v[218:221], v[88:91]
	v_mfma_f32_16x16x32_bf16 v[76:79], v[152:155], v[226:229], v[76:79]
	v_mfma_f32_16x16x32_bf16 v[72:75], v[174:177], v[226:229], v[72:75]
	v_mfma_f32_16x16x32_bf16 v[116:119], v[182:185], v[198:201], v[116:119]
	v_mfma_f32_16x16x32_bf16 v[112:115], v[190:193], v[198:201], v[112:115]
	v_mfma_f32_16x16x32_bf16 v[100:103], v[182:185], v[206:209], v[100:103]
	v_mfma_f32_16x16x32_bf16 v[96:99], v[190:193], v[206:209], v[96:99]
	v_mfma_f32_16x16x32_bf16 v[84:87], v[182:185], v[214:217], v[84:87]
	v_mfma_f32_16x16x32_bf16 v[80:83], v[190:193], v[214:217], v[80:83]
	v_mfma_f32_16x16x32_bf16 v[68:71], v[182:185], v[222:225], v[68:71]
	v_mfma_f32_16x16x32_bf16 v[64:67], v[190:193], v[222:225], v[64:67]
	v_mfma_f32_16x16x32_bf16 v[116:119], v[186:189], v[202:205], v[116:119]
	v_mfma_f32_16x16x32_bf16 v[112:115], v[194:197], v[202:205], v[112:115]
	v_mfma_f32_16x16x32_bf16 v[100:103], v[186:189], v[210:213], v[100:103]
	v_mfma_f32_16x16x32_bf16 v[96:99], v[194:197], v[210:213], v[96:99]
	v_mfma_f32_16x16x32_bf16 v[84:87], v[186:189], v[218:221], v[84:87]
	v_mfma_f32_16x16x32_bf16 v[80:83], v[194:197], v[218:221], v[80:83]
	v_mfma_f32_16x16x32_bf16 v[68:71], v[186:189], v[226:229], v[68:71]
	v_mfma_f32_16x16x32_bf16 v[64:67], v[194:197], v[226:229], v[64:67]
	s_barrier
	s_add_i32 s68, s33, s81
	v_lshl_add_u64 v[178:179], s[12:13], 0, v[134:135]
	s_mov_b32 m0, s68
	ds_read_b128 v[198:201], v171 offset:16384
	ds_read_b128 v[202:205], v171 offset:17408
	ds_read_b128 v[206:209], v171 offset:18432
	ds_read_b128 v[210:213], v171 offset:19456
	ds_read_b128 v[214:217], v171 offset:20480
	ds_read_b128 v[218:221], v171 offset:21504
	ds_read_b128 v[222:225], v171 offset:22528
	ds_read_b128 v[226:229], v171 offset:23552
	global_load_lds_dwordx4 v[178:179], off
	s_add_i32 m0, s68, 0x2000
	s_add_u32 s68, s12, 0x40000
	v_lshl_add_u64 v[230:231], s[12:13], 0, v[138:139]
	s_addc_u32 s69, s13, 0
	s_add_i32 s70, s34, s81
	global_load_lds_dwordx4 v[230:231], off
	v_lshl_add_u64 v[232:233], s[68:69], 0, v[134:135]
	s_mov_b32 m0, s70
	v_lshl_add_u64 v[234:235], s[14:15], 0, v[136:137]
	global_load_lds_dwordx4 v[232:233], off
	v_lshl_add_u64 v[232:233], s[68:69], 0, v[138:139]
	s_add_i32 m0, s70, 0x2000
	s_nop 0
	global_load_lds_dwordx4 v[232:233], off
	v_lshl_add_u64 v[232:233], s[14:15], 0, v[132:133]
	s_mov_b32 m0, s82
	s_nop 0
	global_load_lds_dwordx4 v[232:233], off
	s_mov_b32 m0, s83
	s_nop 0
	global_load_lds_dwordx4 v[234:235], off
	s_waitcnt vmcnt(8)
	s_waitcnt lgkmcnt(0)
	s_barrier
; #define PG8_STAGE(bufoff, gbase, voff) do { _Pragma("unroll") for (int _i = 0; _i < 2; ++_i) \
;         __builtin_amdgcn_global_load_lds((const unsigned*)((const char*)(gbase) + (voff)[_i]), (PG8_LAS unsigned*)(lds + (bufoff) + ldsw + _i * 8192), 16, 0, 0); } while (0)
; #define PG8_LDA(dst, b, h) do { _Pragma("unroll") for (int m = 0; m < 4; ++m) _Pragma("unroll") for (int k = 0; k < 2; ++k) dst[m][k] = *(const PG8_LAS bf16x8*)(lds + PG8_SA(b, h) + aoff + m * 2048 + k * 1024); } while (0)
; #define PG8_LDB(dst, b, h) do { _Pragma("unroll") for (int n = 0; n < 2; ++n) _Pragma("unroll") for (int k = 0; k < 2; ++k) dst[n][k] = *(const PG8_LAS bf16x8*)(lds + PG8_SB(b, h) + boff + n * 2048 + k * 1024); } while (0)
; #define PG8_MMA(ai, bj, At, Bt) do { __builtin_amdgcn_s_setprio(1); _Pragma("unroll") for (int m = 0; m < 4; ++m) _Pragma("unroll") for (int n = 0; n < 2; ++n) _Pragma("unroll") for (int k = 0; k < 2; ++k) \
;         acc[ai][bj][m][n] = __builtin_amdgcn_mfma_f32_16x16x32_bf16(Bt[n][k], At[m][k], acc[ai][bj][m][n], 0, 0, 0); __builtin_amdgcn_s_setprio(0); } while (0)
; #define PG8_WAIT_V(n) asm volatile("s_waitcnt vmcnt(" #n ")" ::: "memory")
; #define PG8_WAIT_L(n) asm volatile("s_waitcnt lgkmcnt(" #n ")" ::: "memory")
; #define PG8_BAR __builtin_amdgcn_s_barrier()
; #define PG8_SCHED __builtin_amdgcn_sched_barrier(0)
; template <class Epi, class Sched, bool ALIGN_EPI = false, bool SP2 = false>
; __device__ __forceinline__ void gemm_phase(PG8_LAS unsigned char* lds, const Gemm g, const Sched& S, const Epi& E) {
;     ...
;             PG8_WAIT_V(8); PG8_WAIT_L(0); PG8_BAR; PG8_MMA(1, 0, At, B0); PG8_MMA(1, 1, At, B1); PG8_BAR; PG8_SCHED;
;             PG8_LDB(B0, 1, 0); PG8_LDB(B1, 1, 1); PG8_SCHED; PG8_LDA(At, 1, 0); PG8_STAGE(PG8_SA(0, 1), a2 + hstep, voffA);
;             PG8_WAIT_V(8); PG8_WAIT_L(0); PG8_BAR; PG8_MMA(0, 0, At, B0); PG8_MMA(0, 1, At, B1); PG8_BAR; PG8_SCHED;
	s_waitcnt lgkmcnt(0)
	v_mfma_f32_16x16x32_bf16 v[60:63], v[128:131], v[198:201], v[60:63]
	v_mfma_f32_16x16x32_bf16 v[56:59], v[156:159], v[198:201], v[56:59]
	v_mfma_f32_16x16x32_bf16 v[44:47], v[128:131], v[206:209], v[44:47]
	v_mfma_f32_16x16x32_bf16 v[40:43], v[156:159], v[206:209], v[40:43]
	v_mfma_f32_16x16x32_bf16 v[28:31], v[128:131], v[214:217], v[28:31]
	v_mfma_f32_16x16x32_bf16 v[24:27], v[156:159], v[214:217], v[24:27]
	v_mfma_f32_16x16x32_bf16 v[12:15], v[128:131], v[222:225], v[12:15]
	v_mfma_f32_16x16x32_bf16 v[8:11], v[156:159], v[222:225], v[8:11]
	v_mfma_f32_16x16x32_bf16 v[60:63], v[152:155], v[202:205], v[60:63]
	v_mfma_f32_16x16x32_bf16 v[56:59], v[174:177], v[202:205], v[56:59]
	v_mfma_f32_16x16x32_bf16 v[44:47], v[152:155], v[210:213], v[44:47]
	v_mfma_f32_16x16x32_bf16 v[40:43], v[174:177], v[210:213], v[40:43]
	v_mfma_f32_16x16x32_bf16 v[28:31], v[152:155], v[218:221], v[28:31]
	v_mfma_f32_16x16x32_bf16 v[24:27], v[174:177], v[218:221], v[24:27]
	v_mfma_f32_16x16x32_bf16 v[12:15], v[152:155], v[226:229], v[12:15]
	v_mfma_f32_16x16x32_bf16 v[8:11], v[174:177], v[226:229], v[8:11]
	v_mfma_f32_16x16x32_bf16 v[52:55], v[182:185], v[198:201], v[52:55]
	v_mfma_f32_16x16x32_bf16 v[48:51], v[190:193], v[198:201], v[48:51]
	v_mfma_f32_16x16x32_bf16 v[36:39], v[182:185], v[206:209], v[36:39]
	v_mfma_f32_16x16x32_bf16 v[32:35], v[190:193], v[206:209], v[32:35]
	v_mfma_f32_16x16x32_bf16 v[20:23], v[182:185], v[214:217], v[20:23]
	v_mfma_f32_16x16x32_bf16 v[16:19], v[190:193], v[214:217], v[16:19]
	v_mfma_f32_16x16x32_bf16 v[4:7], v[182:185], v[222:225], v[4:7]
	v_mfma_f32_16x16x32_bf16 v[0:3], v[190:193], v[222:225], v[0:3]
	v_mfma_f32_16x16x32_bf16 v[52:55], v[186:189], v[202:205], v[52:55]
	v_mfma_f32_16x16x32_bf16 v[48:51], v[194:197], v[202:205], v[48:51]
	v_mfma_f32_16x16x32_bf16 v[36:39], v[186:189], v[210:213], v[36:39]
	v_mfma_f32_16x16x32_bf16 v[32:35], v[194:197], v[210:213], v[32:35]
	v_mfma_f32_16x16x32_bf16 v[20:23], v[186:189], v[218:221], v[20:23]
	v_mfma_f32_16x16x32_bf16 v[16:19], v[194:197], v[218:221], v[16:19]
	v_mfma_f32_16x16x32_bf16 v[4:7], v[186:189], v[226:229], v[4:7]
	v_mfma_f32_16x16x32_bf16 v[0:3], v[194:197], v[226:229], v[0:3]
	s_barrier
	s_add_i32 s68, 0, 0x18000
	v_add_u32_e32 v140, s68, v162
	s_add_i32 s69, 0, 0x1c000
	ds_read_b128 v[128:131], v140
	ds_read_b128 v[152:155], v140 offset:1024
	ds_read_b128 v[156:159], v140 offset:2048
	ds_read_b128 v[174:177], v140 offset:3072
	v_add_u32_e32 v140, s69, v162
	ds_read_b128 v[182:185], v140
	ds_read_b128 v[186:189], v140 offset:1024
	ds_read_b128 v[190:193], v140 offset:2048
	ds_read_b128 v[194:197], v140 offset:3072
	s_add_u32 s14, s14, 0x40000
	s_addc_u32 s15, s15, 0
	s_mov_b32 m0, s84
	v_lshl_add_u64 v[236:237], s[14:15], 0, v[132:133]
	ds_read_b128 v[198:201], v171 offset:32768
	ds_read_b128 v[202:205], v171 offset:33792
	ds_read_b128 v[206:209], v171 offset:34816
	ds_read_b128 v[210:213], v171 offset:35840
	ds_read_b128 v[214:217], v171 offset:36864
	ds_read_b128 v[218:221], v171 offset:37888
	ds_read_b128 v[222:225], v171 offset:38912
	ds_read_b128 v[226:229], v171 offset:39936
	global_load_lds_dwordx4 v[236:237], off
	v_lshl_add_u64 v[236:237], s[14:15], 0, v[136:137]
	s_mov_b32 m0, s85
	s_nop 0
	global_load_lds_dwordx4 v[236:237], off
	s_waitcnt vmcnt(8)
	s_waitcnt lgkmcnt(0)
	s_barrier
	s_waitcnt lgkmcnt(0)
	v_mfma_f32_16x16x32_bf16 v[124:127], v[128:131], v[198:201], v[124:127]
	v_mfma_f32_16x16x32_bf16 v[120:123], v[156:159], v[198:201], v[120:123]
	v_mfma_f32_16x16x32_bf16 v[108:111], v[128:131], v[206:209], v[108:111]
	v_mfma_f32_16x16x32_bf16 v[104:107], v[156:159], v[206:209], v[104:107]
	v_mfma_f32_16x16x32_bf16 v[92:95], v[128:131], v[214:217], v[92:95]
	v_mfma_f32_16x16x32_bf16 v[88:91], v[156:159], v[214:217], v[88:91]
	v_mfma_f32_16x16x32_bf16 v[76:79], v[128:131], v[222:225], v[76:79]
	v_mfma_f32_16x16x32_bf16 v[72:75], v[156:159], v[222:225], v[72:75]
	v_mfma_f32_16x16x32_bf16 v[124:127], v[152:155], v[202:205], v[124:127]
	v_mfma_f32_16x16x32_bf16 v[120:123], v[174:177], v[202:205], v[120:123]
	v_mfma_f32_16x16x32_bf16 v[108:111], v[152:155], v[210:213], v[108:111]
	v_mfma_f32_16x16x32_bf16 v[104:107], v[174:177], v[210:213], v[104:107]
	v_mfma_f32_16x16x32_bf16 v[92:95], v[152:155], v[218:221], v[92:95]
	v_mfma_f32_16x16x32_bf16 v[88:91], v[174:177], v[218:221], v[88:91]
	v_mfma_f32_16x16x32_bf16 v[76:79], v[152:155], v[226:229], v[76:79]
	v_mfma_f32_16x16x32_bf16 v[72:75], v[174:177], v[226:229], v[72:75]
	v_mfma_f32_16x16x32_bf16 v[116:119], v[182:185], v[198:201], v[116:119]
	v_mfma_f32_16x16x32_bf16 v[112:115], v[190:193], v[198:201], v[112:115]
	v_mfma_f32_16x16x32_bf16 v[100:103], v[182:185], v[206:209], v[100:103]
	v_mfma_f32_16x16x32_bf16 v[96:99], v[190:193], v[206:209], v[96:99]
	v_mfma_f32_16x16x32_bf16 v[84:87], v[182:185], v[214:217], v[84:87]
	v_mfma_f32_16x16x32_bf16 v[80:83], v[190:193], v[214:217], v[80:83]
	v_mfma_f32_16x16x32_bf16 v[68:71], v[182:185], v[222:225], v[68:71]
	v_mfma_f32_16x16x32_bf16 v[64:67], v[190:193], v[222:225], v[64:67]
	v_mfma_f32_16x16x32_bf16 v[116:119], v[186:189], v[202:205], v[116:119]
	v_mfma_f32_16x16x32_bf16 v[112:115], v[194:197], v[202:205], v[112:115]
	v_mfma_f32_16x16x32_bf16 v[100:103], v[186:189], v[210:213], v[100:103]
	v_mfma_f32_16x16x32_bf16 v[96:99], v[194:197], v[210:213], v[96:99]
	v_mfma_f32_16x16x32_bf16 v[84:87], v[186:189], v[218:221], v[84:87]
	v_mfma_f32_16x16x32_bf16 v[80:83], v[194:197], v[218:221], v[80:83]
	v_mfma_f32_16x16x32_bf16 v[68:71], v[186:189], v[226:229], v[68:71]
	v_mfma_f32_16x16x32_bf16 v[64:67], v[194:197], v[226:229], v[64:67]
	s_barrier
; #define PG8_STAGE(bufoff, gbase, voff) do { _Pragma("unroll") for (int _i = 0; _i < 2; ++_i) \
;         __builtin_amdgcn_global_load_lds((const unsigned*)((const char*)(gbase) + (voff)[_i]), (PG8_LAS unsigned*)(lds + (bufoff) + ldsw + _i * 8192), 16, 0, 0); } while (0)
; #define PG8_LDA(dst, b, h) do { _Pragma("unroll") for (int m = 0; m < 4; ++m) _Pragma("unroll") for (int k = 0; k < 2; ++k) dst[m][k] = *(const PG8_LAS bf16x8*)(lds + PG8_SA(b, h) + aoff + m * 2048 + k * 1024); } while (0)
; #define PG8_MMA(ai, bj, At, Bt) do { __builtin_amdgcn_s_setprio(1); _Pragma("unroll") for (int m = 0; m < 4; ++m) _Pragma("unroll") for (int n = 0; n < 2; ++n) _Pragma("unroll") for (int k = 0; k < 2; ++k) \
;         acc[ai][bj][m][n] = __builtin_amdgcn_mfma_f32_16x16x32_bf16(Bt[n][k], At[m][k], acc[ai][bj][m][n], 0, 0, 0); __builtin_amdgcn_s_setprio(0); } while (0)
; #define PG8_WAIT_V(n) asm volatile("s_waitcnt vmcnt(" #n ")" ::: "memory")
; #define PG8_WAIT_L(n) asm volatile("s_waitcnt lgkmcnt(" #n ")" ::: "memory")
; #define PG8_BAR __builtin_amdgcn_s_barrier()
; #define PG8_SCHED __builtin_amdgcn_sched_barrier(0)
; template <class Epi, class Sched, bool ALIGN_EPI = false, bool SP2 = false>
; __device__ __forceinline__ void gemm_phase(PG8_LAS unsigned char* lds, const Gemm g, const Sched& S, const Epi& E) {
;     ...
;             PG8_LDA(At, 1, 1); PG8_STAGE(PG8_SB(1, 0), b3, voffB); PG8_STAGE(PG8_SB(1, 1), b3 + hstep, voffB); PG8_STAGE(PG8_SA(1, 0), a3, voffA);
;             PG8_WAIT_V(8); PG8_WAIT_L(0); PG8_BAR; PG8_MMA(1, 0, At, B0); PG8_MMA(1, 1, At, B1); PG8_BAR; PG8_SCHED;
	s_add_i32 s14, s68, s81
	v_lshl_add_u64 v[178:179], v[178:179], 0, s[44:45]
	s_mov_b32 m0, s14
	ds_read_b128 v[198:201], v171 offset:49152
	ds_read_b128 v[202:205], v171 offset:50176
	ds_read_b128 v[206:209], v171 offset:51200
	ds_read_b128 v[210:213], v171 offset:52224
	ds_read_b128 v[214:217], v171 offset:53248
	ds_read_b128 v[218:221], v171 offset:54272
	ds_read_b128 v[222:225], v171 offset:55296
	ds_read_b128 v[226:229], v171 offset:56320
	global_load_lds_dwordx4 v[178:179], off
	s_add_i32 m0, s14, 0x2000
	s_add_u32 s12, s12, 0x40080
	v_lshl_add_u64 v[178:179], v[230:231], 0, s[44:45]
	s_addc_u32 s13, s13, 0
	s_add_i32 s14, s69, s81
	global_load_lds_dwordx4 v[178:179], off
	v_lshl_add_u64 v[178:179], s[12:13], 0, v[134:135]
	s_mov_b32 m0, s14
	s_nop 0
	global_load_lds_dwordx4 v[178:179], off
	v_lshl_add_u64 v[178:179], s[12:13], 0, v[138:139]
	s_add_i32 m0, s14, 0x2000
	s_nop 0
	global_load_lds_dwordx4 v[178:179], off
	v_lshl_add_u64 v[178:179], v[232:233], 0, s[44:45]
	s_mov_b32 m0, s89
	s_nop 0
	global_load_lds_dwordx4 v[178:179], off
	v_lshl_add_u64 v[178:179], v[234:235], 0, s[44:45]
	s_mov_b32 m0, s90
	s_nop 0
	global_load_lds_dwordx4 v[178:179], off
	s_waitcnt vmcnt(8)
	s_waitcnt lgkmcnt(0)
	s_barrier
	s_waitcnt lgkmcnt(0)
	v_mfma_f32_16x16x32_bf16 v[60:63], v[128:131], v[198:201], v[60:63]
	v_mfma_f32_16x16x32_bf16 v[56:59], v[156:159], v[198:201], v[56:59]
	v_mfma_f32_16x16x32_bf16 v[44:47], v[128:131], v[206:209], v[44:47]
	v_mfma_f32_16x16x32_bf16 v[40:43], v[156:159], v[206:209], v[40:43]
	v_mfma_f32_16x16x32_bf16 v[28:31], v[128:131], v[214:217], v[28:31]
	v_mfma_f32_16x16x32_bf16 v[24:27], v[156:159], v[214:217], v[24:27]
	v_mfma_f32_16x16x32_bf16 v[12:15], v[128:131], v[222:225], v[12:15]
	v_mfma_f32_16x16x32_bf16 v[8:11], v[156:159], v[222:225], v[8:11]
	v_mfma_f32_16x16x32_bf16 v[60:63], v[152:155], v[202:205], v[60:63]
	v_mfma_f32_16x16x32_bf16 v[56:59], v[174:177], v[202:205], v[56:59]
	v_mfma_f32_16x16x32_bf16 v[44:47], v[152:155], v[210:213], v[44:47]
	v_mfma_f32_16x16x32_bf16 v[40:43], v[174:177], v[210:213], v[40:43]
	v_mfma_f32_16x16x32_bf16 v[28:31], v[152:155], v[218:221], v[28:31]
	v_mfma_f32_16x16x32_bf16 v[24:27], v[174:177], v[218:221], v[24:27]
	v_mfma_f32_16x16x32_bf16 v[12:15], v[152:155], v[226:229], v[12:15]
	v_mfma_f32_16x16x32_bf16 v[8:11], v[174:177], v[226:229], v[8:11]
	v_mfma_f32_16x16x32_bf16 v[52:55], v[182:185], v[198:201], v[52:55]
	v_mfma_f32_16x16x32_bf16 v[48:51], v[190:193], v[198:201], v[48:51]
	v_mfma_f32_16x16x32_bf16 v[36:39], v[182:185], v[206:209], v[36:39]
	v_mfma_f32_16x16x32_bf16 v[32:35], v[190:193], v[206:209], v[32:35]
	v_mfma_f32_16x16x32_bf16 v[20:23], v[182:185], v[214:217], v[20:23]
	v_mfma_f32_16x16x32_bf16 v[16:19], v[190:193], v[214:217], v[16:19]
	v_mfma_f32_16x16x32_bf16 v[4:7], v[182:185], v[222:225], v[4:7]
	v_mfma_f32_16x16x32_bf16 v[0:3], v[190:193], v[222:225], v[0:3]
	v_mfma_f32_16x16x32_bf16 v[52:55], v[186:189], v[202:205], v[52:55]
	v_mfma_f32_16x16x32_bf16 v[48:51], v[194:197], v[202:205], v[48:51]
	v_mfma_f32_16x16x32_bf16 v[36:39], v[186:189], v[210:213], v[36:39]
	v_mfma_f32_16x16x32_bf16 v[32:35], v[194:197], v[210:213], v[32:35]
	v_mfma_f32_16x16x32_bf16 v[20:23], v[186:189], v[218:221], v[20:23]
	v_mfma_f32_16x16x32_bf16 v[16:19], v[194:197], v[218:221], v[16:19]
	v_mfma_f32_16x16x32_bf16 v[4:7], v[186:189], v[226:229], v[4:7]
	v_mfma_f32_16x16x32_bf16 v[0:3], v[194:197], v[226:229], v[0:3]
	s_barrier
	s_add_i32 s67, s67, 2
	s_add_u32 s10, s10, 0x100
	s_addc_u32 s11, s11, 0
	s_add_u32 s61, s61, 0x100
	s_addc_u32 s66, s66, 0
	s_cmp_gt_u32 s67, 13
	s_cbranch_scc0 .LBB0_521
	s_and_b64 vcc, exec, s[46:47]
	s_cbranch_vccz .LBB0_524
	s_barrier

; #define PG8_STAGE(bufoff, gbase, voff) do { _Pragma("unroll") for (int _i = 0; _i < 2; ++_i) \
;         __builtin_amdgcn_global_load_lds((const unsigned*)((const char*)(gbase) + (voff)[_i]), (PG8_LAS unsigned*)(lds + (bufoff) + ldsw + _i * 8192), 16, 0, 0); } while (0)
; #define PG8_LDA(dst, b, h) do { _Pragma("unroll") for (int m = 0; m < 4; ++m) _Pragma("unroll") for (int k = 0; k < 2; ++k) dst[m][k] = *(const PG8_LAS bf16x8*)(lds + PG8_SA(b, h) + aoff + m * 2048 + k * 1024); } while (0)
; #define PG8_LDB(dst, b, h) do { _Pragma("unroll") for (int n = 0; n < 2; ++n) _Pragma("unroll") for (int k = 0; k < 2; ++k) dst[n][k] = *(const PG8_LAS bf16x8*)(lds + PG8_SB(b, h) + boff + n * 2048 + k * 1024); } while (0)
; #define PG8_MMA(ai, bj, At, Bt) do { __builtin_amdgcn_s_setprio(1); _Pragma("unroll") for (int m = 0; m < 4; ++m) _Pragma("unroll") for (int n = 0; n < 2; ++n) _Pragma("unroll") for (int k = 0; k < 2; ++k) \
;         acc[ai][bj][m][n] = __builtin_amdgcn_mfma_f32_16x16x32_bf16(Bt[n][k], At[m][k], acc[ai][bj][m][n], 0, 0, 0); __builtin_amdgcn_s_setprio(0); } while (0)
; #define PG8_WAIT_V(n) asm volatile("s_waitcnt vmcnt(" #n ")" ::: "memory")
; #define PG8_WAIT_L(n) asm volatile("s_waitcnt lgkmcnt(" #n ")" ::: "memory")
; #define PG8_BAR __builtin_amdgcn_s_barrier()
; #define PG8_SCHED __builtin_amdgcn_sched_barrier(0)
; template <class Epi, class Sched, bool ALIGN_EPI = false, bool SP2 = false>
; __device__ __forceinline__ void gemm_phase(PG8_LAS unsigned char* lds, const Gemm g, const Sched& S, const Epi& E) {
;     ...
;             PG8_LDB(B0, 0, 0); PG8_LDB(B1, 0, 1); PG8_SCHED; PG8_LDA(At, 0, 0); PG8_STAGE(PG8_SA(1, 1), a1 + hstep, voffA);
;             PG8_WAIT_V(8); PG8_WAIT_L(0); PG8_BAR; PG8_MMA(0, 0, At, B0); PG8_MMA(0, 1, At, B1); PG8_BAR; PG8_SCHED;
;             PG8_LDA(At, 0, 1); PG8_STAGE(PG8_SB(0, 0), b2, voffB); PG8_STAGE(PG8_SB(0, 1), b2 + hstep, voffB); PG8_STAGE(PG8_SA(0, 0), a2, voffA);
;             PG8_WAIT_V(8); PG8_WAIT_L(0); PG8_BAR; PG8_MMA(1, 0, At, B0); PG8_MMA(1, 1, At, B1); PG8_BAR; PG8_SCHED;
.LBB0_1846:
	ds_read_b128 v[144:147], v151
	ds_read_b128 v[154:157], v151 offset:1024
	ds_read_b128 v[158:161], v151 offset:2048
	ds_read_b128 v[162:165], v151 offset:3072
	ds_read_b128 v[166:169], v152
	ds_read_b128 v[170:173], v152 offset:1024
	ds_read_b128 v[174:177], v152 offset:2048
	ds_read_b128 v[182:185], v152 offset:3072
	s_add_u32 s44, s42, 0xfffe0080
	s_addc_u32 s45, s43, -1
	s_cmp_eq_u32 s63, 4
	s_cselect_b32 s47, s19, s45
	s_cselect_b32 s46, s25, s44
	s_cselect_b32 s45, s17, s62
	s_cselect_b32 s44, s60, s61
	v_lshl_add_u64 v[178:179], s[42:43], 0, v[136:137]
	s_add_i32 m0, s27, 0xc000
	ds_read_b128 v[186:189], v153
	ds_read_b128 v[190:193], v153 offset:1024
	ds_read_b128 v[194:197], v153 offset:2048
	ds_read_b128 v[198:201], v153 offset:3072
	ds_read_b128 v[202:205], v153 offset:4096
	ds_read_b128 v[206:209], v153 offset:5120
	ds_read_b128 v[210:213], v153 offset:6144
	ds_read_b128 v[214:217], v153 offset:7168
	global_load_lds_dwordx4 v[178:179], off
	v_lshl_add_u64 v[178:179], s[42:43], 0, v[138:139]
	s_add_i32 m0, s27, 0xe000
	s_nop 0
	global_load_lds_dwordx4 v[178:179], off
	s_waitcnt vmcnt(8)
	s_waitcnt lgkmcnt(0)
	s_barrier
	s_waitcnt lgkmcnt(0)
	v_mfma_f32_16x16x32_bf16 v[124:127], v[144:147], v[186:189], v[124:127]
	v_mfma_f32_16x16x32_bf16 v[120:123], v[158:161], v[186:189], v[120:123]
	v_mfma_f32_16x16x32_bf16 v[108:111], v[144:147], v[194:197], v[108:111]
	v_mfma_f32_16x16x32_bf16 v[104:107], v[158:161], v[194:197], v[104:107]
	v_mfma_f32_16x16x32_bf16 v[92:95], v[144:147], v[202:205], v[92:95]
	v_mfma_f32_16x16x32_bf16 v[88:91], v[158:161], v[202:205], v[88:91]
	v_mfma_f32_16x16x32_bf16 v[76:79], v[144:147], v[210:213], v[76:79]
	v_mfma_f32_16x16x32_bf16 v[72:75], v[158:161], v[210:213], v[72:75]
	v_mfma_f32_16x16x32_bf16 v[124:127], v[154:157], v[190:193], v[124:127]
	v_mfma_f32_16x16x32_bf16 v[120:123], v[162:165], v[190:193], v[120:123]
	v_mfma_f32_16x16x32_bf16 v[108:111], v[154:157], v[198:201], v[108:111]
	v_mfma_f32_16x16x32_bf16 v[104:107], v[162:165], v[198:201], v[104:107]
	v_mfma_f32_16x16x32_bf16 v[92:95], v[154:157], v[206:209], v[92:95]
	v_mfma_f32_16x16x32_bf16 v[88:91], v[162:165], v[206:209], v[88:91]
	v_mfma_f32_16x16x32_bf16 v[76:79], v[154:157], v[214:217], v[76:79]
	v_mfma_f32_16x16x32_bf16 v[72:75], v[162:165], v[214:217], v[72:75]
	v_mfma_f32_16x16x32_bf16 v[116:119], v[166:169], v[186:189], v[116:119]
	v_mfma_f32_16x16x32_bf16 v[112:115], v[174:177], v[186:189], v[112:115]
	v_mfma_f32_16x16x32_bf16 v[100:103], v[166:169], v[194:197], v[100:103]
	v_mfma_f32_16x16x32_bf16 v[96:99], v[174:177], v[194:197], v[96:99]
	v_mfma_f32_16x16x32_bf16 v[84:87], v[166:169], v[202:205], v[84:87]
	v_mfma_f32_16x16x32_bf16 v[80:83], v[174:177], v[202:205], v[80:83]
	v_mfma_f32_16x16x32_bf16 v[68:71], v[166:169], v[210:213], v[68:71]
	v_mfma_f32_16x16x32_bf16 v[64:67], v[174:177], v[210:213], v[64:67]
	v_mfma_f32_16x16x32_bf16 v[116:119], v[170:173], v[190:193], v[116:119]
	v_mfma_f32_16x16x32_bf16 v[112:115], v[182:185], v[190:193], v[112:115]
	v_mfma_f32_16x16x32_bf16 v[100:103], v[170:173], v[198:201], v[100:103]
	v_mfma_f32_16x16x32_bf16 v[96:99], v[182:185], v[198:201], v[96:99]
	v_mfma_f32_16x16x32_bf16 v[84:87], v[170:173], v[206:209], v[84:87]
	v_mfma_f32_16x16x32_bf16 v[80:83], v[182:185], v[206:209], v[80:83]
	v_mfma_f32_16x16x32_bf16 v[68:71], v[170:173], v[214:217], v[68:71]
	v_mfma_f32_16x16x32_bf16 v[64:67], v[182:185], v[214:217], v[64:67]
	s_barrier
	s_add_i32 s64, s57, s50
	v_lshl_add_u64 v[178:179], s[44:45], 0, v[130:131]
	s_mov_b32 m0, s64
	ds_read_b128 v[186:189], v153 offset:16384
	ds_read_b128 v[190:193], v153 offset:17408
	ds_read_b128 v[194:197], v153 offset:18432
	ds_read_b128 v[198:201], v153 offset:19456
	ds_read_b128 v[202:205], v153 offset:20480
	ds_read_b128 v[206:209], v153 offset:21504
	ds_read_b128 v[210:213], v153 offset:22528
	ds_read_b128 v[214:217], v153 offset:23552
	global_load_lds_dwordx4 v[178:179], off
	s_add_i32 m0, s64, 0x2000
	s_add_u32 s64, s44, 0x20000
	v_lshl_add_u64 v[218:219], s[44:45], 0, v[134:135]
	s_addc_u32 s65, s45, 0
	s_add_i32 s66, s58, s50
	global_load_lds_dwordx4 v[218:219], off
	v_lshl_add_u64 v[220:221], s[64:65], 0, v[130:131]
	s_mov_b32 m0, s66
	v_lshl_add_u64 v[222:223], s[46:47], 0, v[132:133]
	global_load_lds_dwordx4 v[220:221], off
	v_lshl_add_u64 v[220:221], s[64:65], 0, v[134:135]
	s_add_i32 m0, s66, 0x2000
	s_nop 0
	global_load_lds_dwordx4 v[220:221], off
	v_lshl_add_u64 v[220:221], s[46:47], 0, v[128:129]
	s_mov_b32 m0, s27
	s_nop 0
	global_load_lds_dwordx4 v[220:221], off
	s_mov_b32 m0, s51
	s_nop 0
	global_load_lds_dwordx4 v[222:223], off
	s_waitcnt vmcnt(8)
	s_waitcnt lgkmcnt(0)
	s_barrier
; #define PG8_STAGE(bufoff, gbase, voff) do { _Pragma("unroll") for (int _i = 0; _i < 2; ++_i) \
;         __builtin_amdgcn_global_load_lds((const unsigned*)((const char*)(gbase) + (voff)[_i]), (PG8_LAS unsigned*)(lds + (bufoff) + ldsw + _i * 8192), 16, 0, 0); } while (0)
; #define PG8_LDA(dst, b, h) do { _Pragma("unroll") for (int m = 0; m < 4; ++m) _Pragma("unroll") for (int k = 0; k < 2; ++k) dst[m][k] = *(const PG8_LAS bf16x8*)(lds + PG8_SA(b, h) + aoff + m * 2048 + k * 1024); } while (0)
; #define PG8_LDB(dst, b, h) do { _Pragma("unroll") for (int n = 0; n < 2; ++n) _Pragma("unroll") for (int k = 0; k < 2; ++k) dst[n][k] = *(const PG8_LAS bf16x8*)(lds + PG8_SB(b, h) + boff + n * 2048 + k * 1024); } while (0)
; #define PG8_MMA(ai, bj, At, Bt) do { __builtin_amdgcn_s_setprio(1); _Pragma("unroll") for (int m = 0; m < 4; ++m) _Pragma("unroll") for (int n = 0; n < 2; ++n) _Pragma("unroll") for (int k = 0; k < 2; ++k) \
;         acc[ai][bj][m][n] = __builtin_amdgcn_mfma_f32_16x16x32_bf16(Bt[n][k], At[m][k], acc[ai][bj][m][n], 0, 0, 0); __builtin_amdgcn_s_setprio(0); } while (0)
; #define PG8_WAIT_V(n) asm volatile("s_waitcnt vmcnt(" #n ")" ::: "memory")
; #define PG8_WAIT_L(n) asm volatile("s_waitcnt lgkmcnt(" #n ")" ::: "memory")
; #define PG8_BAR __builtin_amdgcn_s_barrier()
; #define PG8_SCHED __builtin_amdgcn_sched_barrier(0)
; template <class Epi, class Sched, bool ALIGN_EPI = false, bool SP2 = false>
; __device__ __forceinline__ void gemm_phase(PG8_LAS unsigned char* lds, const Gemm g, const Sched& S, const Epi& E) {
;     ...
;             PG8_WAIT_V(8); PG8_WAIT_L(0); PG8_BAR; PG8_MMA(1, 0, At, B0); PG8_MMA(1, 1, At, B1); PG8_BAR; PG8_SCHED;
;             PG8_LDB(B0, 1, 0); PG8_LDB(B1, 1, 1); PG8_SCHED; PG8_LDA(At, 1, 0); PG8_STAGE(PG8_SA(0, 1), a2 + hstep, voffA);
;             PG8_WAIT_V(8); PG8_WAIT_L(0); PG8_BAR; PG8_MMA(0, 0, At, B0); PG8_MMA(0, 1, At, B1); PG8_BAR; PG8_SCHED;
	s_waitcnt lgkmcnt(0)
	v_mfma_f32_16x16x32_bf16 v[60:63], v[144:147], v[186:189], v[60:63]
	v_mfma_f32_16x16x32_bf16 v[56:59], v[158:161], v[186:189], v[56:59]
	v_mfma_f32_16x16x32_bf16 v[44:47], v[144:147], v[194:197], v[44:47]
	v_mfma_f32_16x16x32_bf16 v[40:43], v[158:161], v[194:197], v[40:43]
	v_mfma_f32_16x16x32_bf16 v[28:31], v[144:147], v[202:205], v[28:31]
	v_mfma_f32_16x16x32_bf16 v[24:27], v[158:161], v[202:205], v[24:27]
	v_mfma_f32_16x16x32_bf16 v[12:15], v[144:147], v[210:213], v[12:15]
	v_mfma_f32_16x16x32_bf16 v[8:11], v[158:161], v[210:213], v[8:11]
	v_mfma_f32_16x16x32_bf16 v[60:63], v[154:157], v[190:193], v[60:63]
	v_mfma_f32_16x16x32_bf16 v[56:59], v[162:165], v[190:193], v[56:59]
	v_mfma_f32_16x16x32_bf16 v[44:47], v[154:157], v[198:201], v[44:47]
	v_mfma_f32_16x16x32_bf16 v[40:43], v[162:165], v[198:201], v[40:43]
	v_mfma_f32_16x16x32_bf16 v[28:31], v[154:157], v[206:209], v[28:31]
	v_mfma_f32_16x16x32_bf16 v[24:27], v[162:165], v[206:209], v[24:27]
	v_mfma_f32_16x16x32_bf16 v[12:15], v[154:157], v[214:217], v[12:15]
	v_mfma_f32_16x16x32_bf16 v[8:11], v[162:165], v[214:217], v[8:11]
	v_mfma_f32_16x16x32_bf16 v[52:55], v[166:169], v[186:189], v[52:55]
	v_mfma_f32_16x16x32_bf16 v[48:51], v[174:177], v[186:189], v[48:51]
	v_mfma_f32_16x16x32_bf16 v[36:39], v[166:169], v[194:197], v[36:39]
	v_mfma_f32_16x16x32_bf16 v[32:35], v[174:177], v[194:197], v[32:35]
	v_mfma_f32_16x16x32_bf16 v[20:23], v[166:169], v[202:205], v[20:23]
	v_mfma_f32_16x16x32_bf16 v[16:19], v[174:177], v[202:205], v[16:19]
	v_mfma_f32_16x16x32_bf16 v[4:7], v[166:169], v[210:213], v[4:7]
	v_mfma_f32_16x16x32_bf16 v[0:3], v[174:177], v[210:213], v[0:3]
	v_mfma_f32_16x16x32_bf16 v[52:55], v[170:173], v[190:193], v[52:55]
	v_mfma_f32_16x16x32_bf16 v[48:51], v[182:185], v[190:193], v[48:51]
	v_mfma_f32_16x16x32_bf16 v[36:39], v[170:173], v[198:201], v[36:39]
	v_mfma_f32_16x16x32_bf16 v[32:35], v[182:185], v[198:201], v[32:35]
	v_mfma_f32_16x16x32_bf16 v[20:23], v[170:173], v[206:209], v[20:23]
	v_mfma_f32_16x16x32_bf16 v[16:19], v[182:185], v[206:209], v[16:19]
	v_mfma_f32_16x16x32_bf16 v[4:7], v[170:173], v[214:217], v[4:7]
	v_mfma_f32_16x16x32_bf16 v[0:3], v[182:185], v[214:217], v[0:3]
	s_barrier
	s_add_i32 s64, 0, 0x18000
	s_add_i32 s65, 0, 0x1c000
	v_add_u32_e32 v162, s64, v149
	v_add_u32_e32 v181, s65, v149
	ds_read_b128 v[144:147], v162
	ds_read_b128 v[154:157], v162 offset:1024
	ds_read_b128 v[158:161], v162 offset:2048
	ds_read_b128 v[162:165], v162 offset:3072
	ds_read_b128 v[166:169], v181
	ds_read_b128 v[170:173], v181 offset:1024
	ds_read_b128 v[174:177], v181 offset:2048
	ds_read_b128 v[182:185], v181 offset:3072
	s_add_u32 s46, s46, 0x20000
	s_addc_u32 s47, s47, 0
	s_mov_b32 m0, s52
	v_lshl_add_u64 v[224:225], s[46:47], 0, v[128:129]
	ds_read_b128 v[186:189], v153 offset:32768
	ds_read_b128 v[190:193], v153 offset:33792
	ds_read_b128 v[194:197], v153 offset:34816
	ds_read_b128 v[198:201], v153 offset:35840
	ds_read_b128 v[202:205], v153 offset:36864
	ds_read_b128 v[206:209], v153 offset:37888
	ds_read_b128 v[210:213], v153 offset:38912
	ds_read_b128 v[214:217], v153 offset:39936
	global_load_lds_dwordx4 v[224:225], off
	v_lshl_add_u64 v[224:225], s[46:47], 0, v[132:133]
	s_mov_b32 m0, s53
	s_nop 0
	global_load_lds_dwordx4 v[224:225], off
	s_waitcnt vmcnt(8)
	s_waitcnt lgkmcnt(0)
	s_barrier
	s_waitcnt lgkmcnt(0)
	v_mfma_f32_16x16x32_bf16 v[124:127], v[144:147], v[186:189], v[124:127]
	v_mfma_f32_16x16x32_bf16 v[120:123], v[158:161], v[186:189], v[120:123]
	v_mfma_f32_16x16x32_bf16 v[108:111], v[144:147], v[194:197], v[108:111]
	v_mfma_f32_16x16x32_bf16 v[104:107], v[158:161], v[194:197], v[104:107]
	v_mfma_f32_16x16x32_bf16 v[92:95], v[144:147], v[202:205], v[92:95]
	v_mfma_f32_16x16x32_bf16 v[88:91], v[158:161], v[202:205], v[88:91]
	v_mfma_f32_16x16x32_bf16 v[76:79], v[144:147], v[210:213], v[76:79]
	v_mfma_f32_16x16x32_bf16 v[72:75], v[158:161], v[210:213], v[72:75]
	v_mfma_f32_16x16x32_bf16 v[124:127], v[154:157], v[190:193], v[124:127]
	v_mfma_f32_16x16x32_bf16 v[120:123], v[162:165], v[190:193], v[120:123]
	v_mfma_f32_16x16x32_bf16 v[108:111], v[154:157], v[198:201], v[108:111]
	v_mfma_f32_16x16x32_bf16 v[104:107], v[162:165], v[198:201], v[104:107]
	v_mfma_f32_16x16x32_bf16 v[92:95], v[154:157], v[206:209], v[92:95]
	v_mfma_f32_16x16x32_bf16 v[88:91], v[162:165], v[206:209], v[88:91]
	v_mfma_f32_16x16x32_bf16 v[76:79], v[154:157], v[214:217], v[76:79]
	v_mfma_f32_16x16x32_bf16 v[72:75], v[162:165], v[214:217], v[72:75]
	v_mfma_f32_16x16x32_bf16 v[116:119], v[166:169], v[186:189], v[116:119]
	v_mfma_f32_16x16x32_bf16 v[112:115], v[174:177], v[186:189], v[112:115]
	v_mfma_f32_16x16x32_bf16 v[100:103], v[166:169], v[194:197], v[100:103]
	v_mfma_f32_16x16x32_bf16 v[96:99], v[174:177], v[194:197], v[96:99]
	v_mfma_f32_16x16x32_bf16 v[84:87], v[166:169], v[202:205], v[84:87]
	v_mfma_f32_16x16x32_bf16 v[80:83], v[174:177], v[202:205], v[80:83]
	v_mfma_f32_16x16x32_bf16 v[68:71], v[166:169], v[210:213], v[68:71]
	v_mfma_f32_16x16x32_bf16 v[64:67], v[174:177], v[210:213], v[64:67]
	v_mfma_f32_16x16x32_bf16 v[116:119], v[170:173], v[190:193], v[116:119]
	v_mfma_f32_16x16x32_bf16 v[112:115], v[182:185], v[190:193], v[112:115]
	v_mfma_f32_16x16x32_bf16 v[100:103], v[170:173], v[198:201], v[100:103]
	v_mfma_f32_16x16x32_bf16 v[96:99], v[182:185], v[198:201], v[96:99]
	v_mfma_f32_16x16x32_bf16 v[84:87], v[170:173], v[206:209], v[84:87]
	v_mfma_f32_16x16x32_bf16 v[80:83], v[182:185], v[206:209], v[80:83]
	v_mfma_f32_16x16x32_bf16 v[68:71], v[170:173], v[214:217], v[68:71]
	v_mfma_f32_16x16x32_bf16 v[64:67], v[182:185], v[214:217], v[64:67]
	s_barrier
; #define PG8_STAGE(bufoff, gbase, voff) do { _Pragma("unroll") for (int _i = 0; _i < 2; ++_i) \
;         __builtin_amdgcn_global_load_lds((const unsigned*)((const char*)(gbase) + (voff)[_i]), (PG8_LAS unsigned*)(lds + (bufoff) + ldsw + _i * 8192), 16, 0, 0); } while (0)
; #define PG8_LDA(dst, b, h) do { _Pragma("unroll") for (int m = 0; m < 4; ++m) _Pragma("unroll") for (int k = 0; k < 2; ++k) dst[m][k] = *(const PG8_LAS bf16x8*)(lds + PG8_SA(b, h) + aoff + m * 2048 + k * 1024); } while (0)
; #define PG8_MMA(ai, bj, At, Bt) do { __builtin_amdgcn_s_setprio(1); _Pragma("unroll") for (int m = 0; m < 4; ++m) _Pragma("unroll") for (int n = 0; n < 2; ++n) _Pragma("unroll") for (int k = 0; k < 2; ++k) \
;         acc[ai][bj][m][n] = __builtin_amdgcn_mfma_f32_16x16x32_bf16(Bt[n][k], At[m][k], acc[ai][bj][m][n], 0, 0, 0); __builtin_amdgcn_s_setprio(0); } while (0)
; #define PG8_WAIT_V(n) asm volatile("s_waitcnt vmcnt(" #n ")" ::: "memory")
; #define PG8_WAIT_L(n) asm volatile("s_waitcnt lgkmcnt(" #n ")" ::: "memory")
; #define PG8_BAR __builtin_amdgcn_s_barrier()
; #define PG8_SCHED __builtin_amdgcn_sched_barrier(0)
; template <class Epi, class Sched, bool ALIGN_EPI = false, bool SP2 = false>
; __device__ __forceinline__ void gemm_phase(PG8_LAS unsigned char* lds, const Gemm g, const Sched& S, const Epi& E) {
;     ...
;             PG8_LDA(At, 1, 1); PG8_STAGE(PG8_SB(1, 0), b3, voffB); PG8_STAGE(PG8_SB(1, 1), b3 + hstep, voffB); PG8_STAGE(PG8_SA(1, 0), a3, voffA);
;             PG8_WAIT_V(8); PG8_WAIT_L(0); PG8_BAR; PG8_MMA(1, 0, At, B0); PG8_MMA(1, 1, At, B1); PG8_BAR; PG8_SCHED;
	s_add_i32 s46, s64, s50
	v_lshl_add_u64 v[178:179], v[178:179], 0, s[12:13]
	s_mov_b32 m0, s46
	ds_read_b128 v[186:189], v153 offset:49152
	ds_read_b128 v[190:193], v153 offset:50176
	ds_read_b128 v[194:197], v153 offset:51200
	ds_read_b128 v[198:201], v153 offset:52224
	ds_read_b128 v[202:205], v153 offset:53248
	ds_read_b128 v[206:209], v153 offset:54272
	ds_read_b128 v[210:213], v153 offset:55296
	ds_read_b128 v[214:217], v153 offset:56320
	global_load_lds_dwordx4 v[178:179], off
	s_add_i32 m0, s46, 0x2000
	s_add_u32 s44, s44, 0x20080
	v_lshl_add_u64 v[178:179], v[218:219], 0, s[12:13]
	s_addc_u32 s45, s45, 0
	s_add_i32 s46, s65, s50
	global_load_lds_dwordx4 v[178:179], off
	v_lshl_add_u64 v[178:179], s[44:45], 0, v[130:131]
	s_mov_b32 m0, s46
	s_nop 0
	global_load_lds_dwordx4 v[178:179], off
	v_lshl_add_u64 v[178:179], s[44:45], 0, v[134:135]
	s_add_i32 m0, s46, 0x2000
	s_nop 0
	global_load_lds_dwordx4 v[178:179], off
	v_lshl_add_u64 v[178:179], v[220:221], 0, s[12:13]
	s_mov_b32 m0, s54
	s_nop 0
	global_load_lds_dwordx4 v[178:179], off
	v_lshl_add_u64 v[178:179], v[222:223], 0, s[12:13]
	s_mov_b32 m0, s55
	s_nop 0
	global_load_lds_dwordx4 v[178:179], off
	s_waitcnt vmcnt(8)
	s_waitcnt lgkmcnt(0)
	s_barrier
	s_waitcnt lgkmcnt(0)
	v_mfma_f32_16x16x32_bf16 v[60:63], v[144:147], v[186:189], v[60:63]
	v_mfma_f32_16x16x32_bf16 v[56:59], v[158:161], v[186:189], v[56:59]
	v_mfma_f32_16x16x32_bf16 v[44:47], v[144:147], v[194:197], v[44:47]
	v_mfma_f32_16x16x32_bf16 v[40:43], v[158:161], v[194:197], v[40:43]
	v_mfma_f32_16x16x32_bf16 v[28:31], v[144:147], v[202:205], v[28:31]
	v_mfma_f32_16x16x32_bf16 v[24:27], v[158:161], v[202:205], v[24:27]
	v_mfma_f32_16x16x32_bf16 v[12:15], v[144:147], v[210:213], v[12:15]
	v_mfma_f32_16x16x32_bf16 v[8:11], v[158:161], v[210:213], v[8:11]
	v_mfma_f32_16x16x32_bf16 v[60:63], v[154:157], v[190:193], v[60:63]
	v_mfma_f32_16x16x32_bf16 v[56:59], v[162:165], v[190:193], v[56:59]
	v_mfma_f32_16x16x32_bf16 v[44:47], v[154:157], v[198:201], v[44:47]
	v_mfma_f32_16x16x32_bf16 v[40:43], v[162:165], v[198:201], v[40:43]
	v_mfma_f32_16x16x32_bf16 v[28:31], v[154:157], v[206:209], v[28:31]
	v_mfma_f32_16x16x32_bf16 v[24:27], v[162:165], v[206:209], v[24:27]
	v_mfma_f32_16x16x32_bf16 v[12:15], v[154:157], v[214:217], v[12:15]
	v_mfma_f32_16x16x32_bf16 v[8:11], v[162:165], v[214:217], v[8:11]
	v_mfma_f32_16x16x32_bf16 v[52:55], v[166:169], v[186:189], v[52:55]
	v_mfma_f32_16x16x32_bf16 v[48:51], v[174:177], v[186:189], v[48:51]
	v_mfma_f32_16x16x32_bf16 v[36:39], v[166:169], v[194:197], v[36:39]
	v_mfma_f32_16x16x32_bf16 v[32:35], v[174:177], v[194:197], v[32:35]
	v_mfma_f32_16x16x32_bf16 v[20:23], v[166:169], v[202:205], v[20:23]
	v_mfma_f32_16x16x32_bf16 v[16:19], v[174:177], v[202:205], v[16:19]
	v_mfma_f32_16x16x32_bf16 v[4:7], v[166:169], v[210:213], v[4:7]
	v_mfma_f32_16x16x32_bf16 v[0:3], v[174:177], v[210:213], v[0:3]
	v_mfma_f32_16x16x32_bf16 v[52:55], v[170:173], v[190:193], v[52:55]
	v_mfma_f32_16x16x32_bf16 v[48:51], v[182:185], v[190:193], v[48:51]
	v_mfma_f32_16x16x32_bf16 v[36:39], v[170:173], v[198:201], v[36:39]
	v_mfma_f32_16x16x32_bf16 v[32:35], v[182:185], v[198:201], v[32:35]
	v_mfma_f32_16x16x32_bf16 v[20:23], v[170:173], v[206:209], v[20:23]
	v_mfma_f32_16x16x32_bf16 v[16:19], v[182:185], v[206:209], v[16:19]
	v_mfma_f32_16x16x32_bf16 v[4:7], v[170:173], v[214:217], v[4:7]
	v_mfma_f32_16x16x32_bf16 v[0:3], v[182:185], v[214:217], v[0:3]
	s_barrier
	s_add_i32 s63, s63, 2
	s_add_u32 s42, s42, 0x100
	s_addc_u32 s43, s43, 0
	s_add_u32 s61, s61, 0x100
	s_addc_u32 s62, s62, 0
	s_cmp_gt_u32 s63, 5
	s_cbranch_scc0 .LBB0_1846
	s_and_b64 vcc, exec, s[14:15]
	s_cbranch_vccz .LBB0_1849
	s_barrier

; #define PG8_STAGE(bufoff, gbase, voff) do { _Pragma("unroll") for (int _i = 0; _i < 2; ++_i) \
;         __builtin_amdgcn_global_load_lds((const unsigned*)((const char*)(gbase) + (voff)[_i]), (PG8_LAS unsigned*)(lds + (bufoff) + ldsw + _i * 8192), 16, 0, 0); } while (0)
; #define PG8_LDA(dst, b, h) do { _Pragma("unroll") for (int m = 0; m < 4; ++m) _Pragma("unroll") for (int k = 0; k < 2; ++k) dst[m][k] = *(const PG8_LAS bf16x8*)(lds + PG8_SA(b, h) + aoff + m * 2048 + k * 1024); } while (0)
; #define PG8_LDB(dst, b, h) do { _Pragma("unroll") for (int n = 0; n < 2; ++n) _Pragma("unroll") for (int k = 0; k < 2; ++k) dst[n][k] = *(const PG8_LAS bf16x8*)(lds + PG8_SB(b, h) + boff + n * 2048 + k * 1024); } while (0)
; #define PG8_MMA(ai, bj, At, Bt) do { __builtin_amdgcn_s_setprio(1); _Pragma("unroll") for (int m = 0; m < 4; ++m) _Pragma("unroll") for (int n = 0; n < 2; ++n) _Pragma("unroll") for (int k = 0; k < 2; ++k) \
;         acc[ai][bj][m][n] = __builtin_amdgcn_mfma_f32_16x16x32_bf16(Bt[n][k], At[m][k], acc[ai][bj][m][n], 0, 0, 0); __builtin_amdgcn_s_setprio(0); } while (0)
; #define PG8_WAIT_V(n) asm volatile("s_waitcnt vmcnt(" #n ")" ::: "memory")
; #define PG8_WAIT_L(n) asm volatile("s_waitcnt lgkmcnt(" #n ")" ::: "memory")
; #define PG8_BAR __builtin_amdgcn_s_barrier()
; #define PG8_SCHED __builtin_amdgcn_sched_barrier(0)
; template <class Epi, class Sched, bool ALIGN_EPI = false, bool SP2 = false>
; __device__ __forceinline__ void gemm_phase(PG8_LAS unsigned char* lds, const Gemm g, const Sched& S, const Epi& E) {
;     ...
;             PG8_LDB(B0, 0, 0); PG8_LDB(B1, 0, 1); PG8_SCHED; PG8_LDA(At, 0, 0); PG8_STAGE(PG8_SA(1, 1), a1 + hstep, voffA);
;             PG8_WAIT_V(8); PG8_WAIT_L(0); PG8_BAR; PG8_MMA(0, 0, At, B0); PG8_MMA(0, 1, At, B1); PG8_BAR; PG8_SCHED;
;             PG8_LDA(At, 0, 1); PG8_STAGE(PG8_SB(0, 0), b2, voffB); PG8_STAGE(PG8_SB(0, 1), b2 + hstep, voffB); PG8_STAGE(PG8_SA(0, 0), a2, voffA);
;             PG8_WAIT_V(8); PG8_WAIT_L(0); PG8_BAR; PG8_MMA(1, 0, At, B0); PG8_MMA(1, 1, At, B1); PG8_BAR; PG8_SCHED;
.LBB0_2025:
	ds_read_b128 v[144:147], v151
	ds_read_b128 v[154:157], v151 offset:1024
	ds_read_b128 v[158:161], v151 offset:2048
	ds_read_b128 v[162:165], v151 offset:3072
	ds_read_b128 v[166:169], v152
	ds_read_b128 v[170:173], v152 offset:1024
	ds_read_b128 v[174:177], v152 offset:2048
	ds_read_b128 v[182:185], v152 offset:3072
	s_add_u32 s44, s42, 0xfffe0080
	s_addc_u32 s45, s43, -1
	s_cmp_eq_u32 s65, 4
	s_cselect_b32 s47, s21, s45
	s_cselect_b32 s46, s27, s44
	s_cselect_b32 s45, s19, s64
	s_cselect_b32 s44, s62, s63
	v_lshl_add_u64 v[178:179], s[42:43], 0, v[136:137]
	s_add_i32 m0, s41, 0xc000
	ds_read_b128 v[186:189], v153
	ds_read_b128 v[190:193], v153 offset:1024
	ds_read_b128 v[194:197], v153 offset:2048
	ds_read_b128 v[198:201], v153 offset:3072
	ds_read_b128 v[202:205], v153 offset:4096
	ds_read_b128 v[206:209], v153 offset:5120
	ds_read_b128 v[210:213], v153 offset:6144
	ds_read_b128 v[214:217], v153 offset:7168
	global_load_lds_dwordx4 v[178:179], off
	v_lshl_add_u64 v[178:179], s[42:43], 0, v[138:139]
	s_add_i32 m0, s41, 0xe000
	s_nop 0
	global_load_lds_dwordx4 v[178:179], off
	s_waitcnt vmcnt(8)
	s_waitcnt lgkmcnt(0)
	s_barrier
	s_waitcnt lgkmcnt(0)
	v_mfma_f32_16x16x32_bf16 v[124:127], v[144:147], v[186:189], v[124:127]
	v_mfma_f32_16x16x32_bf16 v[120:123], v[158:161], v[186:189], v[120:123]
	v_mfma_f32_16x16x32_bf16 v[108:111], v[144:147], v[194:197], v[108:111]
	v_mfma_f32_16x16x32_bf16 v[104:107], v[158:161], v[194:197], v[104:107]
	v_mfma_f32_16x16x32_bf16 v[92:95], v[144:147], v[202:205], v[92:95]
	v_mfma_f32_16x16x32_bf16 v[88:91], v[158:161], v[202:205], v[88:91]
	v_mfma_f32_16x16x32_bf16 v[76:79], v[144:147], v[210:213], v[76:79]
	v_mfma_f32_16x16x32_bf16 v[72:75], v[158:161], v[210:213], v[72:75]
	v_mfma_f32_16x16x32_bf16 v[124:127], v[154:157], v[190:193], v[124:127]
	v_mfma_f32_16x16x32_bf16 v[120:123], v[162:165], v[190:193], v[120:123]
	v_mfma_f32_16x16x32_bf16 v[108:111], v[154:157], v[198:201], v[108:111]
	v_mfma_f32_16x16x32_bf16 v[104:107], v[162:165], v[198:201], v[104:107]
	v_mfma_f32_16x16x32_bf16 v[92:95], v[154:157], v[206:209], v[92:95]
	v_mfma_f32_16x16x32_bf16 v[88:91], v[162:165], v[206:209], v[88:91]
	v_mfma_f32_16x16x32_bf16 v[76:79], v[154:157], v[214:217], v[76:79]
	v_mfma_f32_16x16x32_bf16 v[72:75], v[162:165], v[214:217], v[72:75]
	v_mfma_f32_16x16x32_bf16 v[116:119], v[166:169], v[186:189], v[116:119]
	v_mfma_f32_16x16x32_bf16 v[112:115], v[174:177], v[186:189], v[112:115]
	v_mfma_f32_16x16x32_bf16 v[100:103], v[166:169], v[194:197], v[100:103]
	v_mfma_f32_16x16x32_bf16 v[96:99], v[174:177], v[194:197], v[96:99]
	v_mfma_f32_16x16x32_bf16 v[84:87], v[166:169], v[202:205], v[84:87]
	v_mfma_f32_16x16x32_bf16 v[80:83], v[174:177], v[202:205], v[80:83]
	v_mfma_f32_16x16x32_bf16 v[68:71], v[166:169], v[210:213], v[68:71]
	v_mfma_f32_16x16x32_bf16 v[64:67], v[174:177], v[210:213], v[64:67]
	v_mfma_f32_16x16x32_bf16 v[116:119], v[170:173], v[190:193], v[116:119]
	v_mfma_f32_16x16x32_bf16 v[112:115], v[182:185], v[190:193], v[112:115]
	v_mfma_f32_16x16x32_bf16 v[100:103], v[170:173], v[198:201], v[100:103]
	v_mfma_f32_16x16x32_bf16 v[96:99], v[182:185], v[198:201], v[96:99]
	v_mfma_f32_16x16x32_bf16 v[84:87], v[170:173], v[206:209], v[84:87]
	v_mfma_f32_16x16x32_bf16 v[80:83], v[182:185], v[206:209], v[80:83]
	v_mfma_f32_16x16x32_bf16 v[68:71], v[170:173], v[214:217], v[68:71]
	v_mfma_f32_16x16x32_bf16 v[64:67], v[182:185], v[214:217], v[64:67]
	s_barrier
	s_add_i32 s66, s59, s49
	v_lshl_add_u64 v[178:179], s[44:45], 0, v[130:131]
	s_mov_b32 m0, s66
	ds_read_b128 v[186:189], v153 offset:16384
	ds_read_b128 v[190:193], v153 offset:17408
	ds_read_b128 v[194:197], v153 offset:18432
	ds_read_b128 v[198:201], v153 offset:19456
	ds_read_b128 v[202:205], v153 offset:20480
	ds_read_b128 v[206:209], v153 offset:21504
	ds_read_b128 v[210:213], v153 offset:22528
	ds_read_b128 v[214:217], v153 offset:23552
	global_load_lds_dwordx4 v[178:179], off
	s_add_i32 m0, s66, 0x2000
	s_add_u32 s66, s44, 0x20000
	v_lshl_add_u64 v[218:219], s[44:45], 0, v[134:135]
	s_addc_u32 s67, s45, 0
	s_add_i32 s68, s60, s49
	global_load_lds_dwordx4 v[218:219], off
	v_lshl_add_u64 v[220:221], s[66:67], 0, v[130:131]
	s_mov_b32 m0, s68
	v_lshl_add_u64 v[222:223], s[46:47], 0, v[132:133]
	global_load_lds_dwordx4 v[220:221], off
	v_lshl_add_u64 v[220:221], s[66:67], 0, v[134:135]
	s_add_i32 m0, s68, 0x2000
	s_nop 0
	global_load_lds_dwordx4 v[220:221], off
	v_lshl_add_u64 v[220:221], s[46:47], 0, v[128:129]
	s_mov_b32 m0, s41
	s_nop 0
	global_load_lds_dwordx4 v[220:221], off
	s_mov_b32 m0, s50
	s_nop 0
	global_load_lds_dwordx4 v[222:223], off
	s_waitcnt vmcnt(8)
	s_waitcnt lgkmcnt(0)
	s_barrier
; #define PG8_STAGE(bufoff, gbase, voff) do { _Pragma("unroll") for (int _i = 0; _i < 2; ++_i) \
;         __builtin_amdgcn_global_load_lds((const unsigned*)((const char*)(gbase) + (voff)[_i]), (PG8_LAS unsigned*)(lds + (bufoff) + ldsw + _i * 8192), 16, 0, 0); } while (0)
; #define PG8_LDA(dst, b, h) do { _Pragma("unroll") for (int m = 0; m < 4; ++m) _Pragma("unroll") for (int k = 0; k < 2; ++k) dst[m][k] = *(const PG8_LAS bf16x8*)(lds + PG8_SA(b, h) + aoff + m * 2048 + k * 1024); } while (0)
; #define PG8_LDB(dst, b, h) do { _Pragma("unroll") for (int n = 0; n < 2; ++n) _Pragma("unroll") for (int k = 0; k < 2; ++k) dst[n][k] = *(const PG8_LAS bf16x8*)(lds + PG8_SB(b, h) + boff + n * 2048 + k * 1024); } while (0)
; #define PG8_MMA(ai, bj, At, Bt) do { __builtin_amdgcn_s_setprio(1); _Pragma("unroll") for (int m = 0; m < 4; ++m) _Pragma("unroll") for (int n = 0; n < 2; ++n) _Pragma("unroll") for (int k = 0; k < 2; ++k) \
;         acc[ai][bj][m][n] = __builtin_amdgcn_mfma_f32_16x16x32_bf16(Bt[n][k], At[m][k], acc[ai][bj][m][n], 0, 0, 0); __builtin_amdgcn_s_setprio(0); } while (0)
; #define PG8_WAIT_V(n) asm volatile("s_waitcnt vmcnt(" #n ")" ::: "memory")
; #define PG8_WAIT_L(n) asm volatile("s_waitcnt lgkmcnt(" #n ")" ::: "memory")
; #define PG8_BAR __builtin_amdgcn_s_barrier()
; #define PG8_SCHED __builtin_amdgcn_sched_barrier(0)
; template <class Epi, class Sched, bool ALIGN_EPI = false, bool SP2 = false>
; __device__ __forceinline__ void gemm_phase(PG8_LAS unsigned char* lds, const Gemm g, const Sched& S, const Epi& E) {
;     ...
;             PG8_WAIT_V(8); PG8_WAIT_L(0); PG8_BAR; PG8_MMA(1, 0, At, B0); PG8_MMA(1, 1, At, B1); PG8_BAR; PG8_SCHED;
;             PG8_LDB(B0, 1, 0); PG8_LDB(B1, 1, 1); PG8_SCHED; PG8_LDA(At, 1, 0); PG8_STAGE(PG8_SA(0, 1), a2 + hstep, voffA);
;             PG8_WAIT_V(8); PG8_WAIT_L(0); PG8_BAR; PG8_MMA(0, 0, At, B0); PG8_MMA(0, 1, At, B1); PG8_BAR; PG8_SCHED;
	s_waitcnt lgkmcnt(0)
	v_mfma_f32_16x16x32_bf16 v[60:63], v[144:147], v[186:189], v[60:63]
	v_mfma_f32_16x16x32_bf16 v[56:59], v[158:161], v[186:189], v[56:59]
	v_mfma_f32_16x16x32_bf16 v[44:47], v[144:147], v[194:197], v[44:47]
	v_mfma_f32_16x16x32_bf16 v[40:43], v[158:161], v[194:197], v[40:43]
	v_mfma_f32_16x16x32_bf16 v[28:31], v[144:147], v[202:205], v[28:31]
	v_mfma_f32_16x16x32_bf16 v[24:27], v[158:161], v[202:205], v[24:27]
	v_mfma_f32_16x16x32_bf16 v[12:15], v[144:147], v[210:213], v[12:15]
	v_mfma_f32_16x16x32_bf16 v[8:11], v[158:161], v[210:213], v[8:11]
	v_mfma_f32_16x16x32_bf16 v[60:63], v[154:157], v[190:193], v[60:63]
	v_mfma_f32_16x16x32_bf16 v[56:59], v[162:165], v[190:193], v[56:59]
	v_mfma_f32_16x16x32_bf16 v[44:47], v[154:157], v[198:201], v[44:47]
	v_mfma_f32_16x16x32_bf16 v[40:43], v[162:165], v[198:201], v[40:43]
	v_mfma_f32_16x16x32_bf16 v[28:31], v[154:157], v[206:209], v[28:31]
	v_mfma_f32_16x16x32_bf16 v[24:27], v[162:165], v[206:209], v[24:27]
	v_mfma_f32_16x16x32_bf16 v[12:15], v[154:157], v[214:217], v[12:15]
	v_mfma_f32_16x16x32_bf16 v[8:11], v[162:165], v[214:217], v[8:11]
	v_mfma_f32_16x16x32_bf16 v[52:55], v[166:169], v[186:189], v[52:55]
	v_mfma_f32_16x16x32_bf16 v[48:51], v[174:177], v[186:189], v[48:51]
	v_mfma_f32_16x16x32_bf16 v[36:39], v[166:169], v[194:197], v[36:39]
	v_mfma_f32_16x16x32_bf16 v[32:35], v[174:177], v[194:197], v[32:35]
	v_mfma_f32_16x16x32_bf16 v[20:23], v[166:169], v[202:205], v[20:23]
	v_mfma_f32_16x16x32_bf16 v[16:19], v[174:177], v[202:205], v[16:19]
	v_mfma_f32_16x16x32_bf16 v[4:7], v[166:169], v[210:213], v[4:7]
	v_mfma_f32_16x16x32_bf16 v[0:3], v[174:177], v[210:213], v[0:3]
	v_mfma_f32_16x16x32_bf16 v[52:55], v[170:173], v[190:193], v[52:55]
	v_mfma_f32_16x16x32_bf16 v[48:51], v[182:185], v[190:193], v[48:51]
	v_mfma_f32_16x16x32_bf16 v[36:39], v[170:173], v[198:201], v[36:39]
	v_mfma_f32_16x16x32_bf16 v[32:35], v[182:185], v[198:201], v[32:35]
	v_mfma_f32_16x16x32_bf16 v[20:23], v[170:173], v[206:209], v[20:23]
	v_mfma_f32_16x16x32_bf16 v[16:19], v[182:185], v[206:209], v[16:19]
	v_mfma_f32_16x16x32_bf16 v[4:7], v[170:173], v[214:217], v[4:7]
	v_mfma_f32_16x16x32_bf16 v[0:3], v[182:185], v[214:217], v[0:3]
	s_barrier
	s_add_i32 s66, 0, 0x18000
	s_add_i32 s67, 0, 0x1c000
	v_add_u32_e32 v162, s66, v149
	v_add_u32_e32 v181, s67, v149
	ds_read_b128 v[144:147], v162
	ds_read_b128 v[154:157], v162 offset:1024
	ds_read_b128 v[158:161], v162 offset:2048
	ds_read_b128 v[162:165], v162 offset:3072
	ds_read_b128 v[166:169], v181
	ds_read_b128 v[170:173], v181 offset:1024
	ds_read_b128 v[174:177], v181 offset:2048
	ds_read_b128 v[182:185], v181 offset:3072
	s_add_u32 s46, s46, 0x20000
	s_addc_u32 s47, s47, 0
	s_mov_b32 m0, s51
	v_lshl_add_u64 v[224:225], s[46:47], 0, v[128:129]
	ds_read_b128 v[186:189], v153 offset:32768
	ds_read_b128 v[190:193], v153 offset:33792
	ds_read_b128 v[194:197], v153 offset:34816
	ds_read_b128 v[198:201], v153 offset:35840
	ds_read_b128 v[202:205], v153 offset:36864
	ds_read_b128 v[206:209], v153 offset:37888
	ds_read_b128 v[210:213], v153 offset:38912
	ds_read_b128 v[214:217], v153 offset:39936
	global_load_lds_dwordx4 v[224:225], off
	v_lshl_add_u64 v[224:225], s[46:47], 0, v[132:133]
	s_mov_b32 m0, s52
	s_nop 0
	global_load_lds_dwordx4 v[224:225], off
	s_waitcnt vmcnt(8)
	s_waitcnt lgkmcnt(0)
	s_barrier
	s_waitcnt lgkmcnt(0)
	v_mfma_f32_16x16x32_bf16 v[124:127], v[144:147], v[186:189], v[124:127]
	v_mfma_f32_16x16x32_bf16 v[120:123], v[158:161], v[186:189], v[120:123]
	v_mfma_f32_16x16x32_bf16 v[108:111], v[144:147], v[194:197], v[108:111]
	v_mfma_f32_16x16x32_bf16 v[104:107], v[158:161], v[194:197], v[104:107]
	v_mfma_f32_16x16x32_bf16 v[92:95], v[144:147], v[202:205], v[92:95]
	v_mfma_f32_16x16x32_bf16 v[88:91], v[158:161], v[202:205], v[88:91]
	v_mfma_f32_16x16x32_bf16 v[76:79], v[144:147], v[210:213], v[76:79]
	v_mfma_f32_16x16x32_bf16 v[72:75], v[158:161], v[210:213], v[72:75]
	v_mfma_f32_16x16x32_bf16 v[124:127], v[154:157], v[190:193], v[124:127]
	v_mfma_f32_16x16x32_bf16 v[120:123], v[162:165], v[190:193], v[120:123]
	v_mfma_f32_16x16x32_bf16 v[108:111], v[154:157], v[198:201], v[108:111]
	v_mfma_f32_16x16x32_bf16 v[104:107], v[162:165], v[198:201], v[104:107]
	v_mfma_f32_16x16x32_bf16 v[92:95], v[154:157], v[206:209], v[92:95]
	v_mfma_f32_16x16x32_bf16 v[88:91], v[162:165], v[206:209], v[88:91]
	v_mfma_f32_16x16x32_bf16 v[76:79], v[154:157], v[214:217], v[76:79]
	v_mfma_f32_16x16x32_bf16 v[72:75], v[162:165], v[214:217], v[72:75]
	v_mfma_f32_16x16x32_bf16 v[116:119], v[166:169], v[186:189], v[116:119]
	v_mfma_f32_16x16x32_bf16 v[112:115], v[174:177], v[186:189], v[112:115]
	v_mfma_f32_16x16x32_bf16 v[100:103], v[166:169], v[194:197], v[100:103]
	v_mfma_f32_16x16x32_bf16 v[96:99], v[174:177], v[194:197], v[96:99]
	v_mfma_f32_16x16x32_bf16 v[84:87], v[166:169], v[202:205], v[84:87]
	v_mfma_f32_16x16x32_bf16 v[80:83], v[174:177], v[202:205], v[80:83]
	v_mfma_f32_16x16x32_bf16 v[68:71], v[166:169], v[210:213], v[68:71]
	v_mfma_f32_16x16x32_bf16 v[64:67], v[174:177], v[210:213], v[64:67]
	v_mfma_f32_16x16x32_bf16 v[116:119], v[170:173], v[190:193], v[116:119]
	v_mfma_f32_16x16x32_bf16 v[112:115], v[182:185], v[190:193], v[112:115]
	v_mfma_f32_16x16x32_bf16 v[100:103], v[170:173], v[198:201], v[100:103]
	v_mfma_f32_16x16x32_bf16 v[96:99], v[182:185], v[198:201], v[96:99]
	v_mfma_f32_16x16x32_bf16 v[84:87], v[170:173], v[206:209], v[84:87]
	v_mfma_f32_16x16x32_bf16 v[80:83], v[182:185], v[206:209], v[80:83]
	v_mfma_f32_16x16x32_bf16 v[68:71], v[170:173], v[214:217], v[68:71]
	v_mfma_f32_16x16x32_bf16 v[64:67], v[182:185], v[214:217], v[64:67]
	s_barrier
; #define PG8_STAGE(bufoff, gbase, voff) do { _Pragma("unroll") for (int _i = 0; _i < 2; ++_i) \
;         __builtin_amdgcn_global_load_lds((const unsigned*)((const char*)(gbase) + (voff)[_i]), (PG8_LAS unsigned*)(lds + (bufoff) + ldsw + _i * 8192), 16, 0, 0); } while (0)
; #define PG8_LDA(dst, b, h) do { _Pragma("unroll") for (int m = 0; m < 4; ++m) _Pragma("unroll") for (int k = 0; k < 2; ++k) dst[m][k] = *(const PG8_LAS bf16x8*)(lds + PG8_SA(b, h) + aoff + m * 2048 + k * 1024); } while (0)
; #define PG8_MMA(ai, bj, At, Bt) do { __builtin_amdgcn_s_setprio(1); _Pragma("unroll") for (int m = 0; m < 4; ++m) _Pragma("unroll") for (int n = 0; n < 2; ++n) _Pragma("unroll") for (int k = 0; k < 2; ++k) \
;         acc[ai][bj][m][n] = __builtin_amdgcn_mfma_f32_16x16x32_bf16(Bt[n][k], At[m][k], acc[ai][bj][m][n], 0, 0, 0); __builtin_amdgcn_s_setprio(0); } while (0)
; #define PG8_WAIT_V(n) asm volatile("s_waitcnt vmcnt(" #n ")" ::: "memory")
; #define PG8_WAIT_L(n) asm volatile("s_waitcnt lgkmcnt(" #n ")" ::: "memory")
; #define PG8_BAR __builtin_amdgcn_s_barrier()
; #define PG8_SCHED __builtin_amdgcn_sched_barrier(0)
; template <class Epi, class Sched, bool ALIGN_EPI = false, bool SP2 = false>
; __device__ __forceinline__ void gemm_phase(PG8_LAS unsigned char* lds, const Gemm g, const Sched& S, const Epi& E) {
;     ...
;             PG8_LDA(At, 1, 1); PG8_STAGE(PG8_SB(1, 0), b3, voffB); PG8_STAGE(PG8_SB(1, 1), b3 + hstep, voffB); PG8_STAGE(PG8_SA(1, 0), a3, voffA);
;             PG8_WAIT_V(8); PG8_WAIT_L(0); PG8_BAR; PG8_MMA(1, 0, At, B0); PG8_MMA(1, 1, At, B1); PG8_BAR; PG8_SCHED;
	s_add_i32 s46, s66, s49
	v_lshl_add_u64 v[178:179], v[178:179], 0, s[14:15]
	s_mov_b32 m0, s46
	ds_read_b128 v[186:189], v153 offset:49152
	ds_read_b128 v[190:193], v153 offset:50176
	ds_read_b128 v[194:197], v153 offset:51200
	ds_read_b128 v[198:201], v153 offset:52224
	ds_read_b128 v[202:205], v153 offset:53248
	ds_read_b128 v[206:209], v153 offset:54272
	ds_read_b128 v[210:213], v153 offset:55296
	ds_read_b128 v[214:217], v153 offset:56320
	global_load_lds_dwordx4 v[178:179], off
	s_add_i32 m0, s46, 0x2000
	s_add_u32 s44, s44, 0x20080
	v_lshl_add_u64 v[178:179], v[218:219], 0, s[14:15]
	s_addc_u32 s45, s45, 0
	s_add_i32 s46, s67, s49
	global_load_lds_dwordx4 v[178:179], off
	v_lshl_add_u64 v[178:179], s[44:45], 0, v[130:131]
	s_mov_b32 m0, s46
	s_nop 0
	global_load_lds_dwordx4 v[178:179], off
	v_lshl_add_u64 v[178:179], s[44:45], 0, v[134:135]
	s_add_i32 m0, s46, 0x2000
	s_nop 0
	global_load_lds_dwordx4 v[178:179], off
	v_lshl_add_u64 v[178:179], v[220:221], 0, s[14:15]
	s_mov_b32 m0, s54
	s_nop 0
	global_load_lds_dwordx4 v[178:179], off
	v_lshl_add_u64 v[178:179], v[222:223], 0, s[14:15]
	s_mov_b32 m0, s55
	s_nop 0
	global_load_lds_dwordx4 v[178:179], off
	s_waitcnt vmcnt(8)
	s_waitcnt lgkmcnt(0)
	s_barrier
	s_waitcnt lgkmcnt(0)
	v_mfma_f32_16x16x32_bf16 v[60:63], v[144:147], v[186:189], v[60:63]
	v_mfma_f32_16x16x32_bf16 v[56:59], v[158:161], v[186:189], v[56:59]
	v_mfma_f32_16x16x32_bf16 v[44:47], v[144:147], v[194:197], v[44:47]
	v_mfma_f32_16x16x32_bf16 v[40:43], v[158:161], v[194:197], v[40:43]
	v_mfma_f32_16x16x32_bf16 v[28:31], v[144:147], v[202:205], v[28:31]
	v_mfma_f32_16x16x32_bf16 v[24:27], v[158:161], v[202:205], v[24:27]
	v_mfma_f32_16x16x32_bf16 v[12:15], v[144:147], v[210:213], v[12:15]
	v_mfma_f32_16x16x32_bf16 v[8:11], v[158:161], v[210:213], v[8:11]
	v_mfma_f32_16x16x32_bf16 v[60:63], v[154:157], v[190:193], v[60:63]
	v_mfma_f32_16x16x32_bf16 v[56:59], v[162:165], v[190:193], v[56:59]
	v_mfma_f32_16x16x32_bf16 v[44:47], v[154:157], v[198:201], v[44:47]
	v_mfma_f32_16x16x32_bf16 v[40:43], v[162:165], v[198:201], v[40:43]
	v_mfma_f32_16x16x32_bf16 v[28:31], v[154:157], v[206:209], v[28:31]
	v_mfma_f32_16x16x32_bf16 v[24:27], v[162:165], v[206:209], v[24:27]
	v_mfma_f32_16x16x32_bf16 v[12:15], v[154:157], v[214:217], v[12:15]
	v_mfma_f32_16x16x32_bf16 v[8:11], v[162:165], v[214:217], v[8:11]
	v_mfma_f32_16x16x32_bf16 v[52:55], v[166:169], v[186:189], v[52:55]
	v_mfma_f32_16x16x32_bf16 v[48:51], v[174:177], v[186:189], v[48:51]
	v_mfma_f32_16x16x32_bf16 v[36:39], v[166:169], v[194:197], v[36:39]
	v_mfma_f32_16x16x32_bf16 v[32:35], v[174:177], v[194:197], v[32:35]
	v_mfma_f32_16x16x32_bf16 v[20:23], v[166:169], v[202:205], v[20:23]
	v_mfma_f32_16x16x32_bf16 v[16:19], v[174:177], v[202:205], v[16:19]
	v_mfma_f32_16x16x32_bf16 v[4:7], v[166:169], v[210:213], v[4:7]
	v_mfma_f32_16x16x32_bf16 v[0:3], v[174:177], v[210:213], v[0:3]
	v_mfma_f32_16x16x32_bf16 v[52:55], v[170:173], v[190:193], v[52:55]
	v_mfma_f32_16x16x32_bf16 v[48:51], v[182:185], v[190:193], v[48:51]
	v_mfma_f32_16x16x32_bf16 v[36:39], v[170:173], v[198:201], v[36:39]
	v_mfma_f32_16x16x32_bf16 v[32:35], v[182:185], v[198:201], v[32:35]
	v_mfma_f32_16x16x32_bf16 v[20:23], v[170:173], v[206:209], v[20:23]
	v_mfma_f32_16x16x32_bf16 v[16:19], v[182:185], v[206:209], v[16:19]
	v_mfma_f32_16x16x32_bf16 v[4:7], v[170:173], v[214:217], v[4:7]
	v_mfma_f32_16x16x32_bf16 v[0:3], v[182:185], v[214:217], v[0:3]
	s_barrier
	s_add_i32 s65, s65, 2
	s_add_u32 s42, s42, 0x100
	s_addc_u32 s43, s43, 0
	s_add_u32 s63, s63, 0x100
	s_addc_u32 s64, s64, 0
	s_cmp_gt_u32 s65, 5
	s_cbranch_scc0 .LBB0_2025
	s_and_b64 vcc, exec, s[16:17]
	s_cbranch_vccz .LBB0_2028
	s_barrier

; #define PG8_STAGE(bufoff, gbase, voff) do { _Pragma("unroll") for (int _i = 0; _i < 2; ++_i) \
;         __builtin_amdgcn_global_load_lds((const unsigned*)((const char*)(gbase) + (voff)[_i]), (PG8_LAS unsigned*)(lds + (bufoff) + ldsw + _i * 8192), 16, 0, 0); } while (0)
; #define PG8_LDA(dst, b, h) do { _Pragma("unroll") for (int m = 0; m < 4; ++m) _Pragma("unroll") for (int k = 0; k < 2; ++k) dst[m][k] = *(const PG8_LAS bf16x8*)(lds + PG8_SA(b, h) + aoff + m * 2048 + k * 1024); } while (0)
; #define PG8_LDB(dst, b, h) do { _Pragma("unroll") for (int n = 0; n < 2; ++n) _Pragma("unroll") for (int k = 0; k < 2; ++k) dst[n][k] = *(const PG8_LAS bf16x8*)(lds + PG8_SB(b, h) + boff + n * 2048 + k * 1024); } while (0)
; #define PG8_MMA(ai, bj, At, Bt) do { __builtin_amdgcn_s_setprio(1); _Pragma("unroll") for (int m = 0; m < 4; ++m) _Pragma("unroll") for (int n = 0; n < 2; ++n) _Pragma("unroll") for (int k = 0; k < 2; ++k) \
;         acc[ai][bj][m][n] = __builtin_amdgcn_mfma_f32_16x16x32_bf16(Bt[n][k], At[m][k], acc[ai][bj][m][n], 0, 0, 0); __builtin_amdgcn_s_setprio(0); } while (0)
; #define PG8_WAIT_V(n) asm volatile("s_waitcnt vmcnt(" #n ")" ::: "memory")
; #define PG8_WAIT_L(n) asm volatile("s_waitcnt lgkmcnt(" #n ")" ::: "memory")
; #define PG8_BAR __builtin_amdgcn_s_barrier()
; #define PG8_SCHED __builtin_amdgcn_sched_barrier(0)
; template <class Epi, class Sched, bool ALIGN_EPI = false, bool SP2 = false>
; __device__ __forceinline__ void gemm_phase(PG8_LAS unsigned char* lds, const Gemm g, const Sched& S, const Epi& E) {
;     ...
;             PG8_LDB(B0, 0, 0); PG8_LDB(B1, 0, 1); PG8_SCHED; PG8_LDA(At, 0, 0); PG8_STAGE(PG8_SA(1, 1), a1 + hstep, voffA);
;             PG8_WAIT_V(8); PG8_WAIT_L(0); PG8_BAR; PG8_MMA(0, 0, At, B0); PG8_MMA(0, 1, At, B1); PG8_BAR; PG8_SCHED;
;             PG8_LDA(At, 0, 1); PG8_STAGE(PG8_SB(0, 0), b2, voffB); PG8_STAGE(PG8_SB(0, 1), b2 + hstep, voffB); PG8_STAGE(PG8_SA(0, 0), a2, voffA);
;             PG8_WAIT_V(8); PG8_WAIT_L(0); PG8_BAR; PG8_MMA(1, 0, At, B0); PG8_MMA(1, 1, At, B1); PG8_BAR; PG8_SCHED;
.LBB0_2122:
	ds_read_b128 v[140:143], v151
	ds_read_b128 v[154:157], v151 offset:1024
	ds_read_b128 v[158:161], v151 offset:2048
	ds_read_b128 v[162:165], v151 offset:3072
	ds_read_b128 v[166:169], v152
	ds_read_b128 v[170:173], v152 offset:1024
	ds_read_b128 v[174:177], v152 offset:2048
	ds_read_b128 v[182:185], v152 offset:3072
	s_add_u32 s40, s26, 0xfffc0080
	s_addc_u32 s41, s27, -1
	s_cmp_eq_u32 s61, 12
	s_cselect_b32 s43, s15, s41
	s_cselect_b32 s42, s21, s40
	s_cselect_b32 s41, s19, s60
	s_cselect_b32 s40, s58, s59
	v_lshl_add_u64 v[178:179], s[26:27], 0, v[132:133]
	s_add_i32 m0, s17, 0xc000
	ds_read_b128 v[186:189], v153
	ds_read_b128 v[190:193], v153 offset:1024
	ds_read_b128 v[194:197], v153 offset:2048
	ds_read_b128 v[198:201], v153 offset:3072
	ds_read_b128 v[202:205], v153 offset:4096
	ds_read_b128 v[206:209], v153 offset:5120
	ds_read_b128 v[210:213], v153 offset:6144
	ds_read_b128 v[214:217], v153 offset:7168
	global_load_lds_dwordx4 v[178:179], off
	v_lshl_add_u64 v[178:179], s[26:27], 0, v[134:135]
	s_add_i32 m0, s17, 0xe000
	s_nop 0
	global_load_lds_dwordx4 v[178:179], off
	s_waitcnt vmcnt(8)
	s_waitcnt lgkmcnt(0)
	s_barrier
	s_waitcnt lgkmcnt(0)
	v_mfma_f32_16x16x32_bf16 v[124:127], v[140:143], v[186:189], v[124:127]
	v_mfma_f32_16x16x32_bf16 v[120:123], v[158:161], v[186:189], v[120:123]
	v_mfma_f32_16x16x32_bf16 v[116:119], v[140:143], v[194:197], v[116:119]
	v_mfma_f32_16x16x32_bf16 v[112:115], v[158:161], v[194:197], v[112:115]
	v_mfma_f32_16x16x32_bf16 v[100:103], v[140:143], v[202:205], v[100:103]
	v_mfma_f32_16x16x32_bf16 v[96:99], v[158:161], v[202:205], v[96:99]
	v_mfma_f32_16x16x32_bf16 v[84:87], v[140:143], v[210:213], v[84:87]
	v_mfma_f32_16x16x32_bf16 v[80:83], v[158:161], v[210:213], v[80:83]
	v_mfma_f32_16x16x32_bf16 v[124:127], v[154:157], v[190:193], v[124:127]
	v_mfma_f32_16x16x32_bf16 v[120:123], v[162:165], v[190:193], v[120:123]
	v_mfma_f32_16x16x32_bf16 v[116:119], v[154:157], v[198:201], v[116:119]
	v_mfma_f32_16x16x32_bf16 v[112:115], v[162:165], v[198:201], v[112:115]
	v_mfma_f32_16x16x32_bf16 v[100:103], v[154:157], v[206:209], v[100:103]
	v_mfma_f32_16x16x32_bf16 v[96:99], v[162:165], v[206:209], v[96:99]
	v_mfma_f32_16x16x32_bf16 v[84:87], v[154:157], v[214:217], v[84:87]
	v_mfma_f32_16x16x32_bf16 v[80:83], v[162:165], v[214:217], v[80:83]
	v_mfma_f32_16x16x32_bf16 v[108:111], v[166:169], v[186:189], v[108:111]
	v_mfma_f32_16x16x32_bf16 v[104:107], v[174:177], v[186:189], v[104:107]
	v_mfma_f32_16x16x32_bf16 v[92:95], v[166:169], v[194:197], v[92:95]
	v_mfma_f32_16x16x32_bf16 v[88:91], v[174:177], v[194:197], v[88:91]
	v_mfma_f32_16x16x32_bf16 v[76:79], v[166:169], v[202:205], v[76:79]
	v_mfma_f32_16x16x32_bf16 v[72:75], v[174:177], v[202:205], v[72:75]
	v_mfma_f32_16x16x32_bf16 v[68:71], v[166:169], v[210:213], v[68:71]
	v_mfma_f32_16x16x32_bf16 v[64:67], v[174:177], v[210:213], v[64:67]
	v_mfma_f32_16x16x32_bf16 v[108:111], v[170:173], v[190:193], v[108:111]
	v_mfma_f32_16x16x32_bf16 v[104:107], v[182:185], v[190:193], v[104:107]
	v_mfma_f32_16x16x32_bf16 v[92:95], v[170:173], v[198:201], v[92:95]
	v_mfma_f32_16x16x32_bf16 v[88:91], v[182:185], v[198:201], v[88:91]
	v_mfma_f32_16x16x32_bf16 v[76:79], v[170:173], v[206:209], v[76:79]
	v_mfma_f32_16x16x32_bf16 v[72:75], v[182:185], v[206:209], v[72:75]
	v_mfma_f32_16x16x32_bf16 v[68:71], v[170:173], v[214:217], v[68:71]
	v_mfma_f32_16x16x32_bf16 v[64:67], v[182:185], v[214:217], v[64:67]
	s_barrier
	s_add_i32 s62, s55, s45
	v_lshl_add_u64 v[178:179], s[40:41], 0, v[128:129]
	s_mov_b32 m0, s62
	ds_read_b128 v[186:189], v153 offset:16384
	ds_read_b128 v[190:193], v153 offset:17408
	ds_read_b128 v[194:197], v153 offset:18432
	ds_read_b128 v[198:201], v153 offset:19456
	ds_read_b128 v[202:205], v153 offset:20480
	ds_read_b128 v[206:209], v153 offset:21504
	ds_read_b128 v[210:213], v153 offset:22528
	ds_read_b128 v[214:217], v153 offset:23552
	global_load_lds_dwordx4 v[178:179], off
	s_add_i32 m0, s62, 0x2000
	s_add_u32 s62, s40, 0x40000
	v_lshl_add_u64 v[218:219], s[40:41], 0, v[130:131]
	s_addc_u32 s63, s41, 0
	s_add_i32 s64, s56, s45
	global_load_lds_dwordx4 v[218:219], off
	v_lshl_add_u64 v[220:221], s[62:63], 0, v[128:129]
	s_mov_b32 m0, s64
	v_lshl_add_u64 v[222:223], s[42:43], 0, v[130:131]
	global_load_lds_dwordx4 v[220:221], off
	v_lshl_add_u64 v[220:221], s[62:63], 0, v[130:131]
	s_add_i32 m0, s64, 0x2000
	s_nop 0
	global_load_lds_dwordx4 v[220:221], off
	v_lshl_add_u64 v[220:221], s[42:43], 0, v[128:129]
	s_mov_b32 m0, s17
	s_nop 0
	global_load_lds_dwordx4 v[220:221], off
	s_mov_b32 m0, s46
	s_nop 0
	global_load_lds_dwordx4 v[222:223], off
	s_waitcnt vmcnt(8)
	s_waitcnt lgkmcnt(0)
	s_barrier
; #define PG8_STAGE(bufoff, gbase, voff) do { _Pragma("unroll") for (int _i = 0; _i < 2; ++_i) \
;         __builtin_amdgcn_global_load_lds((const unsigned*)((const char*)(gbase) + (voff)[_i]), (PG8_LAS unsigned*)(lds + (bufoff) + ldsw + _i * 8192), 16, 0, 0); } while (0)
; #define PG8_LDA(dst, b, h) do { _Pragma("unroll") for (int m = 0; m < 4; ++m) _Pragma("unroll") for (int k = 0; k < 2; ++k) dst[m][k] = *(const PG8_LAS bf16x8*)(lds + PG8_SA(b, h) + aoff + m * 2048 + k * 1024); } while (0)
; #define PG8_LDB(dst, b, h) do { _Pragma("unroll") for (int n = 0; n < 2; ++n) _Pragma("unroll") for (int k = 0; k < 2; ++k) dst[n][k] = *(const PG8_LAS bf16x8*)(lds + PG8_SB(b, h) + boff + n * 2048 + k * 1024); } while (0)
; #define PG8_MMA(ai, bj, At, Bt) do { __builtin_amdgcn_s_setprio(1); _Pragma("unroll") for (int m = 0; m < 4; ++m) _Pragma("unroll") for (int n = 0; n < 2; ++n) _Pragma("unroll") for (int k = 0; k < 2; ++k) \
;         acc[ai][bj][m][n] = __builtin_amdgcn_mfma_f32_16x16x32_bf16(Bt[n][k], At[m][k], acc[ai][bj][m][n], 0, 0, 0); __builtin_amdgcn_s_setprio(0); } while (0)
; #define PG8_WAIT_V(n) asm volatile("s_waitcnt vmcnt(" #n ")" ::: "memory")
; #define PG8_WAIT_L(n) asm volatile("s_waitcnt lgkmcnt(" #n ")" ::: "memory")
; #define PG8_BAR __builtin_amdgcn_s_barrier()
; #define PG8_SCHED __builtin_amdgcn_sched_barrier(0)
; template <class Epi, class Sched, bool ALIGN_EPI = false, bool SP2 = false>
; __device__ __forceinline__ void gemm_phase(PG8_LAS unsigned char* lds, const Gemm g, const Sched& S, const Epi& E) {
;     ...
;             PG8_WAIT_V(8); PG8_WAIT_L(0); PG8_BAR; PG8_MMA(1, 0, At, B0); PG8_MMA(1, 1, At, B1); PG8_BAR; PG8_SCHED;
;             PG8_LDB(B0, 1, 0); PG8_LDB(B1, 1, 1); PG8_SCHED; PG8_LDA(At, 1, 0); PG8_STAGE(PG8_SA(0, 1), a2 + hstep, voffA);
;             PG8_WAIT_V(8); PG8_WAIT_L(0); PG8_BAR; PG8_MMA(0, 0, At, B0); PG8_MMA(0, 1, At, B1); PG8_BAR; PG8_SCHED;
	s_waitcnt lgkmcnt(0)
	v_mfma_f32_16x16x32_bf16 v[60:63], v[140:143], v[186:189], v[60:63]
	v_mfma_f32_16x16x32_bf16 v[56:59], v[158:161], v[186:189], v[56:59]
	v_mfma_f32_16x16x32_bf16 v[52:55], v[140:143], v[194:197], v[52:55]
	v_mfma_f32_16x16x32_bf16 v[48:51], v[158:161], v[194:197], v[48:51]
	v_mfma_f32_16x16x32_bf16 v[36:39], v[140:143], v[202:205], v[36:39]
	v_mfma_f32_16x16x32_bf16 v[32:35], v[158:161], v[202:205], v[32:35]
	v_mfma_f32_16x16x32_bf16 v[20:23], v[140:143], v[210:213], v[20:23]
	v_mfma_f32_16x16x32_bf16 v[16:19], v[158:161], v[210:213], v[16:19]
	v_mfma_f32_16x16x32_bf16 v[60:63], v[154:157], v[190:193], v[60:63]
	v_mfma_f32_16x16x32_bf16 v[56:59], v[162:165], v[190:193], v[56:59]
	v_mfma_f32_16x16x32_bf16 v[52:55], v[154:157], v[198:201], v[52:55]
	v_mfma_f32_16x16x32_bf16 v[48:51], v[162:165], v[198:201], v[48:51]
	v_mfma_f32_16x16x32_bf16 v[36:39], v[154:157], v[206:209], v[36:39]
	v_mfma_f32_16x16x32_bf16 v[32:35], v[162:165], v[206:209], v[32:35]
	v_mfma_f32_16x16x32_bf16 v[20:23], v[154:157], v[214:217], v[20:23]
	v_mfma_f32_16x16x32_bf16 v[16:19], v[162:165], v[214:217], v[16:19]
	v_mfma_f32_16x16x32_bf16 v[44:47], v[166:169], v[186:189], v[44:47]
	v_mfma_f32_16x16x32_bf16 v[40:43], v[174:177], v[186:189], v[40:43]
	v_mfma_f32_16x16x32_bf16 v[28:31], v[166:169], v[194:197], v[28:31]
	v_mfma_f32_16x16x32_bf16 v[24:27], v[174:177], v[194:197], v[24:27]
	v_mfma_f32_16x16x32_bf16 v[12:15], v[166:169], v[202:205], v[12:15]
	v_mfma_f32_16x16x32_bf16 v[8:11], v[174:177], v[202:205], v[8:11]
	v_mfma_f32_16x16x32_bf16 v[4:7], v[166:169], v[210:213], v[4:7]
	v_mfma_f32_16x16x32_bf16 v[0:3], v[174:177], v[210:213], v[0:3]
	v_mfma_f32_16x16x32_bf16 v[44:47], v[170:173], v[190:193], v[44:47]
	v_mfma_f32_16x16x32_bf16 v[40:43], v[182:185], v[190:193], v[40:43]
	v_mfma_f32_16x16x32_bf16 v[28:31], v[170:173], v[198:201], v[28:31]
	v_mfma_f32_16x16x32_bf16 v[24:27], v[182:185], v[198:201], v[24:27]
	v_mfma_f32_16x16x32_bf16 v[12:15], v[170:173], v[206:209], v[12:15]
	v_mfma_f32_16x16x32_bf16 v[8:11], v[182:185], v[206:209], v[8:11]
	v_mfma_f32_16x16x32_bf16 v[4:7], v[170:173], v[214:217], v[4:7]
	v_mfma_f32_16x16x32_bf16 v[0:3], v[182:185], v[214:217], v[0:3]
	s_barrier
	s_add_i32 s62, 0, 0x18000
	s_add_i32 s63, 0, 0x1c000
	v_add_u32_e32 v162, s62, v149
	v_add_u32_e32 v181, s63, v149
	ds_read_b128 v[140:143], v162
	ds_read_b128 v[154:157], v162 offset:1024
	ds_read_b128 v[158:161], v162 offset:2048
	ds_read_b128 v[162:165], v162 offset:3072
	ds_read_b128 v[166:169], v181
	ds_read_b128 v[170:173], v181 offset:1024
	ds_read_b128 v[174:177], v181 offset:2048
	ds_read_b128 v[182:185], v181 offset:3072
	s_add_u32 s42, s42, 0x40000
	s_addc_u32 s43, s43, 0
	s_mov_b32 m0, s47
	v_lshl_add_u64 v[224:225], s[42:43], 0, v[128:129]
	ds_read_b128 v[186:189], v153 offset:32768
	ds_read_b128 v[190:193], v153 offset:33792
	ds_read_b128 v[194:197], v153 offset:34816
	ds_read_b128 v[198:201], v153 offset:35840
	ds_read_b128 v[202:205], v153 offset:36864
	ds_read_b128 v[206:209], v153 offset:37888
	ds_read_b128 v[210:213], v153 offset:38912
	ds_read_b128 v[214:217], v153 offset:39936
	global_load_lds_dwordx4 v[224:225], off
	v_lshl_add_u64 v[224:225], s[42:43], 0, v[130:131]
	s_mov_b32 m0, s48
	s_nop 0
	global_load_lds_dwordx4 v[224:225], off
	s_waitcnt vmcnt(8)
	s_waitcnt lgkmcnt(0)
	s_barrier
	s_waitcnt lgkmcnt(0)
	v_mfma_f32_16x16x32_bf16 v[124:127], v[140:143], v[186:189], v[124:127]
	v_mfma_f32_16x16x32_bf16 v[120:123], v[158:161], v[186:189], v[120:123]
	v_mfma_f32_16x16x32_bf16 v[116:119], v[140:143], v[194:197], v[116:119]
	v_mfma_f32_16x16x32_bf16 v[112:115], v[158:161], v[194:197], v[112:115]
	v_mfma_f32_16x16x32_bf16 v[100:103], v[140:143], v[202:205], v[100:103]
	v_mfma_f32_16x16x32_bf16 v[96:99], v[158:161], v[202:205], v[96:99]
	v_mfma_f32_16x16x32_bf16 v[84:87], v[140:143], v[210:213], v[84:87]
	v_mfma_f32_16x16x32_bf16 v[80:83], v[158:161], v[210:213], v[80:83]
	v_mfma_f32_16x16x32_bf16 v[124:127], v[154:157], v[190:193], v[124:127]
	v_mfma_f32_16x16x32_bf16 v[120:123], v[162:165], v[190:193], v[120:123]
	v_mfma_f32_16x16x32_bf16 v[116:119], v[154:157], v[198:201], v[116:119]
	v_mfma_f32_16x16x32_bf16 v[112:115], v[162:165], v[198:201], v[112:115]
	v_mfma_f32_16x16x32_bf16 v[100:103], v[154:157], v[206:209], v[100:103]
	v_mfma_f32_16x16x32_bf16 v[96:99], v[162:165], v[206:209], v[96:99]
	v_mfma_f32_16x16x32_bf16 v[84:87], v[154:157], v[214:217], v[84:87]
	v_mfma_f32_16x16x32_bf16 v[80:83], v[162:165], v[214:217], v[80:83]
	v_mfma_f32_16x16x32_bf16 v[108:111], v[166:169], v[186:189], v[108:111]
	v_mfma_f32_16x16x32_bf16 v[104:107], v[174:177], v[186:189], v[104:107]
	v_mfma_f32_16x16x32_bf16 v[92:95], v[166:169], v[194:197], v[92:95]
	v_mfma_f32_16x16x32_bf16 v[88:91], v[174:177], v[194:197], v[88:91]
	v_mfma_f32_16x16x32_bf16 v[76:79], v[166:169], v[202:205], v[76:79]
	v_mfma_f32_16x16x32_bf16 v[72:75], v[174:177], v[202:205], v[72:75]
	v_mfma_f32_16x16x32_bf16 v[68:71], v[166:169], v[210:213], v[68:71]
	v_mfma_f32_16x16x32_bf16 v[64:67], v[174:177], v[210:213], v[64:67]
	v_mfma_f32_16x16x32_bf16 v[108:111], v[170:173], v[190:193], v[108:111]
	v_mfma_f32_16x16x32_bf16 v[104:107], v[182:185], v[190:193], v[104:107]
	v_mfma_f32_16x16x32_bf16 v[92:95], v[170:173], v[198:201], v[92:95]
	v_mfma_f32_16x16x32_bf16 v[88:91], v[182:185], v[198:201], v[88:91]
	v_mfma_f32_16x16x32_bf16 v[76:79], v[170:173], v[206:209], v[76:79]
	v_mfma_f32_16x16x32_bf16 v[72:75], v[182:185], v[206:209], v[72:75]
	v_mfma_f32_16x16x32_bf16 v[68:71], v[170:173], v[214:217], v[68:71]
	v_mfma_f32_16x16x32_bf16 v[64:67], v[182:185], v[214:217], v[64:67]
	s_barrier
; #define PG8_STAGE(bufoff, gbase, voff) do { _Pragma("unroll") for (int _i = 0; _i < 2; ++_i) \
;         __builtin_amdgcn_global_load_lds((const unsigned*)((const char*)(gbase) + (voff)[_i]), (PG8_LAS unsigned*)(lds + (bufoff) + ldsw + _i * 8192), 16, 0, 0); } while (0)
; #define PG8_LDA(dst, b, h) do { _Pragma("unroll") for (int m = 0; m < 4; ++m) _Pragma("unroll") for (int k = 0; k < 2; ++k) dst[m][k] = *(const PG8_LAS bf16x8*)(lds + PG8_SA(b, h) + aoff + m * 2048 + k * 1024); } while (0)
; #define PG8_MMA(ai, bj, At, Bt) do { __builtin_amdgcn_s_setprio(1); _Pragma("unroll") for (int m = 0; m < 4; ++m) _Pragma("unroll") for (int n = 0; n < 2; ++n) _Pragma("unroll") for (int k = 0; k < 2; ++k) \
;         acc[ai][bj][m][n] = __builtin_amdgcn_mfma_f32_16x16x32_bf16(Bt[n][k], At[m][k], acc[ai][bj][m][n], 0, 0, 0); __builtin_amdgcn_s_setprio(0); } while (0)
; #define PG8_WAIT_V(n) asm volatile("s_waitcnt vmcnt(" #n ")" ::: "memory")
; #define PG8_WAIT_L(n) asm volatile("s_waitcnt lgkmcnt(" #n ")" ::: "memory")
; #define PG8_BAR __builtin_amdgcn_s_barrier()
; #define PG8_SCHED __builtin_amdgcn_sched_barrier(0)
; template <class Epi, class Sched, bool ALIGN_EPI = false, bool SP2 = false>
; __device__ __forceinline__ void gemm_phase(PG8_LAS unsigned char* lds, const Gemm g, const Sched& S, const Epi& E) {
;     ...
;             PG8_LDA(At, 1, 1); PG8_STAGE(PG8_SB(1, 0), b3, voffB); PG8_STAGE(PG8_SB(1, 1), b3 + hstep, voffB); PG8_STAGE(PG8_SA(1, 0), a3, voffA);
;             PG8_WAIT_V(8); PG8_WAIT_L(0); PG8_BAR; PG8_MMA(1, 0, At, B0); PG8_MMA(1, 1, At, B1); PG8_BAR; PG8_SCHED;
	s_add_i32 s42, s62, s45
	v_lshl_add_u64 v[178:179], v[178:179], 0, s[10:11]
	s_mov_b32 m0, s42
	ds_read_b128 v[186:189], v153 offset:49152
	ds_read_b128 v[190:193], v153 offset:50176
	ds_read_b128 v[194:197], v153 offset:51200
	ds_read_b128 v[198:201], v153 offset:52224
	ds_read_b128 v[202:205], v153 offset:53248
	ds_read_b128 v[206:209], v153 offset:54272
	ds_read_b128 v[210:213], v153 offset:55296
	ds_read_b128 v[214:217], v153 offset:56320
	global_load_lds_dwordx4 v[178:179], off
	s_add_i32 m0, s42, 0x2000
	s_add_u32 s40, s40, 0x40080
	v_lshl_add_u64 v[178:179], v[218:219], 0, s[10:11]
	s_addc_u32 s41, s41, 0
	s_add_i32 s42, s63, s45
	global_load_lds_dwordx4 v[178:179], off
	v_lshl_add_u64 v[178:179], s[40:41], 0, v[128:129]
	s_mov_b32 m0, s42
	s_nop 0
	global_load_lds_dwordx4 v[178:179], off
	v_lshl_add_u64 v[178:179], s[40:41], 0, v[130:131]
	s_add_i32 m0, s42, 0x2000
	s_nop 0
	global_load_lds_dwordx4 v[178:179], off
	v_lshl_add_u64 v[178:179], v[220:221], 0, s[10:11]
	s_mov_b32 m0, s50
	s_nop 0
	global_load_lds_dwordx4 v[178:179], off
	v_lshl_add_u64 v[178:179], v[222:223], 0, s[10:11]
	s_mov_b32 m0, s51
	s_nop 0
	global_load_lds_dwordx4 v[178:179], off
	s_waitcnt vmcnt(8)
	s_waitcnt lgkmcnt(0)
	s_barrier
	s_waitcnt lgkmcnt(0)
	v_mfma_f32_16x16x32_bf16 v[60:63], v[140:143], v[186:189], v[60:63]
	v_mfma_f32_16x16x32_bf16 v[56:59], v[158:161], v[186:189], v[56:59]
	v_mfma_f32_16x16x32_bf16 v[52:55], v[140:143], v[194:197], v[52:55]
	v_mfma_f32_16x16x32_bf16 v[48:51], v[158:161], v[194:197], v[48:51]
	v_mfma_f32_16x16x32_bf16 v[36:39], v[140:143], v[202:205], v[36:39]
	v_mfma_f32_16x16x32_bf16 v[32:35], v[158:161], v[202:205], v[32:35]
	v_mfma_f32_16x16x32_bf16 v[20:23], v[140:143], v[210:213], v[20:23]
	v_mfma_f32_16x16x32_bf16 v[16:19], v[158:161], v[210:213], v[16:19]
	v_mfma_f32_16x16x32_bf16 v[60:63], v[154:157], v[190:193], v[60:63]
	v_mfma_f32_16x16x32_bf16 v[56:59], v[162:165], v[190:193], v[56:59]
	v_mfma_f32_16x16x32_bf16 v[52:55], v[154:157], v[198:201], v[52:55]
	v_mfma_f32_16x16x32_bf16 v[48:51], v[162:165], v[198:201], v[48:51]
	v_mfma_f32_16x16x32_bf16 v[36:39], v[154:157], v[206:209], v[36:39]
	v_mfma_f32_16x16x32_bf16 v[32:35], v[162:165], v[206:209], v[32:35]
	v_mfma_f32_16x16x32_bf16 v[20:23], v[154:157], v[214:217], v[20:23]
	v_mfma_f32_16x16x32_bf16 v[16:19], v[162:165], v[214:217], v[16:19]
	v_mfma_f32_16x16x32_bf16 v[44:47], v[166:169], v[186:189], v[44:47]
	v_mfma_f32_16x16x32_bf16 v[40:43], v[174:177], v[186:189], v[40:43]
	v_mfma_f32_16x16x32_bf16 v[28:31], v[166:169], v[194:197], v[28:31]
	v_mfma_f32_16x16x32_bf16 v[24:27], v[174:177], v[194:197], v[24:27]
	v_mfma_f32_16x16x32_bf16 v[12:15], v[166:169], v[202:205], v[12:15]
	v_mfma_f32_16x16x32_bf16 v[8:11], v[174:177], v[202:205], v[8:11]
	v_mfma_f32_16x16x32_bf16 v[4:7], v[166:169], v[210:213], v[4:7]
	v_mfma_f32_16x16x32_bf16 v[0:3], v[174:177], v[210:213], v[0:3]
	v_mfma_f32_16x16x32_bf16 v[44:47], v[170:173], v[190:193], v[44:47]
	v_mfma_f32_16x16x32_bf16 v[40:43], v[182:185], v[190:193], v[40:43]
	v_mfma_f32_16x16x32_bf16 v[28:31], v[170:173], v[198:201], v[28:31]
	v_mfma_f32_16x16x32_bf16 v[24:27], v[182:185], v[198:201], v[24:27]
	v_mfma_f32_16x16x32_bf16 v[12:15], v[170:173], v[206:209], v[12:15]
	v_mfma_f32_16x16x32_bf16 v[8:11], v[182:185], v[206:209], v[8:11]
	v_mfma_f32_16x16x32_bf16 v[4:7], v[170:173], v[214:217], v[4:7]
	v_mfma_f32_16x16x32_bf16 v[0:3], v[182:185], v[214:217], v[0:3]
	s_barrier
	s_add_i32 s61, s61, 2
	s_add_u32 s26, s26, 0x100
	s_addc_u32 s27, s27, 0
	s_add_u32 s59, s59, 0x100
	s_addc_u32 s60, s60, 0
	s_cmp_gt_u32 s61, 13
	s_cbranch_scc0 .LBB0_2122
	s_and_b64 vcc, exec, s[12:13]
	s_cbranch_vccz .LBB0_2125
	s_barrier

; #define PG8_STAGE(bufoff, gbase, voff) do { _Pragma("unroll") for (int _i = 0; _i < 2; ++_i) \
;         __builtin_amdgcn_global_load_lds((const unsigned*)((const char*)(gbase) + (voff)[_i]), (PG8_LAS unsigned*)(lds + (bufoff) + ldsw + _i * 8192), 16, 0, 0); } while (0)
; #define PG8_WAIT_V(n) asm volatile("s_waitcnt vmcnt(" #n ")" ::: "memory")
; template <class Epi, class Sched, bool ALIGN_EPI = false, bool SP2 = false>
; __device__ __forceinline__ void gemm_phase(PG8_LAS unsigned char* lds, const Gemm g, const Sched& S, const Epi& E) {
;     ...
;         PG8_STAGE(PG8_SB(1, 0), cB + kstep, voffB); PG8_STAGE(PG8_SA(1, 0), cA + kstep, voffA); PG8_STAGE(PG8_SB(1, 1), cB + hstep + kstep, voffB);
;         PG8_WAIT_V(6); PG8_BAR;
;     } else {
;         PG8_STAGE(PG8_SB(0, 0), cB, voffB); PG8_STAGE(PG8_SA(0, 0), cA, voffA); PG8_STAGE(PG8_SB(0, 1), cB + hstep, voffB); PG8_STAGE(PG8_SA(0, 1), cA + hstep, voffA);
;         if (wr == 1) PG8_BAR;
;         PG8_WAIT_V(4); PG8_BAR;
;         PG8_STAGE(PG8_SB(1, 0), cB + kstep, voffB); PG8_STAGE(PG8_SA(1, 0), cA + kstep, voffA); PG8_STAGE(PG8_SB(1, 1), cB + hstep + kstep, voffB);
;         PG8_WAIT_V(6); PG8_BAR;
;     }
;     for (;;) {
;         const bool has_next = S.next(ui + 1, nxt);
;         const char* nA = has_next ? (const char*)g.A + (size_t)nxt.pm * tstep : cA; const char* nB = has_next ? (const char*)g.Bt + (size_t)nxt.pn * tstep : cB;
;         for (int t = 0; t < nt; t += 2) {
;             const bool last = (t == nt - 2);
;             const char* a1 = cA + (size_t)(t + 1) * kstep;
;             const char* a2 = last ? nA : cA + (size_t)(t + 2) * kstep; const char* b2 = last ? nB : cB + (size_t)(t + 2) * kstep;
;             const char* a3 = a2 + kstep; const char* b3 = b2 + kstep;
;             if (last && has_next) S.a_ready(nxt);
;             if constexpr (SP2) {
;             PG8_LDB(B0, 0, 0); PG8_LDB(B1, 0, 1); PG8_SCHED; PG8_LDA(At, 0, 0); PG8_STAGE(PG8_SA(1, 1), a1 + hstep, voffA);
;             PG8_WAIT_V(8); PG8_WAIT_L(0); PG8_BAR; PG8_MMA(0, 0, At, B0); PG8_MMA(0, 1, At, B1); PG8_BAR; PG8_SCHED;
;             PG8_LDA(At, 0, 1); PG8_STAGE(PG8_SB(0, 0), b2, voffB); PG8_STAGE(PG8_SB(0, 1), b2 + hstep, voffB); PG8_STAGE(PG8_SA(0, 0), a2, voffA);
;             PG8_WAIT_V(8); PG8_WAIT_L(0); PG8_BAR; PG8_MMA(1, 0, At, B0); PG8_MMA(1, 1, At, B1); PG8_BAR; PG8_SCHED;
.LBB0_2148:
	s_lshl_b64 s[8:9], s[8:9], 19
	s_add_u32 s8, s14, s8
	s_addc_u32 s9, s16, s9
	s_add_u32 s24, s8, 0xf000000
	s_addc_u32 s25, s9, 0
	s_add_i32 s33, 0, 0x18000
	s_lshl_b32 s8, s17, 5
	s_add_i32 s9, s33, s21
	s_mov_b64 s[18:19], 0x80
	s_lshl_b32 s23, s22, 13
	s_and_b32 s8, s8, 0x60
	v_lshl_add_u64 v[4:5], v[32:33], 0, s[18:19]
	s_mov_b32 m0, s9
	s_add_i32 s16, s9, 0x2000
	s_add_i32 s14, s12, 0x8000
	s_add_i32 s17, s12, 0xa000
	s_waitcnt vmcnt(2)
	s_barrier
	global_load_lds_dwordx4 v[4:5], off
	v_lshl_add_u64 v[6:7], v[34:35], 0, s[18:19]
	s_mov_b32 m0, s16
	s_add_u32 s26, s6, 0x40080
	global_load_lds_dwordx4 v[6:7], off
	v_lshl_add_u64 v[2:3], v[24:25], 0, s[18:19]
	s_mov_b32 m0, s14
	s_addc_u32 s27, s7, 0
	s_add_i32 s34, 0, 0x1c000
	global_load_lds_dwordx4 v[2:3], off
	v_lshl_add_u64 v[8:9], v[22:23], 0, s[18:19]
	s_mov_b32 m0, s17
	s_add_i32 s18, s34, s21
	global_load_lds_dwordx4 v[8:9], off
	v_lshl_add_u64 v[16:17], s[26:27], 0, v[128:129]
	s_mov_b32 m0, s18
	s_add_i32 s19, s18, 0x2000
	global_load_lds_dwordx4 v[16:17], off
	v_lshl_add_u64 v[18:19], s[26:27], 0, v[130:131]
	s_mov_b32 m0, s19
	v_lshl_or_b32 v69, s8, 7, v147
	global_load_lds_dwordx4 v[18:19], off
	s_add_i32 s35, 0, 0x10000
	s_add_i32 s40, 0, 0x14000
	v_add_u32_e32 v172, s35, v69
	v_lshl_or_b32 v28, s22, 6, v145
	v_lshl_or_b32 v0, v145, 6, v146
	v_lshlrev_b32_e32 v1, 2, v145
	s_waitcnt vmcnt(6)
	s_barrier
	v_add_u32_e32 v145, s40, v69
	ds_read_b128 v[36:39], v172
	ds_read_b128 v[40:43], v172 offset:1024
	ds_read_b128 v[44:47], v172 offset:2048
	ds_read_b128 v[48:51], v172 offset:3072
	ds_read_b128 v[52:55], v145
	ds_read_b128 v[56:59], v145 offset:1024
	ds_read_b128 v[60:63], v145 offset:2048
	ds_read_b128 v[64:67], v145 offset:3072
	v_and_b32_e32 v1, 32, v1
	v_bitop3_b32 v68, v0, s23, v1 bitop3:0xde
	v_or_b32_e32 v0, 48, v28
	v_mov_b32_e32 v1, v129
	v_or_b32_e32 v10, 32, v28
	v_mov_b32_e32 v11, v129
	v_or_b32_e32 v20, 16, v28
	v_mov_b32_e32 v21, v129
	v_mov_b32_e32 v29, v129
	v_lshlrev_b64 v[0:1], 12, v[0:1]
	v_lshlrev_b64 v[10:11], 12, v[10:11]
	v_lshlrev_b64 v[20:21], 12, v[20:21]
	v_lshlrev_b64 v[28:29], 12, v[28:29]
	v_lshl_add_u64 v[0:1], s[24:25], 0, v[0:1]
	v_lshl_add_u64 v[10:11], s[24:25], 0, v[10:11]
	v_lshl_add_u64 v[20:21], s[24:25], 0, v[20:21]
	v_lshl_add_u64 v[28:29], s[24:25], 0, v[28:29]
	v_add_u32_e32 v173, 0, v68
	v_add_u32_e32 v174, s34, v69
	v_add_u32_e32 v175, s33, v69
	s_add_u32 s22, s2, 0x40080
	s_addc_u32 s23, s3, 0
	s_add_i32 s25, s12, 0xc000
	v_lshl_add_u64 v[100:101], s[22:23], 0, v[128:129]
	s_mov_b32 m0, s25
	ds_read_b128 v[68:71], v173
	ds_read_b128 v[72:75], v173 offset:1024
	ds_read_b128 v[76:79], v173 offset:2048
	ds_read_b128 v[80:83], v173 offset:3072
	ds_read_b128 v[84:87], v173 offset:4096
	ds_read_b128 v[88:91], v173 offset:5120
	ds_read_b128 v[92:95], v173 offset:6144
	ds_read_b128 v[96:99], v173 offset:7168
	global_load_lds_dwordx4 v[100:101], off
	v_lshl_add_u64 v[100:101], s[22:23], 0, v[130:131]
	s_add_i32 s22, s12, 0xe000
	s_mov_b32 m0, s22
	s_nop 0
	global_load_lds_dwordx4 v[100:101], off
	s_waitcnt vmcnt(8)
	s_waitcnt lgkmcnt(0)
	s_barrier
	s_waitcnt lgkmcnt(0)
	v_mfma_f32_16x16x32_bf16 v[100:103], v[36:39], v[68:71], 0
	v_mfma_f32_16x16x32_bf16 v[108:111], v[36:39], v[76:79], 0
	v_mfma_f32_16x16x32_bf16 v[116:119], v[36:39], v[84:87], 0
	v_mfma_f32_16x16x32_bf16 v[36:39], v[36:39], v[92:95], 0
	v_mfma_f32_16x16x32_bf16 v[100:103], v[40:43], v[72:75], v[100:103]
	v_mfma_f32_16x16x32_bf16 v[104:107], v[44:47], v[68:71], 0
	v_mfma_f32_16x16x32_bf16 v[108:111], v[40:43], v[80:83], v[108:111]
	v_mfma_f32_16x16x32_bf16 v[112:115], v[44:47], v[76:79], 0
	v_mfma_f32_16x16x32_bf16 v[116:119], v[40:43], v[88:91], v[116:119]
	v_mfma_f32_16x16x32_bf16 v[120:123], v[44:47], v[84:87], 0
	v_mfma_f32_16x16x32_bf16 v[36:39], v[40:43], v[96:99], v[36:39]
	v_mfma_f32_16x16x32_bf16 v[40:43], v[44:47], v[92:95], 0
	v_mfma_f32_16x16x32_bf16 v[104:107], v[48:51], v[72:75], v[104:107]
	v_mfma_f32_16x16x32_bf16 v[112:115], v[48:51], v[80:83], v[112:115]
	v_mfma_f32_16x16x32_bf16 v[120:123], v[48:51], v[88:91], v[120:123]
	v_mfma_f32_16x16x32_bf16 v[40:43], v[48:51], v[96:99], v[40:43]
	v_mfma_f32_16x16x32_bf16 v[44:47], v[52:55], v[68:71], 0
	v_mfma_f32_16x16x32_bf16 v[48:51], v[60:63], v[68:71], 0
	v_mfma_f32_16x16x32_bf16 v[44:47], v[56:59], v[72:75], v[44:47]
	v_mfma_f32_16x16x32_bf16 v[48:51], v[64:67], v[72:75], v[48:51]
	v_mfma_f32_16x16x32_bf16 v[68:71], v[52:55], v[76:79], 0
	v_mfma_f32_16x16x32_bf16 v[72:75], v[60:63], v[76:79], 0
	v_mfma_f32_16x16x32_bf16 v[76:79], v[52:55], v[84:87], 0
	v_mfma_f32_16x16x32_bf16 v[52:55], v[52:55], v[92:95], 0
	v_mfma_f32_16x16x32_bf16 v[68:71], v[56:59], v[80:83], v[68:71]
	v_mfma_f32_16x16x32_bf16 v[72:75], v[64:67], v[80:83], v[72:75]
	v_mfma_f32_16x16x32_bf16 v[76:79], v[56:59], v[88:91], v[76:79]
	v_mfma_f32_16x16x32_bf16 v[80:83], v[60:63], v[84:87], 0
	v_mfma_f32_16x16x32_bf16 v[52:55], v[56:59], v[96:99], v[52:55]
	v_mfma_f32_16x16x32_bf16 v[56:59], v[60:63], v[92:95], 0
	v_mfma_f32_16x16x32_bf16 v[80:83], v[64:67], v[88:91], v[80:83]
	v_mfma_f32_16x16x32_bf16 v[56:59], v[64:67], v[96:99], v[56:59]
	s_barrier
	s_add_i32 s23, s35, s21
	s_mov_b64 s[26:27], 0x100
	s_add_i32 s24, s23, 0x2000
	v_lshl_add_u64 v[60:61], v[32:33], 0, s[26:27]
	s_mov_b32 m0, s23
	s_add_u32 s34, s6, 0x40100
	global_load_lds_dwordx4 v[60:61], off
	v_lshl_add_u64 v[60:61], v[34:35], 0, s[26:27]
	s_mov_b32 m0, s24
	s_addc_u32 s35, s7, 0
	s_add_i32 s21, s40, s21
	global_load_lds_dwordx4 v[60:61], off
	v_lshl_add_u64 v[60:61], s[34:35], 0, v[128:129]
	s_mov_b32 m0, s21
	s_add_i32 s33, s21, 0x2000
	global_load_lds_dwordx4 v[60:61], off
	v_lshl_add_u64 v[60:61], s[34:35], 0, v[130:131]
	s_mov_b32 m0, s33
	s_nop 0
	global_load_lds_dwordx4 v[60:61], off
	v_lshl_add_u64 v[60:61], v[24:25], 0, s[26:27]
	s_mov_b32 m0, s12
	s_nop 0
	global_load_lds_dwordx4 v[60:61], off
	v_lshl_add_u64 v[60:61], v[22:23], 0, s[26:27]
	s_mov_b32 m0, s20
	s_nop 0
	global_load_lds_dwordx4 v[60:61], off
	s_waitcnt vmcnt(8)
	s_waitcnt lgkmcnt(0)
	s_barrier
; #define PG8_STAGE(bufoff, gbase, voff) do { _Pragma("unroll") for (int _i = 0; _i < 2; ++_i) \
;         __builtin_amdgcn_global_load_lds((const unsigned*)((const char*)(gbase) + (voff)[_i]), (PG8_LAS unsigned*)(lds + (bufoff) + ldsw + _i * 8192), 16, 0, 0); } while (0)
; #define PG8_LDA(dst, b, h) do { _Pragma("unroll") for (int m = 0; m < 4; ++m) _Pragma("unroll") for (int k = 0; k < 2; ++k) dst[m][k] = *(const PG8_LAS bf16x8*)(lds + PG8_SA(b, h) + aoff + m * 2048 + k * 1024); } while (0)
; #define PG8_LDB(dst, b, h) do { _Pragma("unroll") for (int n = 0; n < 2; ++n) _Pragma("unroll") for (int k = 0; k < 2; ++k) dst[n][k] = *(const PG8_LAS bf16x8*)(lds + PG8_SB(b, h) + boff + n * 2048 + k * 1024); } while (0)
; #define PG8_MMA(ai, bj, At, Bt) do { __builtin_amdgcn_s_setprio(1); _Pragma("unroll") for (int m = 0; m < 4; ++m) _Pragma("unroll") for (int n = 0; n < 2; ++n) _Pragma("unroll") for (int k = 0; k < 2; ++k) \
;         acc[ai][bj][m][n] = __builtin_amdgcn_mfma_f32_16x16x32_bf16(Bt[n][k], At[m][k], acc[ai][bj][m][n], 0, 0, 0); __builtin_amdgcn_s_setprio(0); } while (0)
; #define PG8_WAIT_V(n) asm volatile("s_waitcnt vmcnt(" #n ")" ::: "memory")
; template <class Epi, class Sched, bool ALIGN_EPI = false, bool SP2 = false>
; __device__ __forceinline__ void gemm_phase(PG8_LAS unsigned char* lds, const Gemm g, const Sched& S, const Epi& E) {
;     ...
;             PG8_LDB(B0, 0, 0); PG8_LDB(B1, 0, 1); PG8_SCHED; PG8_LDA(At, 0, 0); PG8_STAGE(PG8_SA(1, 1), a1 + hstep, voffA);
;             PG8_WAIT_V(8); PG8_WAIT_L(0); PG8_BAR; PG8_MMA(0, 0, At, B0); PG8_MMA(0, 1, At, B1); PG8_BAR; PG8_SCHED;
;             PG8_LDA(At, 0, 1); PG8_STAGE(PG8_SB(0, 0), b2, voffB); PG8_STAGE(PG8_SB(0, 1), b2 + hstep, voffB); PG8_STAGE(PG8_SA(0, 0), a2, voffA);
;             PG8_WAIT_V(8); PG8_WAIT_L(0); PG8_BAR; PG8_MMA(1, 0, At, B0); PG8_MMA(1, 1, At, B1); PG8_BAR; PG8_SCHED;
;             PG8_LDB(B0, 1, 0); PG8_LDB(B1, 1, 1); PG8_SCHED; PG8_LDA(At, 1, 0); PG8_STAGE(PG8_SA(0, 1), a2 + hstep, voffA);
;             PG8_WAIT_V(8); PG8_WAIT_L(0); PG8_BAR; PG8_MMA(0, 0, At, B0); PG8_MMA(0, 1, At, B1); PG8_BAR; PG8_SCHED;
;             PG8_LDA(At, 1, 1); PG8_STAGE(PG8_SB(1, 0), b3, voffB); PG8_STAGE(PG8_SB(1, 1), b3 + hstep, voffB); PG8_STAGE(PG8_SA(1, 0), a3, voffA);
;             PG8_WAIT_V(8); PG8_WAIT_L(0); PG8_BAR; PG8_MMA(1, 0, At, B0); PG8_MMA(1, 1, At, B1); PG8_BAR; PG8_SCHED;
	s_setprio 0
	s_barrier
	ds_read_b128 v[60:63], v175
	ds_read_b128 v[64:67], v175 offset:1024
	ds_read_b128 v[84:87], v175 offset:2048
	ds_read_b128 v[88:91], v175 offset:3072
	ds_read_b128 v[92:95], v174
	ds_read_b128 v[96:99], v174 offset:1024
	ds_read_b128 v[124:127], v174 offset:2048
	ds_read_b128 v[132:135], v174 offset:3072
	s_add_u32 s26, s2, 0x40100
	s_addc_u32 s27, s3, 0
	s_mov_b32 m0, s13
	v_lshl_add_u64 v[170:171], s[26:27], 0, v[128:129]
	ds_read_b128 v[136:139], v173 offset:32768
	ds_read_b128 v[140:143], v173 offset:33792
	ds_read_b128 v[146:149], v173 offset:34816
	ds_read_b128 v[150:153], v173 offset:35840
	ds_read_b128 v[154:157], v173 offset:36864
	ds_read_b128 v[158:161], v173 offset:37888
	ds_read_b128 v[162:165], v173 offset:38912
	ds_read_b128 v[166:169], v173 offset:39936
	global_load_lds_dwordx4 v[170:171], off
	v_lshl_add_u64 v[170:171], s[26:27], 0, v[130:131]
	s_mov_b32 m0, s15
	s_nop 0
	global_load_lds_dwordx4 v[170:171], off
	s_waitcnt vmcnt(8)
	s_waitcnt lgkmcnt(0)
	s_barrier
	s_waitcnt lgkmcnt(0)
	v_mfma_f32_16x16x32_bf16 v[100:103], v[60:63], v[136:139], v[100:103]
	v_mfma_f32_16x16x32_bf16 v[104:107], v[84:87], v[136:139], v[104:107]
	v_mfma_f32_16x16x32_bf16 v[108:111], v[60:63], v[146:149], v[108:111]
	v_mfma_f32_16x16x32_bf16 v[112:115], v[84:87], v[146:149], v[112:115]
	v_mfma_f32_16x16x32_bf16 v[116:119], v[60:63], v[154:157], v[116:119]
	v_mfma_f32_16x16x32_bf16 v[120:123], v[84:87], v[154:157], v[120:123]
	v_mfma_f32_16x16x32_bf16 v[36:39], v[60:63], v[162:165], v[36:39]
	v_mfma_f32_16x16x32_bf16 v[40:43], v[84:87], v[162:165], v[40:43]
	v_mfma_f32_16x16x32_bf16 v[100:103], v[64:67], v[140:143], v[100:103]
	v_mfma_f32_16x16x32_bf16 v[104:107], v[88:91], v[140:143], v[104:107]
	v_mfma_f32_16x16x32_bf16 v[108:111], v[64:67], v[150:153], v[108:111]
	v_mfma_f32_16x16x32_bf16 v[112:115], v[88:91], v[150:153], v[112:115]
	v_mfma_f32_16x16x32_bf16 v[116:119], v[64:67], v[158:161], v[116:119]
	v_mfma_f32_16x16x32_bf16 v[120:123], v[88:91], v[158:161], v[120:123]
	v_mfma_f32_16x16x32_bf16 v[36:39], v[64:67], v[166:169], v[36:39]
	v_mfma_f32_16x16x32_bf16 v[40:43], v[88:91], v[166:169], v[40:43]
	v_mfma_f32_16x16x32_bf16 v[44:47], v[92:95], v[136:139], v[44:47]
	v_mfma_f32_16x16x32_bf16 v[48:51], v[124:127], v[136:139], v[48:51]
	v_mfma_f32_16x16x32_bf16 v[60:63], v[92:95], v[146:149], v[68:71]
	v_mfma_f32_16x16x32_bf16 v[64:67], v[124:127], v[146:149], v[72:75]
	v_mfma_f32_16x16x32_bf16 v[68:71], v[92:95], v[154:157], v[76:79]
	v_mfma_f32_16x16x32_bf16 v[72:75], v[124:127], v[154:157], v[80:83]
	v_mfma_f32_16x16x32_bf16 v[52:55], v[92:95], v[162:165], v[52:55]
	v_mfma_f32_16x16x32_bf16 v[56:59], v[124:127], v[162:165], v[56:59]
	v_mfma_f32_16x16x32_bf16 v[44:47], v[96:99], v[140:143], v[44:47]
	v_mfma_f32_16x16x32_bf16 v[48:51], v[132:135], v[140:143], v[48:51]
	v_mfma_f32_16x16x32_bf16 v[60:63], v[96:99], v[150:153], v[60:63]
	v_mfma_f32_16x16x32_bf16 v[64:67], v[132:135], v[150:153], v[64:67]
	v_mfma_f32_16x16x32_bf16 v[68:71], v[96:99], v[158:161], v[68:71]
	v_mfma_f32_16x16x32_bf16 v[72:75], v[132:135], v[158:161], v[72:75]
	v_mfma_f32_16x16x32_bf16 v[52:55], v[96:99], v[166:169], v[52:55]
	v_mfma_f32_16x16x32_bf16 v[56:59], v[132:135], v[166:169], v[56:59]
	s_barrier
	s_mov_b64 s[26:27], 0x180
	s_mov_b32 m0, s9
	v_lshl_add_u64 v[76:77], v[32:33], 0, s[26:27]
	s_add_u32 s6, s6, 0x40180
	global_load_lds_dwordx4 v[76:77], off
	v_lshl_add_u64 v[76:77], v[34:35], 0, s[26:27]
	s_mov_b32 m0, s16
	s_addc_u32 s7, s7, 0
	global_load_lds_dwordx4 v[76:77], off
	v_lshl_add_u64 v[76:77], s[6:7], 0, v[128:129]
	s_mov_b32 m0, s18
	s_nop 0
	global_load_lds_dwordx4 v[76:77], off
	v_lshl_add_u64 v[76:77], s[6:7], 0, v[130:131]
	s_mov_b32 m0, s19
	s_nop 0
	global_load_lds_dwordx4 v[76:77], off
	v_lshl_add_u64 v[76:77], v[24:25], 0, s[26:27]
	s_mov_b32 m0, s14
	s_nop 0
	global_load_lds_dwordx4 v[76:77], off
	v_lshl_add_u64 v[76:77], v[22:23], 0, s[26:27]
	s_mov_b32 m0, s17
	s_nop 0
	global_load_lds_dwordx4 v[76:77], off
	s_waitcnt vmcnt(8)
	s_waitcnt lgkmcnt(0)
	s_barrier
	s_setprio 0
	s_barrier
	ds_read_b128 v[76:79], v172
	ds_read_b128 v[80:83], v172 offset:1024
	ds_read_b128 v[84:87], v172 offset:2048
	ds_read_b128 v[88:91], v172 offset:3072
	ds_read_b128 v[92:95], v145
	ds_read_b128 v[96:99], v145 offset:1024
	ds_read_b128 v[124:127], v145 offset:2048
	ds_read_b128 v[132:135], v145 offset:3072
	s_add_u32 s2, s2, 0x40180
	s_addc_u32 s3, s3, 0
	s_mov_b32 m0, s25
	v_lshl_add_u64 v[170:171], s[2:3], 0, v[128:129]
	ds_read_b128 v[136:139], v173
	ds_read_b128 v[140:143], v173 offset:1024
	ds_read_b128 v[146:149], v173 offset:2048
	ds_read_b128 v[150:153], v173 offset:3072
	ds_read_b128 v[154:157], v173 offset:4096
	ds_read_b128 v[158:161], v173 offset:5120
	ds_read_b128 v[162:165], v173 offset:6144
	ds_read_b128 v[166:169], v173 offset:7168
	global_load_lds_dwordx4 v[170:171], off
	v_lshl_add_u64 v[130:131], s[2:3], 0, v[130:131]
	s_mov_b32 m0, s22
	s_nop 0
	global_load_lds_dwordx4 v[130:131], off
	s_waitcnt vmcnt(8)
	s_waitcnt lgkmcnt(0)
	s_barrier
; #define PG8_STAGE(bufoff, gbase, voff) do { _Pragma("unroll") for (int _i = 0; _i < 2; ++_i) \
;         __builtin_amdgcn_global_load_lds((const unsigned*)((const char*)(gbase) + (voff)[_i]), (PG8_LAS unsigned*)(lds + (bufoff) + ldsw + _i * 8192), 16, 0, 0); } while (0)
; #define PG8_LDA(dst, b, h) do { _Pragma("unroll") for (int m = 0; m < 4; ++m) _Pragma("unroll") for (int k = 0; k < 2; ++k) dst[m][k] = *(const PG8_LAS bf16x8*)(lds + PG8_SA(b, h) + aoff + m * 2048 + k * 1024); } while (0)
; #define PG8_LDB(dst, b, h) do { _Pragma("unroll") for (int n = 0; n < 2; ++n) _Pragma("unroll") for (int k = 0; k < 2; ++k) dst[n][k] = *(const PG8_LAS bf16x8*)(lds + PG8_SB(b, h) + boff + n * 2048 + k * 1024); } while (0)
; #define PG8_MMA(ai, bj, At, Bt) do { __builtin_amdgcn_s_setprio(1); _Pragma("unroll") for (int m = 0; m < 4; ++m) _Pragma("unroll") for (int n = 0; n < 2; ++n) _Pragma("unroll") for (int k = 0; k < 2; ++k) \
;         acc[ai][bj][m][n] = __builtin_amdgcn_mfma_f32_16x16x32_bf16(Bt[n][k], At[m][k], acc[ai][bj][m][n], 0, 0, 0); __builtin_amdgcn_s_setprio(0); } while (0)
; #define PG8_WAIT_V(n) asm volatile("s_waitcnt vmcnt(" #n ")" ::: "memory")
; template <class Epi, class Sched, bool ALIGN_EPI = false, bool SP2 = false>
; __device__ __forceinline__ void gemm_phase(PG8_LAS unsigned char* lds, const Gemm g, const Sched& S, const Epi& E) {
;     ...
;             PG8_LDB(B0, 0, 0); PG8_LDB(B1, 0, 1); PG8_SCHED; PG8_LDA(At, 0, 0); PG8_STAGE(PG8_SA(1, 1), a1 + hstep, voffA);
;             PG8_WAIT_V(8); PG8_WAIT_L(0); PG8_BAR; PG8_MMA(0, 0, At, B0); PG8_MMA(0, 1, At, B1); PG8_BAR; PG8_SCHED;
;             PG8_LDA(At, 0, 1); PG8_STAGE(PG8_SB(0, 0), b2, voffB); PG8_STAGE(PG8_SB(0, 1), b2 + hstep, voffB); PG8_STAGE(PG8_SA(0, 0), a2, voffA);
;             PG8_WAIT_V(8); PG8_WAIT_L(0); PG8_BAR; PG8_MMA(1, 0, At, B0); PG8_MMA(1, 1, At, B1); PG8_BAR; PG8_SCHED;
;             PG8_LDB(B0, 1, 0); PG8_LDB(B1, 1, 1); PG8_SCHED; PG8_LDA(At, 1, 0); PG8_STAGE(PG8_SA(0, 1), a2 + hstep, voffA);
;             PG8_WAIT_V(8); PG8_WAIT_L(0); PG8_BAR; PG8_MMA(0, 0, At, B0); PG8_MMA(0, 1, At, B1); PG8_BAR; PG8_SCHED;
;             PG8_LDA(At, 1, 1); PG8_STAGE(PG8_SB(1, 0), b3, voffB); PG8_STAGE(PG8_SB(1, 1), b3 + hstep, voffB); PG8_STAGE(PG8_SA(1, 0), a3, voffA);
;             PG8_WAIT_V(8); PG8_WAIT_L(0); PG8_BAR; PG8_MMA(1, 0, At, B0); PG8_MMA(1, 1, At, B1); PG8_BAR; PG8_SCHED;
	s_waitcnt lgkmcnt(0)
	v_mfma_f32_16x16x32_bf16 v[100:103], v[76:79], v[136:139], v[100:103]
	v_mfma_f32_16x16x32_bf16 v[104:107], v[84:87], v[136:139], v[104:107]
	v_mfma_f32_16x16x32_bf16 v[108:111], v[76:79], v[146:149], v[108:111]
	v_mfma_f32_16x16x32_bf16 v[112:115], v[84:87], v[146:149], v[112:115]
	v_mfma_f32_16x16x32_bf16 v[116:119], v[76:79], v[154:157], v[116:119]
	v_mfma_f32_16x16x32_bf16 v[120:123], v[84:87], v[154:157], v[120:123]
	v_mfma_f32_16x16x32_bf16 v[36:39], v[76:79], v[162:165], v[36:39]
	v_mfma_f32_16x16x32_bf16 v[40:43], v[84:87], v[162:165], v[40:43]
	v_mfma_f32_16x16x32_bf16 v[100:103], v[80:83], v[140:143], v[100:103]
	v_mfma_f32_16x16x32_bf16 v[104:107], v[88:91], v[140:143], v[104:107]
	v_mfma_f32_16x16x32_bf16 v[108:111], v[80:83], v[150:153], v[108:111]
	v_mfma_f32_16x16x32_bf16 v[112:115], v[88:91], v[150:153], v[112:115]
	v_mfma_f32_16x16x32_bf16 v[116:119], v[80:83], v[158:161], v[116:119]
	v_mfma_f32_16x16x32_bf16 v[120:123], v[88:91], v[158:161], v[120:123]
	v_mfma_f32_16x16x32_bf16 v[36:39], v[80:83], v[166:169], v[36:39]
	v_mfma_f32_16x16x32_bf16 v[40:43], v[88:91], v[166:169], v[40:43]
	v_mfma_f32_16x16x32_bf16 v[44:47], v[92:95], v[136:139], v[44:47]
	v_mfma_f32_16x16x32_bf16 v[48:51], v[124:127], v[136:139], v[48:51]
	v_mfma_f32_16x16x32_bf16 v[60:63], v[92:95], v[146:149], v[60:63]
	v_mfma_f32_16x16x32_bf16 v[64:67], v[124:127], v[146:149], v[64:67]
	v_mfma_f32_16x16x32_bf16 v[68:71], v[92:95], v[154:157], v[68:71]
	v_mfma_f32_16x16x32_bf16 v[72:75], v[124:127], v[154:157], v[72:75]
	v_mfma_f32_16x16x32_bf16 v[52:55], v[92:95], v[162:165], v[52:55]
	v_mfma_f32_16x16x32_bf16 v[56:59], v[124:127], v[162:165], v[56:59]
	v_mfma_f32_16x16x32_bf16 v[44:47], v[96:99], v[140:143], v[44:47]
	v_mfma_f32_16x16x32_bf16 v[48:51], v[132:135], v[140:143], v[48:51]
	v_mfma_f32_16x16x32_bf16 v[60:63], v[96:99], v[150:153], v[60:63]
	v_mfma_f32_16x16x32_bf16 v[64:67], v[132:135], v[150:153], v[64:67]
	v_mfma_f32_16x16x32_bf16 v[68:71], v[96:99], v[158:161], v[68:71]
	v_mfma_f32_16x16x32_bf16 v[72:75], v[132:135], v[158:161], v[72:75]
	v_mfma_f32_16x16x32_bf16 v[52:55], v[96:99], v[166:169], v[52:55]
	v_mfma_f32_16x16x32_bf16 v[56:59], v[132:135], v[166:169], v[56:59]
	s_barrier
	s_mov_b32 m0, s23
	s_nop 0
	global_load_lds_dwordx4 v[32:33], off
	s_mov_b32 m0, s24
	s_nop 0
	global_load_lds_dwordx4 v[34:35], off
	s_mov_b32 m0, s21
	s_nop 0
	global_load_lds_dwordx4 v[30:31], off
	s_mov_b32 m0, s33
	s_nop 0
	global_load_lds_dwordx4 v[26:27], off
	s_mov_b32 m0, s12
	s_nop 0
	global_load_lds_dwordx4 v[24:25], off
	s_mov_b32 m0, s20
	s_nop 0
	global_load_lds_dwordx4 v[22:23], off
	s_waitcnt vmcnt(8)
	s_waitcnt lgkmcnt(0)
	s_barrier
	s_setprio 0
	s_barrier
	ds_read_b128 v[22:25], v175
	ds_read_b128 v[30:33], v175 offset:1024
	ds_read_b128 v[76:79], v175 offset:2048
	ds_read_b128 v[80:83], v175 offset:3072
	ds_read_b128 v[84:87], v174
	ds_read_b128 v[88:91], v174 offset:1024
	ds_read_b128 v[92:95], v174 offset:2048
	ds_read_b128 v[96:99], v174 offset:3072
	s_mov_b32 m0, s13
	ds_read_b128 v[124:127], v173 offset:32768
	ds_read_b128 v[130:133], v173 offset:33792
	ds_read_b128 v[134:137], v173 offset:34816
	ds_read_b128 v[138:141], v173 offset:35840
	ds_read_b128 v[146:149], v173 offset:36864
	ds_read_b128 v[150:153], v173 offset:37888
	ds_read_b128 v[154:157], v173 offset:38912
	ds_read_b128 v[158:161], v173 offset:39936
	global_load_lds_dwordx4 v[12:13], off
	s_mov_b32 m0, s15
	s_nop 0
	global_load_lds_dwordx4 v[14:15], off
	s_waitcnt vmcnt(8)
	s_waitcnt lgkmcnt(0)
	s_barrier
; #define PG8_STAGE(bufoff, gbase, voff) do { _Pragma("unroll") for (int _i = 0; _i < 2; ++_i) \
;         __builtin_amdgcn_global_load_lds((const unsigned*)((const char*)(gbase) + (voff)[_i]), (PG8_LAS unsigned*)(lds + (bufoff) + ldsw + _i * 8192), 16, 0, 0); } while (0)
; #define PG8_LDA(dst, b, h) do { _Pragma("unroll") for (int m = 0; m < 4; ++m) _Pragma("unroll") for (int k = 0; k < 2; ++k) dst[m][k] = *(const PG8_LAS bf16x8*)(lds + PG8_SA(b, h) + aoff + m * 2048 + k * 1024); } while (0)
; #define PG8_LDB(dst, b, h) do { _Pragma("unroll") for (int n = 0; n < 2; ++n) _Pragma("unroll") for (int k = 0; k < 2; ++k) dst[n][k] = *(const PG8_LAS bf16x8*)(lds + PG8_SB(b, h) + boff + n * 2048 + k * 1024); } while (0)
; #define PG8_WAIT_V(n) asm volatile("s_waitcnt vmcnt(" #n ")" ::: "memory")
; #define PG8_WAIT_L(n) asm volatile("s_waitcnt lgkmcnt(" #n ")" ::: "memory")
; #define PG8_BAR __builtin_amdgcn_s_barrier()
; #define PG8_SCHED __builtin_amdgcn_sched_barrier(0)
; template <class Epi, class Sched, bool ALIGN_EPI = false, bool SP2 = false>
; __device__ __forceinline__ void gemm_phase(PG8_LAS unsigned char* lds, const Gemm g, const Sched& S, const Epi& E) {
;     ...
;             PG8_WAIT_V(8); PG8_WAIT_L(0); PG8_BAR; PG8_MMA(1, 0, At, B0); PG8_MMA(1, 1, At, B1); PG8_BAR; PG8_SCHED;
;             PG8_LDB(B0, 1, 0); PG8_LDB(B1, 1, 1); PG8_SCHED; PG8_LDA(At, 1, 0); PG8_STAGE(PG8_SA(0, 1), a2 + hstep, voffA);
;             PG8_WAIT_V(8); PG8_WAIT_L(0); PG8_BAR; PG8_MMA(0, 0, At, B0); PG8_MMA(0, 1, At, B1); PG8_BAR; PG8_SCHED;
;             PG8_LDA(At, 1, 1); PG8_STAGE(PG8_SB(1, 0), b3, voffB); PG8_STAGE(PG8_SB(1, 1), b3 + hstep, voffB); PG8_STAGE(PG8_SA(1, 0), a3, voffA);
;             PG8_WAIT_V(8); PG8_WAIT_L(0); PG8_BAR; PG8_MMA(1, 0, At, B0); PG8_MMA(1, 1, At, B1); PG8_BAR; PG8_SCHED;
;     __device__ __forceinline__ void operator()(const f32x4 (&acc)[2][2][4][2], const Unit& u, int wr, int wc, int fr, int fq) const {
;         const int col0 = u.pn * 256 + wc * 32 + 4 * fq;
; #pragma unroll
;         for (int m = 0; m < 4; ++m) {
;             const int row = wr * 64 + m * 16 + fr;
; #pragma unroll
;             for (int bj = 0; bj < 2; ++bj)
; #pragma unroll
;                 for (int n = 0; n < 2; ++n) *(f32x4*)(O + (size_t)row * DM + col0 + bj * 128 + n * 16) = acc[0][bj][m][n];
;             asm volatile("" ::: "memory");
;         }
	s_waitcnt lgkmcnt(0)
	v_mfma_f32_16x16x32_bf16 v[12:15], v[22:25], v[124:127], v[100:103]
	v_mfma_f32_16x16x32_bf16 v[100:103], v[76:79], v[124:127], v[104:107]
	v_mfma_f32_16x16x32_bf16 v[104:107], v[22:25], v[134:137], v[108:111]
	v_mfma_f32_16x16x32_bf16 v[108:111], v[76:79], v[134:137], v[112:115]
	v_mfma_f32_16x16x32_bf16 v[112:115], v[22:25], v[146:149], v[116:119]
	v_mfma_f32_16x16x32_bf16 v[22:25], v[22:25], v[154:157], v[36:39]
	v_mfma_f32_16x16x32_bf16 v[12:15], v[30:33], v[130:133], v[12:15]
	v_mfma_f32_16x16x32_bf16 v[104:107], v[30:33], v[138:141], v[104:107]
	v_mfma_f32_16x16x32_bf16 v[112:115], v[30:33], v[150:153], v[112:115]
	v_mfma_f32_16x16x32_bf16 v[116:119], v[76:79], v[146:149], v[120:123]
	v_mfma_f32_16x16x32_bf16 v[22:25], v[30:33], v[158:161], v[22:25]
	v_mfma_f32_16x16x32_bf16 v[30:33], v[76:79], v[154:157], v[40:43]
	v_mfma_f32_16x16x32_bf16 v[100:103], v[80:83], v[130:133], v[100:103]
	v_mfma_f32_16x16x32_bf16 v[108:111], v[80:83], v[138:141], v[108:111]
	v_mfma_f32_16x16x32_bf16 v[116:119], v[80:83], v[150:153], v[116:119]
	v_mfma_f32_16x16x32_bf16 v[30:33], v[80:83], v[158:161], v[30:33]
	v_mfma_f32_16x16x32_bf16 v[34:37], v[84:87], v[124:127], v[44:47]
	v_mfma_f32_16x16x32_bf16 v[38:41], v[92:95], v[124:127], v[48:51]
	v_mfma_f32_16x16x32_bf16 v[42:45], v[84:87], v[134:137], v[60:63]
	v_mfma_f32_16x16x32_bf16 v[46:49], v[92:95], v[134:137], v[64:67]
	v_mfma_f32_16x16x32_bf16 v[60:63], v[84:87], v[146:149], v[68:71]
	v_mfma_f32_16x16x32_bf16 v[64:67], v[92:95], v[146:149], v[72:75]
	v_mfma_f32_16x16x32_bf16 v[50:53], v[84:87], v[154:157], v[52:55]
	v_mfma_f32_16x16x32_bf16 v[54:57], v[92:95], v[154:157], v[56:59]
	v_mfma_f32_16x16x32_bf16 v[34:37], v[88:91], v[130:133], v[34:37]
	v_mfma_f32_16x16x32_bf16 v[38:41], v[96:99], v[130:133], v[38:41]
	v_mfma_f32_16x16x32_bf16 v[42:45], v[88:91], v[138:141], v[42:45]
	v_mfma_f32_16x16x32_bf16 v[46:49], v[96:99], v[138:141], v[46:49]
	v_mfma_f32_16x16x32_bf16 v[60:63], v[88:91], v[150:153], v[60:63]
	v_mfma_f32_16x16x32_bf16 v[64:67], v[96:99], v[150:153], v[64:67]
	v_mfma_f32_16x16x32_bf16 v[50:53], v[88:91], v[158:161], v[50:53]
	v_mfma_f32_16x16x32_bf16 v[54:57], v[96:99], v[158:161], v[54:57]
	s_barrier
	s_mov_b32 m0, s9
	s_nop 0
	global_load_lds_dwordx4 v[4:5], off
	s_mov_b32 m0, s16
	s_nop 0
	global_load_lds_dwordx4 v[6:7], off
	s_mov_b32 m0, s18
	s_nop 0
	global_load_lds_dwordx4 v[16:17], off
	s_mov_b32 m0, s19
	s_nop 0
	global_load_lds_dwordx4 v[18:19], off
	s_mov_b32 m0, s14
	s_nop 0
	global_load_lds_dwordx4 v[2:3], off
	s_mov_b32 m0, s17
	s_nop 0
	global_load_lds_dwordx4 v[8:9], off
	s_waitcnt vmcnt(8)
	s_waitcnt lgkmcnt(0)
	s_barrier
	s_setprio 0
	s_barrier
	s_lshl_b32 s2, s11, 8
	v_lshl_or_b32 v2, v144, 2, s2
	v_or_b32_e32 v2, s8, v2
	v_lshlrev_b32_e32 v128, 2, v2
	v_lshl_add_u64 v[2:3], v[28:29], 0, v[128:129]
	global_store_dwordx4 v[2:3], v[12:15], off
	global_store_dwordx4 v[2:3], v[100:103], off offset:64
	global_store_dwordx4 v[2:3], v[34:37], off offset:512
	global_store_dwordx4 v[2:3], v[38:41], off offset:576
	v_lshl_add_u64 v[2:3], v[20:21], 0, v[128:129]
	global_store_dwordx4 v[2:3], v[104:107], off
	global_store_dwordx4 v[2:3], v[108:111], off offset:64
	global_store_dwordx4 v[2:3], v[42:45], off offset:512
	global_store_dwordx4 v[2:3], v[46:49], off offset:576
	v_lshl_add_u64 v[2:3], v[10:11], 0, v[128:129]
	global_store_dwordx4 v[2:3], v[112:115], off
	global_store_dwordx4 v[2:3], v[116:119], off offset:64
	global_store_dwordx4 v[2:3], v[60:63], off offset:512
	global_store_dwordx4 v[2:3], v[64:67], off offset:576
	v_lshl_add_u64 v[0:1], v[0:1], 0, v[128:129]
	global_store_dwordx4 v[0:1], v[22:25], off
	global_store_dwordx4 v[0:1], v[30:33], off offset:64
	global_store_dwordx4 v[0:1], v[50:53], off offset:512
	global_store_dwordx4 v[0:1], v[54:57], off offset:576
	s_waitcnt vmcnt(0)
	s_cmpk_gt_u32 s10, 0xff
	s_cbranch_scc1 .LBB0_2150
	s_barrier

; #define PG8_STAGE(bufoff, gbase, voff) do { _Pragma("unroll") for (int _i = 0; _i < 2; ++_i) \
;         __builtin_amdgcn_global_load_lds((const unsigned*)((const char*)(gbase) + (voff)[_i]), (PG8_LAS unsigned*)(lds + (bufoff) + ldsw + _i * 8192), 16, 0, 0); } while (0)
; #define PG8_LDA(dst, b, h) do { _Pragma("unroll") for (int m = 0; m < 4; ++m) _Pragma("unroll") for (int k = 0; k < 2; ++k) dst[m][k] = *(const PG8_LAS bf16x8*)(lds + PG8_SA(b, h) + aoff + m * 2048 + k * 1024); } while (0)
; #define PG8_LDB(dst, b, h) do { _Pragma("unroll") for (int n = 0; n < 2; ++n) _Pragma("unroll") for (int k = 0; k < 2; ++k) dst[n][k] = *(const PG8_LAS bf16x8*)(lds + PG8_SB(b, h) + boff + n * 2048 + k * 1024); } while (0)
; #define PG8_MMA(ai, bj, At, Bt) do { __builtin_amdgcn_s_setprio(1); _Pragma("unroll") for (int m = 0; m < 4; ++m) _Pragma("unroll") for (int n = 0; n < 2; ++n) _Pragma("unroll") for (int k = 0; k < 2; ++k) \
;         acc[ai][bj][m][n] = __builtin_amdgcn_mfma_f32_16x16x32_bf16(Bt[n][k], At[m][k], acc[ai][bj][m][n], 0, 0, 0); __builtin_amdgcn_s_setprio(0); } while (0)
; #define PG8_WAIT_V(n) asm volatile("s_waitcnt vmcnt(" #n ")" ::: "memory")
; template <class Epi, class Sched, bool ALIGN_EPI = false, bool SP2 = false>
; __device__ __forceinline__ void gemm_phase(PG8_LAS unsigned char* lds, const Gemm g, const Sched& S, const Epi& E) {
;     ...
;             PG8_LDB(B0, 0, 0); PG8_LDB(B1, 0, 1); PG8_SCHED; PG8_LDA(At, 0, 0); PG8_STAGE(PG8_SA(1, 1), a1 + hstep, voffA);
;             PG8_WAIT_V(8); PG8_WAIT_L(0); PG8_BAR; PG8_MMA(0, 0, At, B0); PG8_MMA(0, 1, At, B1); PG8_BAR; PG8_SCHED;
;             PG8_LDA(At, 0, 1); PG8_STAGE(PG8_SB(0, 0), b2, voffB); PG8_STAGE(PG8_SB(0, 1), b2 + hstep, voffB); PG8_STAGE(PG8_SA(0, 0), a2, voffA);
;             PG8_WAIT_V(8); PG8_WAIT_L(0); PG8_BAR; PG8_MMA(1, 0, At, B0); PG8_MMA(1, 1, At, B1); PG8_BAR; PG8_SCHED;
;             PG8_LDB(B0, 1, 0); PG8_LDB(B1, 1, 1); PG8_SCHED; PG8_LDA(At, 1, 0); PG8_STAGE(PG8_SA(0, 1), a2 + hstep, voffA);
;             PG8_WAIT_V(8); PG8_WAIT_L(0); PG8_BAR; PG8_MMA(0, 0, At, B0); PG8_MMA(0, 1, At, B1); PG8_BAR; PG8_SCHED;
;             PG8_LDA(At, 1, 1); PG8_STAGE(PG8_SB(1, 0), b3, voffB); PG8_STAGE(PG8_SB(1, 1), b3 + hstep, voffB); PG8_STAGE(PG8_SA(1, 0), a3, voffA);
;             PG8_WAIT_V(8); PG8_WAIT_L(0); PG8_BAR; PG8_MMA(1, 0, At, B0); PG8_MMA(1, 1, At, B1); PG8_BAR; PG8_SCHED;
.LBB0_2328:
	ds_read_b128 v[156:159], v152
	ds_read_b128 v[160:163], v152 offset:1024
	ds_read_b128 v[164:167], v152 offset:2048
	ds_read_b128 v[168:171], v152 offset:3072
	ds_read_b128 v[172:175], v153
	ds_read_b128 v[176:179], v153 offset:1024
	ds_read_b128 v[182:185], v153 offset:2048
	ds_read_b128 v[186:189], v153 offset:3072
	s_add_u32 s40, s26, 0xfffc0080
	s_addc_u32 s41, s27, -1
	s_cmp_eq_u32 s62, 12
	s_cselect_b32 s43, s17, s41
	s_cselect_b32 s42, s23, s40
	s_cselect_b32 s41, s15, s61
	s_cselect_b32 s40, s59, s60
	v_lshl_add_u64 v[144:145], s[26:27], 0, v[136:137]
	s_add_i32 m0, s25, 0xc000
	ds_read_b128 v[190:193], v154
	ds_read_b128 v[194:197], v154 offset:1024
	ds_read_b128 v[198:201], v154 offset:2048
	ds_read_b128 v[202:205], v154 offset:3072
	ds_read_b128 v[206:209], v154 offset:4096
	ds_read_b128 v[210:213], v154 offset:5120
	ds_read_b128 v[214:217], v154 offset:6144
	ds_read_b128 v[218:221], v154 offset:7168
	global_load_lds_dwordx4 v[144:145], off
	v_lshl_add_u64 v[144:145], s[26:27], 0, v[138:139]
	s_add_i32 m0, s25, 0xe000
	s_nop 0
	global_load_lds_dwordx4 v[144:145], off
	s_waitcnt vmcnt(8)
	s_waitcnt lgkmcnt(0)
	s_barrier
	s_waitcnt lgkmcnt(0)
	v_mfma_f32_16x16x32_bf16 v[124:127], v[156:159], v[190:193], v[124:127]
	v_mfma_f32_16x16x32_bf16 v[120:123], v[164:167], v[190:193], v[120:123]
	v_mfma_f32_16x16x32_bf16 v[108:111], v[156:159], v[198:201], v[108:111]
	v_mfma_f32_16x16x32_bf16 v[104:107], v[164:167], v[198:201], v[104:107]
	v_mfma_f32_16x16x32_bf16 v[92:95], v[156:159], v[206:209], v[92:95]
	v_mfma_f32_16x16x32_bf16 v[88:91], v[164:167], v[206:209], v[88:91]
	v_mfma_f32_16x16x32_bf16 v[76:79], v[156:159], v[214:217], v[76:79]
	v_mfma_f32_16x16x32_bf16 v[72:75], v[164:167], v[214:217], v[72:75]
	v_mfma_f32_16x16x32_bf16 v[124:127], v[160:163], v[194:197], v[124:127]
	v_mfma_f32_16x16x32_bf16 v[120:123], v[168:171], v[194:197], v[120:123]
	v_mfma_f32_16x16x32_bf16 v[108:111], v[160:163], v[202:205], v[108:111]
	v_mfma_f32_16x16x32_bf16 v[104:107], v[168:171], v[202:205], v[104:107]
	v_mfma_f32_16x16x32_bf16 v[92:95], v[160:163], v[210:213], v[92:95]
	v_mfma_f32_16x16x32_bf16 v[88:91], v[168:171], v[210:213], v[88:91]
	v_mfma_f32_16x16x32_bf16 v[76:79], v[160:163], v[218:221], v[76:79]
	v_mfma_f32_16x16x32_bf16 v[72:75], v[168:171], v[218:221], v[72:75]
	v_mfma_f32_16x16x32_bf16 v[116:119], v[172:175], v[190:193], v[116:119]
	v_mfma_f32_16x16x32_bf16 v[112:115], v[182:185], v[190:193], v[112:115]
	v_mfma_f32_16x16x32_bf16 v[100:103], v[172:175], v[198:201], v[100:103]
	v_mfma_f32_16x16x32_bf16 v[96:99], v[182:185], v[198:201], v[96:99]
	v_mfma_f32_16x16x32_bf16 v[84:87], v[172:175], v[206:209], v[84:87]
	v_mfma_f32_16x16x32_bf16 v[80:83], v[182:185], v[206:209], v[80:83]
	v_mfma_f32_16x16x32_bf16 v[68:71], v[172:175], v[214:217], v[68:71]
	v_mfma_f32_16x16x32_bf16 v[64:67], v[182:185], v[214:217], v[64:67]
	v_mfma_f32_16x16x32_bf16 v[116:119], v[176:179], v[194:197], v[116:119]
	v_mfma_f32_16x16x32_bf16 v[112:115], v[186:189], v[194:197], v[112:115]
	v_mfma_f32_16x16x32_bf16 v[100:103], v[176:179], v[202:205], v[100:103]
	v_mfma_f32_16x16x32_bf16 v[96:99], v[186:189], v[202:205], v[96:99]
	v_mfma_f32_16x16x32_bf16 v[84:87], v[176:179], v[210:213], v[84:87]
	v_mfma_f32_16x16x32_bf16 v[80:83], v[186:189], v[210:213], v[80:83]
	v_mfma_f32_16x16x32_bf16 v[68:71], v[176:179], v[218:221], v[68:71]
	v_mfma_f32_16x16x32_bf16 v[64:67], v[186:189], v[218:221], v[64:67]
	s_barrier
	s_add_i32 s63, s55, s45
	v_lshl_add_u64 v[144:145], s[40:41], 0, v[130:131]
	s_mov_b32 m0, s63
	ds_read_b128 v[190:193], v154 offset:16384
	ds_read_b128 v[194:197], v154 offset:17408
	ds_read_b128 v[198:201], v154 offset:18432
	ds_read_b128 v[202:205], v154 offset:19456
	ds_read_b128 v[206:209], v154 offset:20480
	ds_read_b128 v[210:213], v154 offset:21504
	ds_read_b128 v[214:217], v154 offset:22528
	ds_read_b128 v[218:221], v154 offset:23552
	global_load_lds_dwordx4 v[144:145], off
	s_add_i32 m0, s63, 0x2000
	s_add_u32 s64, s40, 0x40000
	v_lshl_add_u64 v[222:223], s[40:41], 0, v[134:135]
	s_addc_u32 s65, s41, 0
	s_add_i32 s63, s56, s45
	global_load_lds_dwordx4 v[222:223], off
	v_lshl_add_u64 v[224:225], s[64:65], 0, v[130:131]
	s_mov_b32 m0, s63
	v_lshl_add_u64 v[226:227], s[42:43], 0, v[132:133]
	global_load_lds_dwordx4 v[224:225], off
	v_lshl_add_u64 v[224:225], s[64:65], 0, v[134:135]
	s_add_i32 m0, s63, 0x2000
	s_nop 0
	global_load_lds_dwordx4 v[224:225], off
	v_lshl_add_u64 v[224:225], s[42:43], 0, v[128:129]
	s_mov_b32 m0, s25
	s_nop 0
	global_load_lds_dwordx4 v[224:225], off
	s_mov_b32 m0, s46
	s_nop 0
	global_load_lds_dwordx4 v[226:227], off
	s_waitcnt vmcnt(8)
	s_waitcnt lgkmcnt(0)
	s_barrier
; #define PG8_STAGE(bufoff, gbase, voff) do { _Pragma("unroll") for (int _i = 0; _i < 2; ++_i) \
;         __builtin_amdgcn_global_load_lds((const unsigned*)((const char*)(gbase) + (voff)[_i]), (PG8_LAS unsigned*)(lds + (bufoff) + ldsw + _i * 8192), 16, 0, 0); } while (0)
; #define PG8_LDA(dst, b, h) do { _Pragma("unroll") for (int m = 0; m < 4; ++m) _Pragma("unroll") for (int k = 0; k < 2; ++k) dst[m][k] = *(const PG8_LAS bf16x8*)(lds + PG8_SA(b, h) + aoff + m * 2048 + k * 1024); } while (0)
; #define PG8_LDB(dst, b, h) do { _Pragma("unroll") for (int n = 0; n < 2; ++n) _Pragma("unroll") for (int k = 0; k < 2; ++k) dst[n][k] = *(const PG8_LAS bf16x8*)(lds + PG8_SB(b, h) + boff + n * 2048 + k * 1024); } while (0)
; #define PG8_MMA(ai, bj, At, Bt) do { __builtin_amdgcn_s_setprio(1); _Pragma("unroll") for (int m = 0; m < 4; ++m) _Pragma("unroll") for (int n = 0; n < 2; ++n) _Pragma("unroll") for (int k = 0; k < 2; ++k) \
;         acc[ai][bj][m][n] = __builtin_amdgcn_mfma_f32_16x16x32_bf16(Bt[n][k], At[m][k], acc[ai][bj][m][n], 0, 0, 0); __builtin_amdgcn_s_setprio(0); } while (0)
; #define PG8_WAIT_V(n) asm volatile("s_waitcnt vmcnt(" #n ")" ::: "memory")
; template <class Epi, class Sched, bool ALIGN_EPI = false, bool SP2 = false>
; __device__ __forceinline__ void gemm_phase(PG8_LAS unsigned char* lds, const Gemm g, const Sched& S, const Epi& E) {
;     ...
;             PG8_LDB(B0, 0, 0); PG8_LDB(B1, 0, 1); PG8_SCHED; PG8_LDA(At, 0, 0); PG8_STAGE(PG8_SA(1, 1), a1 + hstep, voffA);
;             PG8_WAIT_V(8); PG8_WAIT_L(0); PG8_BAR; PG8_MMA(0, 0, At, B0); PG8_MMA(0, 1, At, B1); PG8_BAR; PG8_SCHED;
;             PG8_LDA(At, 0, 1); PG8_STAGE(PG8_SB(0, 0), b2, voffB); PG8_STAGE(PG8_SB(0, 1), b2 + hstep, voffB); PG8_STAGE(PG8_SA(0, 0), a2, voffA);
;             PG8_WAIT_V(8); PG8_WAIT_L(0); PG8_BAR; PG8_MMA(1, 0, At, B0); PG8_MMA(1, 1, At, B1); PG8_BAR; PG8_SCHED;
;             PG8_LDB(B0, 1, 0); PG8_LDB(B1, 1, 1); PG8_SCHED; PG8_LDA(At, 1, 0); PG8_STAGE(PG8_SA(0, 1), a2 + hstep, voffA);
;             PG8_WAIT_V(8); PG8_WAIT_L(0); PG8_BAR; PG8_MMA(0, 0, At, B0); PG8_MMA(0, 1, At, B1); PG8_BAR; PG8_SCHED;
;             PG8_LDA(At, 1, 1); PG8_STAGE(PG8_SB(1, 0), b3, voffB); PG8_STAGE(PG8_SB(1, 1), b3 + hstep, voffB); PG8_STAGE(PG8_SA(1, 0), a3, voffA);
;             PG8_WAIT_V(8); PG8_WAIT_L(0); PG8_BAR; PG8_MMA(1, 0, At, B0); PG8_MMA(1, 1, At, B1); PG8_BAR; PG8_SCHED;
	s_waitcnt lgkmcnt(0)
	v_mfma_f32_16x16x32_bf16 v[60:63], v[156:159], v[190:193], v[60:63]
	v_mfma_f32_16x16x32_bf16 v[56:59], v[164:167], v[190:193], v[56:59]
	v_mfma_f32_16x16x32_bf16 v[44:47], v[156:159], v[198:201], v[44:47]
	v_mfma_f32_16x16x32_bf16 v[40:43], v[164:167], v[198:201], v[40:43]
	v_mfma_f32_16x16x32_bf16 v[28:31], v[156:159], v[206:209], v[28:31]
	v_mfma_f32_16x16x32_bf16 v[24:27], v[164:167], v[206:209], v[24:27]
	v_mfma_f32_16x16x32_bf16 v[12:15], v[156:159], v[214:217], v[12:15]
	v_mfma_f32_16x16x32_bf16 v[8:11], v[164:167], v[214:217], v[8:11]
	v_mfma_f32_16x16x32_bf16 v[60:63], v[160:163], v[194:197], v[60:63]
	v_mfma_f32_16x16x32_bf16 v[56:59], v[168:171], v[194:197], v[56:59]
	v_mfma_f32_16x16x32_bf16 v[44:47], v[160:163], v[202:205], v[44:47]
	v_mfma_f32_16x16x32_bf16 v[40:43], v[168:171], v[202:205], v[40:43]
	v_mfma_f32_16x16x32_bf16 v[28:31], v[160:163], v[210:213], v[28:31]
	v_mfma_f32_16x16x32_bf16 v[24:27], v[168:171], v[210:213], v[24:27]
	v_mfma_f32_16x16x32_bf16 v[12:15], v[160:163], v[218:221], v[12:15]
	v_mfma_f32_16x16x32_bf16 v[8:11], v[168:171], v[218:221], v[8:11]
	v_mfma_f32_16x16x32_bf16 v[52:55], v[172:175], v[190:193], v[52:55]
	v_mfma_f32_16x16x32_bf16 v[48:51], v[182:185], v[190:193], v[48:51]
	v_mfma_f32_16x16x32_bf16 v[36:39], v[172:175], v[198:201], v[36:39]
	v_mfma_f32_16x16x32_bf16 v[32:35], v[182:185], v[198:201], v[32:35]
	v_mfma_f32_16x16x32_bf16 v[20:23], v[172:175], v[206:209], v[20:23]
	v_mfma_f32_16x16x32_bf16 v[16:19], v[182:185], v[206:209], v[16:19]
	v_mfma_f32_16x16x32_bf16 v[4:7], v[172:175], v[214:217], v[4:7]
	v_mfma_f32_16x16x32_bf16 v[0:3], v[182:185], v[214:217], v[0:3]
	v_mfma_f32_16x16x32_bf16 v[52:55], v[176:179], v[194:197], v[52:55]
	v_mfma_f32_16x16x32_bf16 v[48:51], v[186:189], v[194:197], v[48:51]
	v_mfma_f32_16x16x32_bf16 v[36:39], v[176:179], v[202:205], v[36:39]
	v_mfma_f32_16x16x32_bf16 v[32:35], v[186:189], v[202:205], v[32:35]
	v_mfma_f32_16x16x32_bf16 v[20:23], v[176:179], v[210:213], v[20:23]
	v_mfma_f32_16x16x32_bf16 v[16:19], v[186:189], v[210:213], v[16:19]
	v_mfma_f32_16x16x32_bf16 v[4:7], v[176:179], v[218:221], v[4:7]
	v_mfma_f32_16x16x32_bf16 v[0:3], v[186:189], v[218:221], v[0:3]
	s_barrier
	s_add_i32 s63, 0, 0x18000
	v_add_u32_e32 v155, s63, v147
	s_add_i32 s64, 0, 0x1c000
	ds_read_b128 v[156:159], v155
	ds_read_b128 v[160:163], v155 offset:1024
	ds_read_b128 v[164:167], v155 offset:2048
	ds_read_b128 v[168:171], v155 offset:3072
	v_add_u32_e32 v155, s64, v147
	ds_read_b128 v[172:175], v155
	ds_read_b128 v[176:179], v155 offset:1024
	ds_read_b128 v[182:185], v155 offset:2048
	ds_read_b128 v[186:189], v155 offset:3072
	s_add_u32 s42, s42, 0x40000
	s_addc_u32 s43, s43, 0
	s_mov_b32 m0, s47
	v_lshl_add_u64 v[228:229], s[42:43], 0, v[128:129]
	ds_read_b128 v[190:193], v154 offset:32768
	ds_read_b128 v[194:197], v154 offset:33792
	ds_read_b128 v[198:201], v154 offset:34816
	ds_read_b128 v[202:205], v154 offset:35840
	ds_read_b128 v[206:209], v154 offset:36864
	ds_read_b128 v[210:213], v154 offset:37888
	ds_read_b128 v[214:217], v154 offset:38912
	ds_read_b128 v[218:221], v154 offset:39936
	global_load_lds_dwordx4 v[228:229], off
	v_lshl_add_u64 v[228:229], s[42:43], 0, v[132:133]
	s_mov_b32 m0, s48
	s_nop 0
	global_load_lds_dwordx4 v[228:229], off
	s_waitcnt vmcnt(8)
	s_waitcnt lgkmcnt(0)
	s_barrier
	s_waitcnt lgkmcnt(0)
	v_mfma_f32_16x16x32_bf16 v[124:127], v[156:159], v[190:193], v[124:127]
	v_mfma_f32_16x16x32_bf16 v[120:123], v[164:167], v[190:193], v[120:123]
	v_mfma_f32_16x16x32_bf16 v[108:111], v[156:159], v[198:201], v[108:111]
	v_mfma_f32_16x16x32_bf16 v[104:107], v[164:167], v[198:201], v[104:107]
	v_mfma_f32_16x16x32_bf16 v[92:95], v[156:159], v[206:209], v[92:95]
	v_mfma_f32_16x16x32_bf16 v[88:91], v[164:167], v[206:209], v[88:91]
	v_mfma_f32_16x16x32_bf16 v[76:79], v[156:159], v[214:217], v[76:79]
	v_mfma_f32_16x16x32_bf16 v[72:75], v[164:167], v[214:217], v[72:75]
	v_mfma_f32_16x16x32_bf16 v[124:127], v[160:163], v[194:197], v[124:127]
	v_mfma_f32_16x16x32_bf16 v[120:123], v[168:171], v[194:197], v[120:123]
	v_mfma_f32_16x16x32_bf16 v[108:111], v[160:163], v[202:205], v[108:111]
	v_mfma_f32_16x16x32_bf16 v[104:107], v[168:171], v[202:205], v[104:107]
	v_mfma_f32_16x16x32_bf16 v[92:95], v[160:163], v[210:213], v[92:95]
	v_mfma_f32_16x16x32_bf16 v[88:91], v[168:171], v[210:213], v[88:91]
	v_mfma_f32_16x16x32_bf16 v[76:79], v[160:163], v[218:221], v[76:79]
	v_mfma_f32_16x16x32_bf16 v[72:75], v[168:171], v[218:221], v[72:75]
	v_mfma_f32_16x16x32_bf16 v[116:119], v[172:175], v[190:193], v[116:119]
	v_mfma_f32_16x16x32_bf16 v[112:115], v[182:185], v[190:193], v[112:115]
	v_mfma_f32_16x16x32_bf16 v[100:103], v[172:175], v[198:201], v[100:103]
	v_mfma_f32_16x16x32_bf16 v[96:99], v[182:185], v[198:201], v[96:99]
	v_mfma_f32_16x16x32_bf16 v[84:87], v[172:175], v[206:209], v[84:87]
	v_mfma_f32_16x16x32_bf16 v[80:83], v[182:185], v[206:209], v[80:83]
	v_mfma_f32_16x16x32_bf16 v[68:71], v[172:175], v[214:217], v[68:71]
	v_mfma_f32_16x16x32_bf16 v[64:67], v[182:185], v[214:217], v[64:67]
	v_mfma_f32_16x16x32_bf16 v[116:119], v[176:179], v[194:197], v[116:119]
	v_mfma_f32_16x16x32_bf16 v[112:115], v[186:189], v[194:197], v[112:115]
	v_mfma_f32_16x16x32_bf16 v[100:103], v[176:179], v[202:205], v[100:103]
	v_mfma_f32_16x16x32_bf16 v[96:99], v[186:189], v[202:205], v[96:99]
	v_mfma_f32_16x16x32_bf16 v[84:87], v[176:179], v[210:213], v[84:87]
	v_mfma_f32_16x16x32_bf16 v[80:83], v[186:189], v[210:213], v[80:83]
	v_mfma_f32_16x16x32_bf16 v[68:71], v[176:179], v[218:221], v[68:71]
	v_mfma_f32_16x16x32_bf16 v[64:67], v[186:189], v[218:221], v[64:67]
	s_barrier
; #define PG8_STAGE(bufoff, gbase, voff) do { _Pragma("unroll") for (int _i = 0; _i < 2; ++_i) \
;         __builtin_amdgcn_global_load_lds((const unsigned*)((const char*)(gbase) + (voff)[_i]), (PG8_LAS unsigned*)(lds + (bufoff) + ldsw + _i * 8192), 16, 0, 0); } while (0)
; #define PG8_LDA(dst, b, h) do { _Pragma("unroll") for (int m = 0; m < 4; ++m) _Pragma("unroll") for (int k = 0; k < 2; ++k) dst[m][k] = *(const PG8_LAS bf16x8*)(lds + PG8_SA(b, h) + aoff + m * 2048 + k * 1024); } while (0)
; #define PG8_LDB(dst, b, h) do { _Pragma("unroll") for (int n = 0; n < 2; ++n) _Pragma("unroll") for (int k = 0; k < 2; ++k) dst[n][k] = *(const PG8_LAS bf16x8*)(lds + PG8_SB(b, h) + boff + n * 2048 + k * 1024); } while (0)
; #define PG8_MMA(ai, bj, At, Bt) do { __builtin_amdgcn_s_setprio(1); _Pragma("unroll") for (int m = 0; m < 4; ++m) _Pragma("unroll") for (int n = 0; n < 2; ++n) _Pragma("unroll") for (int k = 0; k < 2; ++k) \
;         acc[ai][bj][m][n] = __builtin_amdgcn_mfma_f32_16x16x32_bf16(Bt[n][k], At[m][k], acc[ai][bj][m][n], 0, 0, 0); __builtin_amdgcn_s_setprio(0); } while (0)
; #define PG8_WAIT_V(n) asm volatile("s_waitcnt vmcnt(" #n ")" ::: "memory")
; template <class Epi, class Sched, bool ALIGN_EPI = false, bool SP2 = false>
; __device__ __forceinline__ void gemm_phase(PG8_LAS unsigned char* lds, const Gemm g, const Sched& S, const Epi& E) {
;     ...
;             PG8_LDB(B0, 0, 0); PG8_LDB(B1, 0, 1); PG8_SCHED; PG8_LDA(At, 0, 0); PG8_STAGE(PG8_SA(1, 1), a1 + hstep, voffA);
;             PG8_WAIT_V(8); PG8_WAIT_L(0); PG8_BAR; PG8_MMA(0, 0, At, B0); PG8_MMA(0, 1, At, B1); PG8_BAR; PG8_SCHED;
;             PG8_LDA(At, 0, 1); PG8_STAGE(PG8_SB(0, 0), b2, voffB); PG8_STAGE(PG8_SB(0, 1), b2 + hstep, voffB); PG8_STAGE(PG8_SA(0, 0), a2, voffA);
;             PG8_WAIT_V(8); PG8_WAIT_L(0); PG8_BAR; PG8_MMA(1, 0, At, B0); PG8_MMA(1, 1, At, B1); PG8_BAR; PG8_SCHED;
;             PG8_LDB(B0, 1, 0); PG8_LDB(B1, 1, 1); PG8_SCHED; PG8_LDA(At, 1, 0); PG8_STAGE(PG8_SA(0, 1), a2 + hstep, voffA);
;             PG8_WAIT_V(8); PG8_WAIT_L(0); PG8_BAR; PG8_MMA(0, 0, At, B0); PG8_MMA(0, 1, At, B1); PG8_BAR; PG8_SCHED;
;             PG8_LDA(At, 1, 1); PG8_STAGE(PG8_SB(1, 0), b3, voffB); PG8_STAGE(PG8_SB(1, 1), b3 + hstep, voffB); PG8_STAGE(PG8_SA(1, 0), a3, voffA);
;             PG8_WAIT_V(8); PG8_WAIT_L(0); PG8_BAR; PG8_MMA(1, 0, At, B0); PG8_MMA(1, 1, At, B1); PG8_BAR; PG8_SCHED;
	s_add_i32 s42, s63, s45
	v_lshl_add_u64 v[144:145], v[144:145], 0, s[10:11]
	s_mov_b32 m0, s42
	ds_read_b128 v[190:193], v154 offset:49152
	ds_read_b128 v[194:197], v154 offset:50176
	ds_read_b128 v[198:201], v154 offset:51200
	ds_read_b128 v[202:205], v154 offset:52224
	ds_read_b128 v[206:209], v154 offset:53248
	ds_read_b128 v[210:213], v154 offset:54272
	ds_read_b128 v[214:217], v154 offset:55296
	ds_read_b128 v[218:221], v154 offset:56320
	global_load_lds_dwordx4 v[144:145], off
	s_add_i32 m0, s42, 0x2000
	s_add_u32 s40, s40, 0x40080
	v_lshl_add_u64 v[144:145], v[222:223], 0, s[10:11]
	s_addc_u32 s41, s41, 0
	s_add_i32 s42, s64, s45
	global_load_lds_dwordx4 v[144:145], off
	v_lshl_add_u64 v[144:145], s[40:41], 0, v[130:131]
	s_mov_b32 m0, s42
	s_nop 0
	global_load_lds_dwordx4 v[144:145], off
	v_lshl_add_u64 v[144:145], s[40:41], 0, v[134:135]
	s_add_i32 m0, s42, 0x2000
	s_nop 0
	global_load_lds_dwordx4 v[144:145], off
	v_lshl_add_u64 v[144:145], v[224:225], 0, s[10:11]
	s_mov_b32 m0, s50
	s_nop 0
	global_load_lds_dwordx4 v[144:145], off
	v_lshl_add_u64 v[144:145], v[226:227], 0, s[10:11]
	s_mov_b32 m0, s51
	s_nop 0
	global_load_lds_dwordx4 v[144:145], off
	s_waitcnt vmcnt(8)
	s_waitcnt lgkmcnt(0)
	s_barrier
	s_waitcnt lgkmcnt(0)
	v_mfma_f32_16x16x32_bf16 v[60:63], v[156:159], v[190:193], v[60:63]
	v_mfma_f32_16x16x32_bf16 v[56:59], v[164:167], v[190:193], v[56:59]
	v_mfma_f32_16x16x32_bf16 v[44:47], v[156:159], v[198:201], v[44:47]
	v_mfma_f32_16x16x32_bf16 v[40:43], v[164:167], v[198:201], v[40:43]
	v_mfma_f32_16x16x32_bf16 v[28:31], v[156:159], v[206:209], v[28:31]
	v_mfma_f32_16x16x32_bf16 v[24:27], v[164:167], v[206:209], v[24:27]
	v_mfma_f32_16x16x32_bf16 v[12:15], v[156:159], v[214:217], v[12:15]
	v_mfma_f32_16x16x32_bf16 v[8:11], v[164:167], v[214:217], v[8:11]
	v_mfma_f32_16x16x32_bf16 v[60:63], v[160:163], v[194:197], v[60:63]
	v_mfma_f32_16x16x32_bf16 v[56:59], v[168:171], v[194:197], v[56:59]
	v_mfma_f32_16x16x32_bf16 v[44:47], v[160:163], v[202:205], v[44:47]
	v_mfma_f32_16x16x32_bf16 v[40:43], v[168:171], v[202:205], v[40:43]
	v_mfma_f32_16x16x32_bf16 v[28:31], v[160:163], v[210:213], v[28:31]
	v_mfma_f32_16x16x32_bf16 v[24:27], v[168:171], v[210:213], v[24:27]
	v_mfma_f32_16x16x32_bf16 v[12:15], v[160:163], v[218:221], v[12:15]
	v_mfma_f32_16x16x32_bf16 v[8:11], v[168:171], v[218:221], v[8:11]
	v_mfma_f32_16x16x32_bf16 v[52:55], v[172:175], v[190:193], v[52:55]
	v_mfma_f32_16x16x32_bf16 v[48:51], v[182:185], v[190:193], v[48:51]
	v_mfma_f32_16x16x32_bf16 v[36:39], v[172:175], v[198:201], v[36:39]
	v_mfma_f32_16x16x32_bf16 v[32:35], v[182:185], v[198:201], v[32:35]
	v_mfma_f32_16x16x32_bf16 v[20:23], v[172:175], v[206:209], v[20:23]
	v_mfma_f32_16x16x32_bf16 v[16:19], v[182:185], v[206:209], v[16:19]
	v_mfma_f32_16x16x32_bf16 v[4:7], v[172:175], v[214:217], v[4:7]
	v_mfma_f32_16x16x32_bf16 v[0:3], v[182:185], v[214:217], v[0:3]
	v_mfma_f32_16x16x32_bf16 v[52:55], v[176:179], v[194:197], v[52:55]
	v_mfma_f32_16x16x32_bf16 v[48:51], v[186:189], v[194:197], v[48:51]
	v_mfma_f32_16x16x32_bf16 v[36:39], v[176:179], v[202:205], v[36:39]
	v_mfma_f32_16x16x32_bf16 v[32:35], v[186:189], v[202:205], v[32:35]
	v_mfma_f32_16x16x32_bf16 v[20:23], v[176:179], v[210:213], v[20:23]
	v_mfma_f32_16x16x32_bf16 v[16:19], v[186:189], v[210:213], v[16:19]
	v_mfma_f32_16x16x32_bf16 v[4:7], v[176:179], v[218:221], v[4:7]
	v_mfma_f32_16x16x32_bf16 v[0:3], v[186:189], v[218:221], v[0:3]
	s_barrier
	s_add_i32 s62, s62, 2
	s_add_u32 s26, s26, 0x100
	s_addc_u32 s27, s27, 0
	s_add_u32 s60, s60, 0x100
	s_addc_u32 s61, s61, 0
	s_cmp_gt_u32 s62, 13
	s_cbranch_scc0 .LBB0_2328
	s_and_b64 vcc, exec, s[12:13]
	s_cbranch_vccz .LBB0_2331
	s_barrier
